# GEMM K-loops: LDS read bases hoisted out of the K loop, duplicate lgkmcnt waits removed
# speedup vs baseline: 1.0248x; 1.0035x over previous
; #define PG8_STAGE(bufoff, gbase, voff) do { _Pragma("unroll") for (int _i = 0; _i < 2; ++_i) \
;     __builtin_amdgcn_global_load_lds((const unsigned*)((const char*)(gbase) + (voff)[_i]), (LAS unsigned*)(lds + (bufoff) + ldsw + _i * 8192), 16, 0, 0); } while (0)
; #define PG8_LDA(dst, b, h) do { _Pragma("unroll") for (int m = 0; m < 4; ++m) _Pragma("unroll") for (int k = 0; k < 2; ++k) dst[m][k] = *(const LAS bf16x8*)(lds + PG8_SA(b, h) + aoff + m * 2048 + k * 1024); } while (0)
; #define PG8_LDB(dst, b, h) do { _Pragma("unroll") for (int n = 0; n < 2; ++n) _Pragma("unroll") for (int k = 0; k < 2; ++k) dst[n][k] = *(const LAS bf16x8*)(lds + PG8_SB(b, h) + boff + n * 2048 + k * 1024); } while (0)
; #define PG8_WAIT_V(n) asm volatile("s_waitcnt vmcnt(" #n ")" ::: "memory")
; #define PG8_WAIT_L(n) asm volatile("s_waitcnt lgkmcnt(" #n ")" ::: "memory")
; #define PG8_BAR __builtin_amdgcn_s_barrier()
; #define PG8_SCHED __builtin_amdgcn_sched_barrier(0)
; template <class Epi, class Sched>
; DI void gemm_phase(LAS unsigned char* lds, const Gemm g, const Sched& S, const Epi& E) {
;     ...
;       PG8_LDB(B0, 0, 0); PG8_SCHED; PG8_LDA(At, 0, 0); PG8_STAGE(PG8_SA(1, 1), a1 + hstep, voffA);
;       PG8_WAIT_L(8); PG8_BAR; PG8_WAIT_L(0); PG8_MMA(0, 0, At, B0); PG8_BAR; PG8_SCHED;
;       PG8_LDB(B1, 0, 1); PG8_STAGE(PG8_SB(0, 0), b2, voffB);
;       PG8_BAR; PG8_WAIT_L(0); PG8_MMA(0, 1, At, B1); PG8_BAR;
;       PG8_LDA(At, 0, 1); PG8_STAGE(PG8_SA(0, 0), a2, voffA);
;       PG8_BAR; PG8_WAIT_L(0); PG8_MMA(1, 0, At, B0); PG8_BAR; PG8_SCHED;
;       PG8_STAGE(PG8_SB(0, 1), b2 + hstep, voffB);
;       PG8_WAIT_V(6); PG8_BAR; PG8_MMA(1, 1, At, B1); PG8_BAR;
;   DI void operator()(const f32x4 (&acc)[2][2][4][2], const pg8::Unit& u, int wr, int wc, int fr_, int fq_) const {
;     ...
;             } else if (EPI == EPI_CIN) {
;               if (n == 0) {
;                 const int gb = u.pn * 256 + bj * 128 + wc * 32;
;                 const int f8 = gb + 8 * fq;
;                 const f32x4 v1 = acc[ai][bj][m][1];
;                 if (gb < 1024) st_bf8((u16*)(big + O_QD) + (size_t)token * 1024 + f8, v, v1, rinv * (0.125f * LOG2E));
;                 else if (gb < 2048) st_bf8((u16*)(big + O_KD) + (size_t)token * 1024 + (f8 - 1024), v, v1, rinv);
;                 else st_bf8((u16*)(big + O_VDT) + (size_t)token * 1024 + (f8 - 2048), v, v1, rinv);
.LBB0_370:
	s_add_u32 s4, s2, 0xfffc0080
	s_addc_u32 s5, s3, -1
	s_add_i32 s51, 0, 0x10000
	ds_read_b128 v[128:131], v228
	ds_read_b128 v[146:149], v228 offset:1024
	ds_read_b128 v[150:153], v228 offset:2048
	ds_read_b128 v[160:163], v228 offset:3072
	s_cmp_eq_u32 s50, 12
	s_cselect_b32 s21, s15, s5
	s_cselect_b32 s20, s29, s4
	s_cselect_b32 s5, s13, s49
	s_cselect_b32 s4, s36, s37
	s_add_i32 m0, s40, 0xc000
	ds_read_b128 v[164:167], v158
	ds_read_b128 v[168:171], v158 offset:1024
	ds_read_b128 v[172:175], v158 offset:2048
	ds_read_b128 v[176:179], v158 offset:3072
	ds_read_b128 v[196:199], v158 offset:4096
	ds_read_b128 v[200:203], v158 offset:5120
	ds_read_b128 v[204:207], v158 offset:6144
	ds_read_b128 v[208:211], v158 offset:7168
	global_load_lds_dwordx4 v140, s[2:3]
	s_add_i32 m0, s40, 0xe000
	s_nop 0
	global_load_lds_dwordx4 v142, s[2:3]
	s_waitcnt lgkmcnt(8)
	s_barrier
	s_waitcnt lgkmcnt(0)
	v_mfma_f32_16x16x32_bf16 v[124:127], v[128:131], v[164:167], v[124:127]
	v_mfma_f32_16x16x32_bf16 v[120:123], v[150:153], v[164:167], v[120:123]
	v_mfma_f32_16x16x32_bf16 v[108:111], v[128:131], v[172:175], v[108:111]
	v_mfma_f32_16x16x32_bf16 v[104:107], v[150:153], v[172:175], v[104:107]
	v_mfma_f32_16x16x32_bf16 v[92:95], v[128:131], v[196:199], v[92:95]
	v_mfma_f32_16x16x32_bf16 v[88:91], v[150:153], v[196:199], v[88:91]
	v_mfma_f32_16x16x32_bf16 v[76:79], v[128:131], v[204:207], v[76:79]
	v_mfma_f32_16x16x32_bf16 v[72:75], v[150:153], v[204:207], v[72:75]
	v_mfma_f32_16x16x32_bf16 v[124:127], v[146:149], v[168:171], v[124:127]
	v_mfma_f32_16x16x32_bf16 v[120:123], v[160:163], v[168:171], v[120:123]
	v_mfma_f32_16x16x32_bf16 v[108:111], v[146:149], v[176:179], v[108:111]
	v_mfma_f32_16x16x32_bf16 v[104:107], v[160:163], v[176:179], v[104:107]
	v_mfma_f32_16x16x32_bf16 v[92:95], v[146:149], v[200:203], v[92:95]
	v_mfma_f32_16x16x32_bf16 v[88:91], v[160:163], v[200:203], v[88:91]
	v_mfma_f32_16x16x32_bf16 v[76:79], v[146:149], v[208:211], v[76:79]
	v_mfma_f32_16x16x32_bf16 v[72:75], v[160:163], v[208:211], v[72:75]
	s_barrier
	s_add_i32 s54, 0, 0x14000
	s_add_i32 s51, s51, s34
	s_add_u32 vcc_lo, s4, s0
	s_addc_u32 vcc_hi, s5, s1
	s_mov_b32 m0, s51
	ds_read_b128 v[212:215], v229
	ds_read_b128 v[216:219], v229 offset:1024
	ds_read_b128 v[220:223], v229 offset:2048
	ds_read_b128 v[224:227], v229 offset:3072
	global_load_lds_dwordx4 v136, s[4:5]
	s_add_i32 m0, s51, 0x2000
	s_nop 0
	global_load_lds_dwordx4 v132, s[4:5]
	s_barrier
	s_waitcnt lgkmcnt(0)
	v_mfma_f32_16x16x32_bf16 v[116:119], v[212:215], v[164:167], v[116:119]
	v_mfma_f32_16x16x32_bf16 v[112:115], v[220:223], v[164:167], v[112:115]
	v_mfma_f32_16x16x32_bf16 v[100:103], v[212:215], v[172:175], v[100:103]
	v_mfma_f32_16x16x32_bf16 v[96:99], v[220:223], v[172:175], v[96:99]
	v_mfma_f32_16x16x32_bf16 v[84:87], v[212:215], v[196:199], v[84:87]
	v_mfma_f32_16x16x32_bf16 v[80:83], v[220:223], v[196:199], v[80:83]
	v_mfma_f32_16x16x32_bf16 v[68:71], v[212:215], v[204:207], v[68:71]
	v_mfma_f32_16x16x32_bf16 v[64:67], v[220:223], v[204:207], v[64:67]
	v_mfma_f32_16x16x32_bf16 v[116:119], v[216:219], v[168:171], v[116:119]
	v_mfma_f32_16x16x32_bf16 v[112:115], v[224:227], v[168:171], v[112:115]
	v_mfma_f32_16x16x32_bf16 v[100:103], v[216:219], v[176:179], v[100:103]
	v_mfma_f32_16x16x32_bf16 v[96:99], v[224:227], v[176:179], v[96:99]
	v_mfma_f32_16x16x32_bf16 v[84:87], v[216:219], v[200:203], v[84:87]
	v_mfma_f32_16x16x32_bf16 v[80:83], v[224:227], v[200:203], v[80:83]
	v_mfma_f32_16x16x32_bf16 v[68:71], v[216:219], v[208:211], v[68:71]
	v_mfma_f32_16x16x32_bf16 v[64:67], v[224:227], v[208:211], v[64:67]
	s_mov_b32 m0, s40
	s_add_u32 s100, s20, s0
	s_addc_u32 s101, s21, s1
	s_barrier
	ds_read_b128 v[164:167], v158 offset:16384
	ds_read_b128 v[168:171], v158 offset:17408
	ds_read_b128 v[172:175], v158 offset:18432
	ds_read_b128 v[176:179], v158 offset:19456
	ds_read_b128 v[196:199], v158 offset:20480
	ds_read_b128 v[200:203], v158 offset:21504
	ds_read_b128 v[204:207], v158 offset:22528
	ds_read_b128 v[208:211], v158 offset:23552
	global_load_lds_dwordx4 v138, s[20:21]
	s_mov_b32 m0, s41
	s_nop 0
	global_load_lds_dwordx4 v134, s[20:21]
	s_barrier
	s_waitcnt lgkmcnt(0)
	v_mfma_f32_16x16x32_bf16 v[60:63], v[128:131], v[164:167], v[60:63]
	v_mfma_f32_16x16x32_bf16 v[56:59], v[150:153], v[164:167], v[56:59]
	v_mfma_f32_16x16x32_bf16 v[44:47], v[128:131], v[172:175], v[44:47]
	v_mfma_f32_16x16x32_bf16 v[40:43], v[150:153], v[172:175], v[40:43]
	v_mfma_f32_16x16x32_bf16 v[28:31], v[128:131], v[196:199], v[28:31]
	v_mfma_f32_16x16x32_bf16 v[24:27], v[150:153], v[196:199], v[24:27]
	v_mfma_f32_16x16x32_bf16 v[12:15], v[128:131], v[204:207], v[12:15]
	v_mfma_f32_16x16x32_bf16 v[8:11], v[150:153], v[204:207], v[8:11]
	v_mfma_f32_16x16x32_bf16 v[60:63], v[146:149], v[168:171], v[60:63]
	v_mfma_f32_16x16x32_bf16 v[56:59], v[160:163], v[168:171], v[56:59]
	v_mfma_f32_16x16x32_bf16 v[44:47], v[146:149], v[176:179], v[44:47]
	v_mfma_f32_16x16x32_bf16 v[40:43], v[160:163], v[176:179], v[40:43]
	v_mfma_f32_16x16x32_bf16 v[28:31], v[146:149], v[200:203], v[28:31]
	v_mfma_f32_16x16x32_bf16 v[24:27], v[160:163], v[200:203], v[24:27]
	v_mfma_f32_16x16x32_bf16 v[12:15], v[146:149], v[208:211], v[12:15]
	v_mfma_f32_16x16x32_bf16 v[8:11], v[160:163], v[208:211], v[8:11]
	s_barrier
	s_add_u32 s52, s4, 0x40000
	s_addc_u32 s53, s5, 0
	s_add_i32 s51, s54, s34
	s_mov_b32 m0, s51
	s_nop 0
	global_load_lds_dwordx4 v136, s[52:53]
	s_add_i32 m0, s51, 0x2000
	s_nop 0
	global_load_lds_dwordx4 v132, s[52:53]
	s_waitcnt vmcnt(6)
	s_barrier
; #define PG8_STAGE(bufoff, gbase, voff) do { _Pragma("unroll") for (int _i = 0; _i < 2; ++_i) \
;     __builtin_amdgcn_global_load_lds((const unsigned*)((const char*)(gbase) + (voff)[_i]), (LAS unsigned*)(lds + (bufoff) + ldsw + _i * 8192), 16, 0, 0); } while (0)
; #define PG8_LDA(dst, b, h) do { _Pragma("unroll") for (int m = 0; m < 4; ++m) _Pragma("unroll") for (int k = 0; k < 2; ++k) dst[m][k] = *(const LAS bf16x8*)(lds + PG8_SA(b, h) + aoff + m * 2048 + k * 1024); } while (0)
; #define PG8_LDB(dst, b, h) do { _Pragma("unroll") for (int n = 0; n < 2; ++n) _Pragma("unroll") for (int k = 0; k < 2; ++k) dst[n][k] = *(const LAS bf16x8*)(lds + PG8_SB(b, h) + boff + n * 2048 + k * 1024); } while (0)
; #define PG8_MMA(ai, bj, At, Bt) do { __builtin_amdgcn_s_setprio(1); _Pragma("unroll") for (int m = 0; m < 4; ++m) _Pragma("unroll") for (int n = 0; n < 2; ++n) _Pragma("unroll") for (int k = 0; k < 2; ++k) \
;     acc[ai][bj][m][n] = __builtin_amdgcn_mfma_f32_16x16x32_bf16(Bt[n][k], At[m][k], acc[ai][bj][m][n], 0, 0, 0); __builtin_amdgcn_s_setprio(0); } while (0)
; #define PG8_WAIT_V(n) asm volatile("s_waitcnt vmcnt(" #n ")" ::: "memory")
; #define PG8_WAIT_L(n) asm volatile("s_waitcnt lgkmcnt(" #n ")" ::: "memory")
; #define PG8_BAR __builtin_amdgcn_s_barrier()
; #define PG8_SCHED __builtin_amdgcn_sched_barrier(0)
; template <class Epi, class Sched>
; DI void gemm_phase(LAS unsigned char* lds, const Gemm g, const Sched& S, const Epi& E) {
;     ...
;       PG8_WAIT_V(6); PG8_BAR; PG8_MMA(1, 1, At, B1); PG8_BAR;
;       PG8_LDB(B0, 1, 0); PG8_SCHED; PG8_LDA(At, 1, 0); PG8_STAGE(PG8_SA(0, 1), a2 + hstep, voffA);
;       PG8_WAIT_L(8); PG8_BAR; PG8_WAIT_L(0); PG8_MMA(0, 0, At, B0); PG8_BAR; PG8_SCHED;
;       PG8_LDB(B1, 1, 1); PG8_STAGE(PG8_SB(1, 0), b3, voffB);
;       PG8_BAR; PG8_WAIT_L(0); PG8_MMA(0, 1, At, B1); PG8_BAR;
;       PG8_LDA(At, 1, 1); PG8_STAGE(PG8_SA(1, 0), a3, voffA);
;       PG8_BAR; PG8_WAIT_L(0); PG8_MMA(1, 0, At, B0); PG8_BAR; PG8_SCHED;
	v_mfma_f32_16x16x32_bf16 v[52:55], v[212:215], v[164:167], v[52:55]
	v_mfma_f32_16x16x32_bf16 v[48:51], v[220:223], v[164:167], v[48:51]
	v_mfma_f32_16x16x32_bf16 v[36:39], v[212:215], v[172:175], v[36:39]
	v_mfma_f32_16x16x32_bf16 v[32:35], v[220:223], v[172:175], v[32:35]
	v_mfma_f32_16x16x32_bf16 v[20:23], v[212:215], v[196:199], v[20:23]
	v_mfma_f32_16x16x32_bf16 v[16:19], v[220:223], v[196:199], v[16:19]
	v_mfma_f32_16x16x32_bf16 v[4:7], v[212:215], v[204:207], v[4:7]
	v_mfma_f32_16x16x32_bf16 v[0:3], v[220:223], v[204:207], v[0:3]
	v_mfma_f32_16x16x32_bf16 v[52:55], v[216:219], v[168:171], v[52:55]
	v_mfma_f32_16x16x32_bf16 v[48:51], v[224:227], v[168:171], v[48:51]
	v_mfma_f32_16x16x32_bf16 v[36:39], v[216:219], v[176:179], v[36:39]
	v_mfma_f32_16x16x32_bf16 v[32:35], v[224:227], v[176:179], v[32:35]
	v_mfma_f32_16x16x32_bf16 v[20:23], v[216:219], v[200:203], v[20:23]
	v_mfma_f32_16x16x32_bf16 v[16:19], v[224:227], v[200:203], v[16:19]
	v_mfma_f32_16x16x32_bf16 v[4:7], v[216:219], v[208:211], v[4:7]
	v_mfma_f32_16x16x32_bf16 v[0:3], v[224:227], v[208:211], v[0:3]
	s_add_i32 s51, 0, 0x18000
	s_barrier
	ds_read_b128 v[128:131], v230
	ds_read_b128 v[146:149], v230 offset:1024
	ds_read_b128 v[150:153], v230 offset:2048
	ds_read_b128 v[160:163], v230 offset:3072
	s_add_u32 s20, s20, 0x40000
	s_addc_u32 s21, s21, 0
	s_mov_b32 m0, s42
	ds_read_b128 v[164:167], v158 offset:32768
	ds_read_b128 v[168:171], v158 offset:33792
	ds_read_b128 v[172:175], v158 offset:34816
	ds_read_b128 v[176:179], v158 offset:35840
	ds_read_b128 v[196:199], v158 offset:36864
	ds_read_b128 v[200:203], v158 offset:37888
	ds_read_b128 v[204:207], v158 offset:38912
	ds_read_b128 v[208:211], v158 offset:39936
	global_load_lds_dwordx4 v138, s[20:21]
	s_mov_b32 m0, s43
	s_nop 0
	global_load_lds_dwordx4 v134, s[20:21]
	s_waitcnt lgkmcnt(8)
	s_barrier
	s_waitcnt lgkmcnt(0)
	v_mfma_f32_16x16x32_bf16 v[124:127], v[128:131], v[164:167], v[124:127]
	v_mfma_f32_16x16x32_bf16 v[120:123], v[150:153], v[164:167], v[120:123]
	v_mfma_f32_16x16x32_bf16 v[108:111], v[128:131], v[172:175], v[108:111]
	v_mfma_f32_16x16x32_bf16 v[104:107], v[150:153], v[172:175], v[104:107]
	v_mfma_f32_16x16x32_bf16 v[92:95], v[128:131], v[196:199], v[92:95]
	v_mfma_f32_16x16x32_bf16 v[88:91], v[150:153], v[196:199], v[88:91]
	v_mfma_f32_16x16x32_bf16 v[76:79], v[128:131], v[204:207], v[76:79]
	v_mfma_f32_16x16x32_bf16 v[72:75], v[150:153], v[204:207], v[72:75]
	v_mfma_f32_16x16x32_bf16 v[124:127], v[146:149], v[168:171], v[124:127]
	v_mfma_f32_16x16x32_bf16 v[120:123], v[160:163], v[168:171], v[120:123]
	v_mfma_f32_16x16x32_bf16 v[108:111], v[146:149], v[176:179], v[108:111]
	v_mfma_f32_16x16x32_bf16 v[104:107], v[160:163], v[176:179], v[104:107]
	v_mfma_f32_16x16x32_bf16 v[92:95], v[146:149], v[200:203], v[92:95]
	v_mfma_f32_16x16x32_bf16 v[88:91], v[160:163], v[200:203], v[88:91]
	v_mfma_f32_16x16x32_bf16 v[76:79], v[146:149], v[208:211], v[76:79]
	v_mfma_f32_16x16x32_bf16 v[72:75], v[160:163], v[208:211], v[72:75]
	s_barrier
	s_add_i32 s20, 0, 0x1c000
	s_add_i32 s21, s51, s34
	s_mov_b32 m0, s21
	ds_read_b128 v[212:215], v231
	ds_read_b128 v[216:219], v231 offset:1024
	ds_read_b128 v[220:223], v231 offset:2048
	ds_read_b128 v[224:227], v231 offset:3072
	global_load_lds_dwordx4 v136, vcc
	s_add_i32 m0, s21, 0x2000
	s_nop 0
	global_load_lds_dwordx4 v132, vcc
	s_barrier
	s_waitcnt lgkmcnt(0)
	v_mfma_f32_16x16x32_bf16 v[116:119], v[212:215], v[164:167], v[116:119]
	v_mfma_f32_16x16x32_bf16 v[112:115], v[220:223], v[164:167], v[112:115]
	v_mfma_f32_16x16x32_bf16 v[100:103], v[212:215], v[172:175], v[100:103]
	v_mfma_f32_16x16x32_bf16 v[96:99], v[220:223], v[172:175], v[96:99]
	v_mfma_f32_16x16x32_bf16 v[84:87], v[212:215], v[196:199], v[84:87]
	v_mfma_f32_16x16x32_bf16 v[80:83], v[220:223], v[196:199], v[80:83]
	v_mfma_f32_16x16x32_bf16 v[68:71], v[212:215], v[204:207], v[68:71]
	v_mfma_f32_16x16x32_bf16 v[64:67], v[220:223], v[204:207], v[64:67]
	v_mfma_f32_16x16x32_bf16 v[116:119], v[216:219], v[168:171], v[116:119]
	v_mfma_f32_16x16x32_bf16 v[112:115], v[224:227], v[168:171], v[112:115]
	v_mfma_f32_16x16x32_bf16 v[100:103], v[216:219], v[176:179], v[100:103]
	v_mfma_f32_16x16x32_bf16 v[96:99], v[224:227], v[176:179], v[96:99]
	v_mfma_f32_16x16x32_bf16 v[84:87], v[216:219], v[200:203], v[84:87]
	v_mfma_f32_16x16x32_bf16 v[80:83], v[224:227], v[200:203], v[80:83]
	v_mfma_f32_16x16x32_bf16 v[68:71], v[216:219], v[208:211], v[68:71]
	v_mfma_f32_16x16x32_bf16 v[64:67], v[224:227], v[208:211], v[64:67]
	s_mov_b32 m0, s46
	s_barrier
; #define PG8_STAGE(bufoff, gbase, voff) do { _Pragma("unroll") for (int _i = 0; _i < 2; ++_i) \
;     __builtin_amdgcn_global_load_lds((const unsigned*)((const char*)(gbase) + (voff)[_i]), (LAS unsigned*)(lds + (bufoff) + ldsw + _i * 8192), 16, 0, 0); } while (0)
; #define PG8_LDA(dst, b, h) do { _Pragma("unroll") for (int m = 0; m < 4; ++m) _Pragma("unroll") for (int k = 0; k < 2; ++k) dst[m][k] = *(const LAS bf16x8*)(lds + PG8_SA(b, h) + aoff + m * 2048 + k * 1024); } while (0)
; #define PG8_MMA(ai, bj, At, Bt) do { __builtin_amdgcn_s_setprio(1); _Pragma("unroll") for (int m = 0; m < 4; ++m) _Pragma("unroll") for (int n = 0; n < 2; ++n) _Pragma("unroll") for (int k = 0; k < 2; ++k) \
;     acc[ai][bj][m][n] = __builtin_amdgcn_mfma_f32_16x16x32_bf16(Bt[n][k], At[m][k], acc[ai][bj][m][n], 0, 0, 0); __builtin_amdgcn_s_setprio(0); } while (0)
; #define PG8_WAIT_V(n) asm volatile("s_waitcnt vmcnt(" #n ")" ::: "memory")
; #define PG8_WAIT_L(n) asm volatile("s_waitcnt lgkmcnt(" #n ")" ::: "memory")
; #define PG8_BAR __builtin_amdgcn_s_barrier()
; #define PG8_SCHED __builtin_amdgcn_sched_barrier(0)
; template <class Epi, class Sched>
; DI void gemm_phase(LAS unsigned char* lds, const Gemm g, const Sched& S, const Epi& E) {
;     ...
;       PG8_LDA(At, 1, 1); PG8_STAGE(PG8_SA(1, 0), a3, voffA);
;       PG8_BAR; PG8_WAIT_L(0); PG8_MMA(1, 0, At, B0); PG8_BAR; PG8_SCHED;
;       PG8_STAGE(PG8_SB(1, 1), b3 + hstep, voffB);
;       PG8_WAIT_V(6); PG8_BAR; PG8_MMA(1, 1, At, B1); PG8_BAR;
;     }
;   DI void operator()(const f32x4 (&acc)[2][2][4][2], const pg8::Unit& u, int wr, int wc, int fr_, int fq_) const {
;     ...
;             } else if (EPI == EPI_CIN) {
;               if (n == 0) {
;                 const int gb = u.pn * 256 + bj * 128 + wc * 32;
;                 const int f8 = gb + 8 * fq;
;                 const f32x4 v1 = acc[ai][bj][m][1];
;                 if (gb < 1024) st_bf8((u16*)(big + O_QD) + (size_t)token * 1024 + f8, v, v1, rinv * (0.125f * LOG2E));
;                 else if (gb < 2048) st_bf8((u16*)(big + O_KD) + (size_t)token * 1024 + (f8 - 1024), v, v1, rinv);
;                 else st_bf8((u16*)(big + O_VDT) + (size_t)token * 1024 + (f8 - 2048), v, v1, rinv);
	ds_read_b128 v[164:167], v158 offset:49152
	ds_read_b128 v[168:171], v158 offset:50176
	ds_read_b128 v[172:175], v158 offset:51200
	ds_read_b128 v[176:179], v158 offset:52224
	ds_read_b128 v[196:199], v158 offset:53248
	ds_read_b128 v[200:203], v158 offset:54272
	ds_read_b128 v[204:207], v158 offset:55296
	ds_read_b128 v[208:211], v158 offset:56320
	global_load_lds_dwordx4 v138, s[100:101]
	s_mov_b32 m0, s47
	s_nop 0
	global_load_lds_dwordx4 v134, s[100:101]
	s_barrier
	s_waitcnt lgkmcnt(0)
	v_mfma_f32_16x16x32_bf16 v[60:63], v[128:131], v[164:167], v[60:63]
	v_mfma_f32_16x16x32_bf16 v[56:59], v[150:153], v[164:167], v[56:59]
	v_mfma_f32_16x16x32_bf16 v[44:47], v[128:131], v[172:175], v[44:47]
	v_mfma_f32_16x16x32_bf16 v[40:43], v[150:153], v[172:175], v[40:43]
	v_mfma_f32_16x16x32_bf16 v[28:31], v[128:131], v[196:199], v[28:31]
	v_mfma_f32_16x16x32_bf16 v[24:27], v[150:153], v[196:199], v[24:27]
	v_mfma_f32_16x16x32_bf16 v[12:15], v[128:131], v[204:207], v[12:15]
	v_mfma_f32_16x16x32_bf16 v[8:11], v[150:153], v[204:207], v[8:11]
	v_mfma_f32_16x16x32_bf16 v[60:63], v[146:149], v[168:171], v[60:63]
	v_mfma_f32_16x16x32_bf16 v[56:59], v[160:163], v[168:171], v[56:59]
	v_mfma_f32_16x16x32_bf16 v[44:47], v[146:149], v[176:179], v[44:47]
	v_mfma_f32_16x16x32_bf16 v[40:43], v[160:163], v[176:179], v[40:43]
	v_mfma_f32_16x16x32_bf16 v[28:31], v[146:149], v[200:203], v[28:31]
	v_mfma_f32_16x16x32_bf16 v[24:27], v[160:163], v[200:203], v[24:27]
	v_mfma_f32_16x16x32_bf16 v[12:15], v[146:149], v[208:211], v[12:15]
	v_mfma_f32_16x16x32_bf16 v[8:11], v[160:163], v[208:211], v[8:11]
	s_barrier
	s_add_u32 s4, s4, 0x40080
	s_addc_u32 s5, s5, 0
	s_add_i32 s20, s20, s34
	s_mov_b32 m0, s20
	s_nop 0
	global_load_lds_dwordx4 v136, s[4:5]
	s_add_i32 m0, s20, 0x2000
	s_nop 0
	global_load_lds_dwordx4 v132, s[4:5]
	s_waitcnt vmcnt(6)
	s_barrier
	v_mfma_f32_16x16x32_bf16 v[52:55], v[212:215], v[164:167], v[52:55]
	v_mfma_f32_16x16x32_bf16 v[48:51], v[220:223], v[164:167], v[48:51]
	v_mfma_f32_16x16x32_bf16 v[36:39], v[212:215], v[172:175], v[36:39]
	v_mfma_f32_16x16x32_bf16 v[32:35], v[220:223], v[172:175], v[32:35]
	v_mfma_f32_16x16x32_bf16 v[20:23], v[212:215], v[196:199], v[20:23]
	v_mfma_f32_16x16x32_bf16 v[16:19], v[220:223], v[196:199], v[16:19]
	v_mfma_f32_16x16x32_bf16 v[4:7], v[212:215], v[204:207], v[4:7]
	v_mfma_f32_16x16x32_bf16 v[0:3], v[220:223], v[204:207], v[0:3]
	v_mfma_f32_16x16x32_bf16 v[52:55], v[216:219], v[168:171], v[52:55]
	v_mfma_f32_16x16x32_bf16 v[48:51], v[224:227], v[168:171], v[48:51]
	v_mfma_f32_16x16x32_bf16 v[36:39], v[216:219], v[176:179], v[36:39]
	v_mfma_f32_16x16x32_bf16 v[32:35], v[224:227], v[176:179], v[32:35]
	v_mfma_f32_16x16x32_bf16 v[20:23], v[216:219], v[200:203], v[20:23]
	v_mfma_f32_16x16x32_bf16 v[16:19], v[224:227], v[200:203], v[16:19]
	v_mfma_f32_16x16x32_bf16 v[4:7], v[216:219], v[208:211], v[4:7]
	v_mfma_f32_16x16x32_bf16 v[0:3], v[224:227], v[208:211], v[0:3]
	s_add_i32 s50, s50, 2
	s_add_u32 s2, s2, 0x100
	s_addc_u32 s3, s3, 0
	s_add_u32 s37, s37, 0x100
	s_addc_u32 s49, s49, 0
	s_cmp_gt_u32 s50, 13
	s_barrier
	s_cbranch_scc0 .LBB0_370
	v_mov_b32_e32 v128, v182
	s_lshl_b32 s2, s22, 10
	v_and_or_b32 v160, v128, 15, s44
	v_lshrrev_b32_e32 v128, 1, v128
	s_add_i32 s2, s2, 0
	v_and_b32_e32 v146, 24, v128
	v_lshl_add_u32 v128, v160, 2, s2
	v_add_u32_e32 v159, 0x20000, v128
	s_lshl_b32 s13, s28, 8
	s_lshl_b32 s3, s23, 8
	ds_read_b32 v154, v159
	v_add_u32_e32 v150, s13, v160
	s_or_b32 s20, s3, s45
	v_ashrrev_i32_e32 v151, 31, v150
	s_cmpk_gt_i32 s20, 0x3ff
	v_lshlrev_b64 v[128:129], 11, v[150:151]
	v_or_b32_e32 v148, s20, v146
	s_cselect_b64 s[4:5], -1, 0
	s_cmpk_gt_u32 s3, 0x7ff
	s_cselect_b64 s[2:3], -1, 0
	v_mov_b32_e32 v144, v148
	v_lshl_add_u64 v[152:153], s[10:11], 0, v[128:129]
	s_mov_b64 s[22:23], -1
	s_and_b64 vcc, exec, s[4:5]
	s_cbranch_vccz .LBB0_377
	s_waitcnt lgkmcnt(0)
	v_pk_mul_f32 v[128:129], v[124:125], v[154:155] op_sel_hi:[1,0]
	v_pk_mul_f32 v[130:131], v[126:127], v[154:155] op_sel_hi:[1,0]
	v_cvt_pk_bf16_f32 v128, v128, v129
	v_cvt_pk_bf16_f32 v129, v130, v131
	v_pk_mul_f32 v[130:131], v[120:121], v[154:155] op_sel_hi:[1,0]
	v_pk_mul_f32 v[162:163], v[122:123], v[154:155] op_sel_hi:[1,0]
	v_lshl_add_u64 v[156:157], v[144:145], 1, v[152:153]
	v_cvt_pk_bf16_f32 v130, v130, v131
	v_cvt_pk_bf16_f32 v131, v162, v163
	s_and_b64 vcc, exec, s[2:3]
	s_cbranch_vccz .LBB0_374
	v_add_co_u32_e32 v162, vcc, 0x7fff000, v156
	s_mov_b64 s[22:23], 0
	s_nop 0
	v_addc_co_u32_e32 v163, vcc, 0, v157, vcc
	global_store_dwordx4 v[162:163], v[128:131], off

; #define PG8_STAGE(bufoff, gbase, voff) do { _Pragma("unroll") for (int _i = 0; _i < 2; ++_i) \
;     __builtin_amdgcn_global_load_lds((const unsigned*)((const char*)(gbase) + (voff)[_i]), (LAS unsigned*)(lds + (bufoff) + ldsw + _i * 8192), 16, 0, 0); } while (0)
; #define PG8_LDA(dst, b, h) do { _Pragma("unroll") for (int m = 0; m < 4; ++m) _Pragma("unroll") for (int k = 0; k < 2; ++k) dst[m][k] = *(const LAS bf16x8*)(lds + PG8_SA(b, h) + aoff + m * 2048 + k * 1024); } while (0)
; #define PG8_LDB(dst, b, h) do { _Pragma("unroll") for (int n = 0; n < 2; ++n) _Pragma("unroll") for (int k = 0; k < 2; ++k) dst[n][k] = *(const LAS bf16x8*)(lds + PG8_SB(b, h) + boff + n * 2048 + k * 1024); } while (0)
; #define PG8_MMA(ai, bj, At, Bt) do { __builtin_amdgcn_s_setprio(1); _Pragma("unroll") for (int m = 0; m < 4; ++m) _Pragma("unroll") for (int n = 0; n < 2; ++n) _Pragma("unroll") for (int k = 0; k < 2; ++k) \
;     acc[ai][bj][m][n] = __builtin_amdgcn_mfma_f32_16x16x32_bf16(Bt[n][k], At[m][k], acc[ai][bj][m][n], 0, 0, 0); __builtin_amdgcn_s_setprio(0); } while (0)
; #define PG8_WAIT_V(n) asm volatile("s_waitcnt vmcnt(" #n ")" ::: "memory")
; #define PG8_WAIT_L(n) asm volatile("s_waitcnt lgkmcnt(" #n ")" ::: "memory")
; #define PG8_BAR __builtin_amdgcn_s_barrier()
; #define PG8_SCHED __builtin_amdgcn_sched_barrier(0)
; template <class Epi, class Sched>
; DI void gemm_phase(LAS unsigned char* lds, const Gemm g, const Sched& S, const Epi& E) {
;     ...
;       PG8_LDB(B0, 0, 0); PG8_SCHED; PG8_LDA(At, 0, 0); PG8_STAGE(PG8_SA(1, 1), a1 + hstep, voffA);
;       PG8_WAIT_L(8); PG8_BAR; PG8_WAIT_L(0); PG8_MMA(0, 0, At, B0); PG8_BAR; PG8_SCHED;
;       PG8_LDB(B1, 0, 1); PG8_STAGE(PG8_SB(0, 0), b2, voffB);
;       PG8_BAR; PG8_WAIT_L(0); PG8_MMA(0, 1, At, B1); PG8_BAR;
;       PG8_LDA(At, 0, 1); PG8_STAGE(PG8_SA(0, 0), a2, voffA);
;       PG8_BAR; PG8_WAIT_L(0); PG8_MMA(1, 0, At, B0); PG8_BAR; PG8_SCHED;
;       PG8_STAGE(PG8_SB(0, 1), b2 + hstep, voffB);
;       PG8_WAIT_V(6); PG8_BAR; PG8_MMA(1, 1, At, B1); PG8_BAR;
.LBB0_689:
	s_add_u32 s22, s20, 0xfffc0080
	s_addc_u32 s23, s21, -1
	s_add_i32 s42, 0, 0x10000
	ds_read_b128 v[128:131], v222
	ds_read_b128 v[132:135], v222 offset:1024
	ds_read_b128 v[150:153], v222 offset:2048
	ds_read_b128 v[154:157], v222 offset:3072
	s_cmp_eq_u32 s41, 12
	s_cselect_b32 s29, s13, s23
	s_cselect_b32 s28, s37, s22
	s_cselect_b32 s23, s15, s40
	s_cselect_b32 s22, s38, s39
	s_add_i32 m0, s56, 0xc000
	ds_read_b128 v[158:161], v197
	ds_read_b128 v[162:165], v197 offset:1024
	ds_read_b128 v[166:169], v197 offset:2048
	ds_read_b128 v[170:173], v197 offset:3072
	ds_read_b128 v[174:177], v197 offset:4096
	ds_read_b128 v[178:181], v197 offset:5120
	ds_read_b128 v[198:201], v197 offset:6144
	ds_read_b128 v[202:205], v197 offset:7168
	global_load_lds_dwordx4 v146, s[20:21]
	s_add_i32 m0, s56, 0xe000
	s_nop 0
	global_load_lds_dwordx4 v148, s[20:21]
	s_waitcnt lgkmcnt(8)
	s_barrier
	s_waitcnt lgkmcnt(0)
	v_mfma_f32_16x16x32_bf16 v[124:127], v[128:131], v[158:161], v[124:127]
	v_mfma_f32_16x16x32_bf16 v[120:123], v[150:153], v[158:161], v[120:123]
	v_mfma_f32_16x16x32_bf16 v[108:111], v[128:131], v[166:169], v[108:111]
	v_mfma_f32_16x16x32_bf16 v[104:107], v[150:153], v[166:169], v[104:107]
	v_mfma_f32_16x16x32_bf16 v[92:95], v[128:131], v[174:177], v[92:95]
	v_mfma_f32_16x16x32_bf16 v[88:91], v[150:153], v[174:177], v[88:91]
	v_mfma_f32_16x16x32_bf16 v[76:79], v[128:131], v[198:201], v[76:79]
	v_mfma_f32_16x16x32_bf16 v[72:75], v[150:153], v[198:201], v[72:75]
	v_mfma_f32_16x16x32_bf16 v[124:127], v[132:135], v[162:165], v[124:127]
	v_mfma_f32_16x16x32_bf16 v[120:123], v[154:157], v[162:165], v[120:123]
	v_mfma_f32_16x16x32_bf16 v[108:111], v[132:135], v[170:173], v[108:111]
	v_mfma_f32_16x16x32_bf16 v[104:107], v[154:157], v[170:173], v[104:107]
	v_mfma_f32_16x16x32_bf16 v[92:95], v[132:135], v[178:181], v[92:95]
	v_mfma_f32_16x16x32_bf16 v[88:91], v[154:157], v[178:181], v[88:91]
	v_mfma_f32_16x16x32_bf16 v[76:79], v[132:135], v[202:205], v[76:79]
	v_mfma_f32_16x16x32_bf16 v[72:75], v[154:157], v[202:205], v[72:75]
	s_barrier
	s_add_i32 s44, 0, 0x14000
	s_add_i32 s42, s42, s52
	s_add_u32 vcc_lo, s22, s0
	s_addc_u32 vcc_hi, s23, s1
	s_mov_b32 m0, s42
	ds_read_b128 v[206:209], v223
	ds_read_b128 v[210:213], v223 offset:1024
	ds_read_b128 v[214:217], v223 offset:2048
	ds_read_b128 v[218:221], v223 offset:3072
	global_load_lds_dwordx4 v140, s[22:23]
	s_add_i32 m0, s42, 0x2000
	s_nop 0
	global_load_lds_dwordx4 v136, s[22:23]
	s_barrier
	s_waitcnt lgkmcnt(0)
	v_mfma_f32_16x16x32_bf16 v[116:119], v[206:209], v[158:161], v[116:119]
	v_mfma_f32_16x16x32_bf16 v[112:115], v[214:217], v[158:161], v[112:115]
	v_mfma_f32_16x16x32_bf16 v[100:103], v[206:209], v[166:169], v[100:103]
	v_mfma_f32_16x16x32_bf16 v[96:99], v[214:217], v[166:169], v[96:99]
	v_mfma_f32_16x16x32_bf16 v[84:87], v[206:209], v[174:177], v[84:87]
	v_mfma_f32_16x16x32_bf16 v[80:83], v[214:217], v[174:177], v[80:83]
	v_mfma_f32_16x16x32_bf16 v[68:71], v[206:209], v[198:201], v[68:71]
	v_mfma_f32_16x16x32_bf16 v[64:67], v[214:217], v[198:201], v[64:67]
	v_mfma_f32_16x16x32_bf16 v[116:119], v[210:213], v[162:165], v[116:119]
	v_mfma_f32_16x16x32_bf16 v[112:115], v[218:221], v[162:165], v[112:115]
	v_mfma_f32_16x16x32_bf16 v[100:103], v[210:213], v[170:173], v[100:103]
	v_mfma_f32_16x16x32_bf16 v[96:99], v[218:221], v[170:173], v[96:99]
	v_mfma_f32_16x16x32_bf16 v[84:87], v[210:213], v[178:181], v[84:87]
	v_mfma_f32_16x16x32_bf16 v[80:83], v[218:221], v[178:181], v[80:83]
	v_mfma_f32_16x16x32_bf16 v[68:71], v[210:213], v[202:205], v[68:71]
	v_mfma_f32_16x16x32_bf16 v[64:67], v[218:221], v[202:205], v[64:67]
	s_mov_b32 m0, s56
	s_add_u32 s100, s28, s0
	s_addc_u32 s101, s29, s1
	s_barrier
	ds_read_b128 v[158:161], v197 offset:16384
	ds_read_b128 v[162:165], v197 offset:17408
	ds_read_b128 v[166:169], v197 offset:18432
	ds_read_b128 v[170:173], v197 offset:19456
	ds_read_b128 v[174:177], v197 offset:20480
	ds_read_b128 v[178:181], v197 offset:21504
	ds_read_b128 v[198:201], v197 offset:22528
	ds_read_b128 v[202:205], v197 offset:23552
	global_load_lds_dwordx4 v142, s[28:29]
	s_mov_b32 m0, s57
	s_nop 0
	global_load_lds_dwordx4 v138, s[28:29]
	s_barrier
	s_waitcnt lgkmcnt(0)
	v_mfma_f32_16x16x32_bf16 v[60:63], v[128:131], v[158:161], v[60:63]
	v_mfma_f32_16x16x32_bf16 v[56:59], v[150:153], v[158:161], v[56:59]
	v_mfma_f32_16x16x32_bf16 v[44:47], v[128:131], v[166:169], v[44:47]
	v_mfma_f32_16x16x32_bf16 v[40:43], v[150:153], v[166:169], v[40:43]
	v_mfma_f32_16x16x32_bf16 v[28:31], v[128:131], v[174:177], v[28:31]
	v_mfma_f32_16x16x32_bf16 v[24:27], v[150:153], v[174:177], v[24:27]
	v_mfma_f32_16x16x32_bf16 v[12:15], v[128:131], v[198:201], v[12:15]
	v_mfma_f32_16x16x32_bf16 v[8:11], v[150:153], v[198:201], v[8:11]
	v_mfma_f32_16x16x32_bf16 v[60:63], v[132:135], v[162:165], v[60:63]
	v_mfma_f32_16x16x32_bf16 v[56:59], v[154:157], v[162:165], v[56:59]
	v_mfma_f32_16x16x32_bf16 v[44:47], v[132:135], v[170:173], v[44:47]
	v_mfma_f32_16x16x32_bf16 v[40:43], v[154:157], v[170:173], v[40:43]
	v_mfma_f32_16x16x32_bf16 v[28:31], v[132:135], v[178:181], v[28:31]
	v_mfma_f32_16x16x32_bf16 v[24:27], v[154:157], v[178:181], v[24:27]
	v_mfma_f32_16x16x32_bf16 v[12:15], v[132:135], v[202:205], v[12:15]
	v_mfma_f32_16x16x32_bf16 v[8:11], v[154:157], v[202:205], v[8:11]
	s_barrier
	s_add_u32 s42, s22, 0x40000
	s_addc_u32 s43, s23, 0
	s_add_i32 s44, s44, s52
	s_mov_b32 m0, s44
	s_nop 0
	global_load_lds_dwordx4 v140, s[42:43]
	s_add_i32 m0, s44, 0x2000
	s_nop 0
	global_load_lds_dwordx4 v136, s[42:43]
	s_waitcnt vmcnt(6)
	s_barrier
; #define PG8_STAGE(bufoff, gbase, voff) do { _Pragma("unroll") for (int _i = 0; _i < 2; ++_i) \
;     __builtin_amdgcn_global_load_lds((const unsigned*)((const char*)(gbase) + (voff)[_i]), (LAS unsigned*)(lds + (bufoff) + ldsw + _i * 8192), 16, 0, 0); } while (0)
; #define PG8_LDA(dst, b, h) do { _Pragma("unroll") for (int m = 0; m < 4; ++m) _Pragma("unroll") for (int k = 0; k < 2; ++k) dst[m][k] = *(const LAS bf16x8*)(lds + PG8_SA(b, h) + aoff + m * 2048 + k * 1024); } while (0)
; #define PG8_LDB(dst, b, h) do { _Pragma("unroll") for (int n = 0; n < 2; ++n) _Pragma("unroll") for (int k = 0; k < 2; ++k) dst[n][k] = *(const LAS bf16x8*)(lds + PG8_SB(b, h) + boff + n * 2048 + k * 1024); } while (0)
; #define PG8_MMA(ai, bj, At, Bt) do { __builtin_amdgcn_s_setprio(1); _Pragma("unroll") for (int m = 0; m < 4; ++m) _Pragma("unroll") for (int n = 0; n < 2; ++n) _Pragma("unroll") for (int k = 0; k < 2; ++k) \
;     acc[ai][bj][m][n] = __builtin_amdgcn_mfma_f32_16x16x32_bf16(Bt[n][k], At[m][k], acc[ai][bj][m][n], 0, 0, 0); __builtin_amdgcn_s_setprio(0); } while (0)
; #define PG8_WAIT_V(n) asm volatile("s_waitcnt vmcnt(" #n ")" ::: "memory")
; #define PG8_WAIT_L(n) asm volatile("s_waitcnt lgkmcnt(" #n ")" ::: "memory")
; #define PG8_BAR __builtin_amdgcn_s_barrier()
; #define PG8_SCHED __builtin_amdgcn_sched_barrier(0)
; template <class Epi, class Sched>
; DI void gemm_phase(LAS unsigned char* lds, const Gemm g, const Sched& S, const Epi& E) {
;     ...
;       PG8_WAIT_V(6); PG8_BAR; PG8_MMA(1, 1, At, B1); PG8_BAR;
;       PG8_LDB(B0, 1, 0); PG8_SCHED; PG8_LDA(At, 1, 0); PG8_STAGE(PG8_SA(0, 1), a2 + hstep, voffA);
;       PG8_WAIT_L(8); PG8_BAR; PG8_WAIT_L(0); PG8_MMA(0, 0, At, B0); PG8_BAR; PG8_SCHED;
;       PG8_LDB(B1, 1, 1); PG8_STAGE(PG8_SB(1, 0), b3, voffB);
;       PG8_BAR; PG8_WAIT_L(0); PG8_MMA(0, 1, At, B1); PG8_BAR;
;       PG8_LDA(At, 1, 1); PG8_STAGE(PG8_SA(1, 0), a3, voffA);
;       PG8_BAR; PG8_WAIT_L(0); PG8_MMA(1, 0, At, B0); PG8_BAR; PG8_SCHED;
	v_mfma_f32_16x16x32_bf16 v[52:55], v[206:209], v[158:161], v[52:55]
	v_mfma_f32_16x16x32_bf16 v[48:51], v[214:217], v[158:161], v[48:51]
	v_mfma_f32_16x16x32_bf16 v[36:39], v[206:209], v[166:169], v[36:39]
	v_mfma_f32_16x16x32_bf16 v[32:35], v[214:217], v[166:169], v[32:35]
	v_mfma_f32_16x16x32_bf16 v[20:23], v[206:209], v[174:177], v[20:23]
	v_mfma_f32_16x16x32_bf16 v[16:19], v[214:217], v[174:177], v[16:19]
	v_mfma_f32_16x16x32_bf16 v[4:7], v[206:209], v[198:201], v[4:7]
	v_mfma_f32_16x16x32_bf16 v[0:3], v[214:217], v[198:201], v[0:3]
	v_mfma_f32_16x16x32_bf16 v[52:55], v[210:213], v[162:165], v[52:55]
	v_mfma_f32_16x16x32_bf16 v[48:51], v[218:221], v[162:165], v[48:51]
	v_mfma_f32_16x16x32_bf16 v[36:39], v[210:213], v[170:173], v[36:39]
	v_mfma_f32_16x16x32_bf16 v[32:35], v[218:221], v[170:173], v[32:35]
	v_mfma_f32_16x16x32_bf16 v[20:23], v[210:213], v[178:181], v[20:23]
	v_mfma_f32_16x16x32_bf16 v[16:19], v[218:221], v[178:181], v[16:19]
	v_mfma_f32_16x16x32_bf16 v[4:7], v[210:213], v[202:205], v[4:7]
	v_mfma_f32_16x16x32_bf16 v[0:3], v[218:221], v[202:205], v[0:3]
	s_add_i32 s42, 0, 0x18000
	s_barrier
	ds_read_b128 v[128:131], v224
	ds_read_b128 v[132:135], v224 offset:1024
	ds_read_b128 v[150:153], v224 offset:2048
	ds_read_b128 v[154:157], v224 offset:3072
	s_add_u32 s28, s28, 0x40000
	s_addc_u32 s29, s29, 0
	s_mov_b32 m0, s58
	ds_read_b128 v[158:161], v197 offset:32768
	ds_read_b128 v[162:165], v197 offset:33792
	ds_read_b128 v[166:169], v197 offset:34816
	ds_read_b128 v[170:173], v197 offset:35840
	ds_read_b128 v[174:177], v197 offset:36864
	ds_read_b128 v[178:181], v197 offset:37888
	ds_read_b128 v[198:201], v197 offset:38912
	ds_read_b128 v[202:205], v197 offset:39936
	global_load_lds_dwordx4 v142, s[28:29]
	s_mov_b32 m0, s59
	s_nop 0
	global_load_lds_dwordx4 v138, s[28:29]
	s_waitcnt lgkmcnt(8)
	s_barrier
	s_waitcnt lgkmcnt(0)
	v_mfma_f32_16x16x32_bf16 v[124:127], v[128:131], v[158:161], v[124:127]
	v_mfma_f32_16x16x32_bf16 v[120:123], v[150:153], v[158:161], v[120:123]
	v_mfma_f32_16x16x32_bf16 v[108:111], v[128:131], v[166:169], v[108:111]
	v_mfma_f32_16x16x32_bf16 v[104:107], v[150:153], v[166:169], v[104:107]
	v_mfma_f32_16x16x32_bf16 v[92:95], v[128:131], v[174:177], v[92:95]
	v_mfma_f32_16x16x32_bf16 v[88:91], v[150:153], v[174:177], v[88:91]
	v_mfma_f32_16x16x32_bf16 v[76:79], v[128:131], v[198:201], v[76:79]
	v_mfma_f32_16x16x32_bf16 v[72:75], v[150:153], v[198:201], v[72:75]
	v_mfma_f32_16x16x32_bf16 v[124:127], v[132:135], v[162:165], v[124:127]
	v_mfma_f32_16x16x32_bf16 v[120:123], v[154:157], v[162:165], v[120:123]
	v_mfma_f32_16x16x32_bf16 v[108:111], v[132:135], v[170:173], v[108:111]
	v_mfma_f32_16x16x32_bf16 v[104:107], v[154:157], v[170:173], v[104:107]
	v_mfma_f32_16x16x32_bf16 v[92:95], v[132:135], v[178:181], v[92:95]
	v_mfma_f32_16x16x32_bf16 v[88:91], v[154:157], v[178:181], v[88:91]
	v_mfma_f32_16x16x32_bf16 v[76:79], v[132:135], v[202:205], v[76:79]
	v_mfma_f32_16x16x32_bf16 v[72:75], v[154:157], v[202:205], v[72:75]
	s_barrier
	s_add_i32 s28, 0, 0x1c000
	s_add_i32 s29, s42, s52
	s_mov_b32 m0, s29
	ds_read_b128 v[206:209], v225
	ds_read_b128 v[210:213], v225 offset:1024
	ds_read_b128 v[214:217], v225 offset:2048
	ds_read_b128 v[218:221], v225 offset:3072
	global_load_lds_dwordx4 v140, vcc
	s_add_i32 m0, s29, 0x2000
	s_nop 0
	global_load_lds_dwordx4 v136, vcc
	s_barrier
	s_waitcnt lgkmcnt(0)
	v_mfma_f32_16x16x32_bf16 v[116:119], v[206:209], v[158:161], v[116:119]
	v_mfma_f32_16x16x32_bf16 v[112:115], v[214:217], v[158:161], v[112:115]
	v_mfma_f32_16x16x32_bf16 v[100:103], v[206:209], v[166:169], v[100:103]
	v_mfma_f32_16x16x32_bf16 v[96:99], v[214:217], v[166:169], v[96:99]
	v_mfma_f32_16x16x32_bf16 v[84:87], v[206:209], v[174:177], v[84:87]
	v_mfma_f32_16x16x32_bf16 v[80:83], v[214:217], v[174:177], v[80:83]
	v_mfma_f32_16x16x32_bf16 v[68:71], v[206:209], v[198:201], v[68:71]
	v_mfma_f32_16x16x32_bf16 v[64:67], v[214:217], v[198:201], v[64:67]
	v_mfma_f32_16x16x32_bf16 v[116:119], v[210:213], v[162:165], v[116:119]
	v_mfma_f32_16x16x32_bf16 v[112:115], v[218:221], v[162:165], v[112:115]
	v_mfma_f32_16x16x32_bf16 v[100:103], v[210:213], v[170:173], v[100:103]
	v_mfma_f32_16x16x32_bf16 v[96:99], v[218:221], v[170:173], v[96:99]
	v_mfma_f32_16x16x32_bf16 v[84:87], v[210:213], v[178:181], v[84:87]
	v_mfma_f32_16x16x32_bf16 v[80:83], v[218:221], v[178:181], v[80:83]
	v_mfma_f32_16x16x32_bf16 v[68:71], v[210:213], v[202:205], v[68:71]
	v_mfma_f32_16x16x32_bf16 v[64:67], v[218:221], v[202:205], v[64:67]
	s_mov_b32 m0, s62
	s_barrier
	ds_read_b128 v[158:161], v197 offset:49152
	ds_read_b128 v[162:165], v197 offset:50176
	ds_read_b128 v[166:169], v197 offset:51200
	ds_read_b128 v[170:173], v197 offset:52224
	ds_read_b128 v[174:177], v197 offset:53248
	ds_read_b128 v[178:181], v197 offset:54272
	ds_read_b128 v[198:201], v197 offset:55296
	ds_read_b128 v[202:205], v197 offset:56320
	global_load_lds_dwordx4 v142, s[100:101]
	s_mov_b32 m0, s63
	s_nop 0
	global_load_lds_dwordx4 v138, s[100:101]
	s_barrier
; #define PG8_STAGE(bufoff, gbase, voff) do { _Pragma("unroll") for (int _i = 0; _i < 2; ++_i) \
;     __builtin_amdgcn_global_load_lds((const unsigned*)((const char*)(gbase) + (voff)[_i]), (LAS unsigned*)(lds + (bufoff) + ldsw + _i * 8192), 16, 0, 0); } while (0)
; #define PG8_MMA(ai, bj, At, Bt) do { __builtin_amdgcn_s_setprio(1); _Pragma("unroll") for (int m = 0; m < 4; ++m) _Pragma("unroll") for (int n = 0; n < 2; ++n) _Pragma("unroll") for (int k = 0; k < 2; ++k) \
;     acc[ai][bj][m][n] = __builtin_amdgcn_mfma_f32_16x16x32_bf16(Bt[n][k], At[m][k], acc[ai][bj][m][n], 0, 0, 0); __builtin_amdgcn_s_setprio(0); } while (0)
; #define PG8_WAIT_V(n) asm volatile("s_waitcnt vmcnt(" #n ")" ::: "memory")
; #define PG8_WAIT_L(n) asm volatile("s_waitcnt lgkmcnt(" #n ")" ::: "memory")
; #define PG8_BAR __builtin_amdgcn_s_barrier()
; template <class Epi, class Sched>
; DI void gemm_phase(LAS unsigned char* lds, const Gemm g, const Sched& S, const Epi& E) {
;     ...
;       PG8_BAR; PG8_WAIT_L(0); PG8_MMA(1, 0, At, B0); PG8_BAR; PG8_SCHED;
;       PG8_STAGE(PG8_SB(1, 1), b3 + hstep, voffB);
;       PG8_WAIT_V(6); PG8_BAR; PG8_MMA(1, 1, At, B1); PG8_BAR;
;     }
;   DI void operator()(const f32x4 (&acc)[2][2][4][2], const pg8::Unit& u, int wr, int wc, int fr_, int fq_) const {
;     ...
;             if (EPI == EPI_ABIN) {
;               if (n == 0) {
;                 const int gb = u.pn * 256 + bj * 128 + wc * 32; const int f8 = gb + 8 * fq;
;                 const f32x4 v1 = acc[ai][bj][m][1];
;                 if (gb < 384) st_bf8((u16*)(big + E_CQ) + (size_t)token * 384 + f8, v, v1, rinv);
;                 else if (gb < 640) st_bf8((u16*)(big + E_CKV) + (size_t)token * 256 + (f8 - 384), v, v1, rinv);
;                 else if (gb < 672) {
;                   f32x4 a0 = v, a1 = v1;
;                   rope_perm(a0, a1, fq, t_ & 63, tcos, tsin, token & (S_ - 1));
;                   st_bf8((u16*)(big + E_KPE) + (size_t)token * 32 + 8 * fq, a0, a1, rinv);
;                 }
;                 else if (gb < 1184) st_bf8((u16*)(big + E_QNA) + (size_t)token * 512 + (f8 - 672), v, v1, rinv * (0.125f * LOG2E));
;                 else if (gb < 1696) st_bf8((u16*)(big + E_KNA) + (size_t)token * 512 + (f8 - 1184), v, v1, rinv);
;                 else if (gb < 2208) st_bf8((u16*)(big + E_VNAT) + (size_t)token * 512 + (f8 - 1696), v, v1, rinv);
	s_waitcnt lgkmcnt(0)
	v_mfma_f32_16x16x32_bf16 v[60:63], v[128:131], v[158:161], v[60:63]
	v_mfma_f32_16x16x32_bf16 v[56:59], v[150:153], v[158:161], v[56:59]
	v_mfma_f32_16x16x32_bf16 v[44:47], v[128:131], v[166:169], v[44:47]
	v_mfma_f32_16x16x32_bf16 v[40:43], v[150:153], v[166:169], v[40:43]
	v_mfma_f32_16x16x32_bf16 v[28:31], v[128:131], v[174:177], v[28:31]
	v_mfma_f32_16x16x32_bf16 v[24:27], v[150:153], v[174:177], v[24:27]
	v_mfma_f32_16x16x32_bf16 v[12:15], v[128:131], v[198:201], v[12:15]
	v_mfma_f32_16x16x32_bf16 v[8:11], v[150:153], v[198:201], v[8:11]
	v_mfma_f32_16x16x32_bf16 v[60:63], v[132:135], v[162:165], v[60:63]
	v_mfma_f32_16x16x32_bf16 v[56:59], v[154:157], v[162:165], v[56:59]
	v_mfma_f32_16x16x32_bf16 v[44:47], v[132:135], v[170:173], v[44:47]
	v_mfma_f32_16x16x32_bf16 v[40:43], v[154:157], v[170:173], v[40:43]
	v_mfma_f32_16x16x32_bf16 v[28:31], v[132:135], v[178:181], v[28:31]
	v_mfma_f32_16x16x32_bf16 v[24:27], v[154:157], v[178:181], v[24:27]
	v_mfma_f32_16x16x32_bf16 v[12:15], v[132:135], v[202:205], v[12:15]
	v_mfma_f32_16x16x32_bf16 v[8:11], v[154:157], v[202:205], v[8:11]
	s_barrier
	s_add_u32 s22, s22, 0x40080
	s_addc_u32 s23, s23, 0
	s_add_i32 s28, s28, s52
	s_mov_b32 m0, s28
	s_nop 0
	global_load_lds_dwordx4 v140, s[22:23]
	s_add_i32 m0, s28, 0x2000
	s_nop 0
	global_load_lds_dwordx4 v136, s[22:23]
	s_waitcnt vmcnt(6)
	s_barrier
	v_mfma_f32_16x16x32_bf16 v[52:55], v[206:209], v[158:161], v[52:55]
	v_mfma_f32_16x16x32_bf16 v[48:51], v[214:217], v[158:161], v[48:51]
	v_mfma_f32_16x16x32_bf16 v[36:39], v[206:209], v[166:169], v[36:39]
	v_mfma_f32_16x16x32_bf16 v[32:35], v[214:217], v[166:169], v[32:35]
	v_mfma_f32_16x16x32_bf16 v[20:23], v[206:209], v[174:177], v[20:23]
	v_mfma_f32_16x16x32_bf16 v[16:19], v[214:217], v[174:177], v[16:19]
	v_mfma_f32_16x16x32_bf16 v[4:7], v[206:209], v[198:201], v[4:7]
	v_mfma_f32_16x16x32_bf16 v[0:3], v[214:217], v[198:201], v[0:3]
	v_mfma_f32_16x16x32_bf16 v[52:55], v[210:213], v[162:165], v[52:55]
	v_mfma_f32_16x16x32_bf16 v[48:51], v[218:221], v[162:165], v[48:51]
	v_mfma_f32_16x16x32_bf16 v[36:39], v[210:213], v[170:173], v[36:39]
	v_mfma_f32_16x16x32_bf16 v[32:35], v[218:221], v[170:173], v[32:35]
	v_mfma_f32_16x16x32_bf16 v[20:23], v[210:213], v[178:181], v[20:23]
	v_mfma_f32_16x16x32_bf16 v[16:19], v[218:221], v[178:181], v[16:19]
	v_mfma_f32_16x16x32_bf16 v[4:7], v[210:213], v[202:205], v[4:7]
	v_mfma_f32_16x16x32_bf16 v[0:3], v[218:221], v[202:205], v[0:3]
	s_add_i32 s41, s41, 2
	s_add_u32 s20, s20, 0x100
	s_addc_u32 s21, s21, 0
	s_add_u32 s39, s39, 0x100
	s_addc_u32 s40, s40, 0
	s_cmp_gt_u32 s41, 13
	s_barrier
	s_cbranch_scc0 .LBB0_689
	v_mov_b32_e32 v128, v182
	s_lshl_b32 s20, s34, 10
	v_bfe_u32 v129, v128, 4, 2
	v_and_or_b32 v201, v128, 15, s60
	s_lshl_b32 s13, s35, 8
	v_lshlrev_b32_e32 v128, 2, v128
	s_movk_i32 s21, 0x80
	s_add_i32 s20, s20, 0
	s_lshl_b32 s15, s36, 8
	v_bitop3_b32 v198, v128, s21, v190 bitop3:0x6c
	v_lshl_add_u32 v128, v201, 2, s20
	s_or_b32 s20, s13, s61
	v_add_u32_e32 v200, 0x20000, v128
	s_cmpk_gt_i32 s20, 0x17f
	ds_read_b32 v156, v200
	s_cselect_b64 s[28:29], -1, 0
	s_cmpk_gt_u32 s13, 0x27f
	s_cselect_b64 s[46:47], -1, 0
	s_cmpk_gt_u32 s20, 0x29f
	s_cselect_b64 s[40:41], -1, 0
	s_cmpk_gt_u32 s20, 0x49f
	v_lshlrev_b32_e32 v144, 3, v129
	v_add_u32_e32 v154, s15, v201
	s_cselect_b64 s[34:35], -1, 0
	s_cmpk_gt_u32 s20, 0x69f
	v_ashrrev_i32_e32 v155, 31, v154
	v_lshlrev_b32_e32 v128, 4, v154
	v_or_b32_e32 v150, s20, v144
	s_cselect_b64 s[22:23], -1, 0
	s_cmpk_lt_u32 s20, 0x8a0
	v_and_b32_e32 v199, 8, v144
	v_cmp_lt_u32_e64 s[92:93], 1, v129
	v_lshlrev_b64 v[164:165], 10, v[154:155]
	s_waitcnt lgkmcnt(0)
	v_mul_f32_e32 v162, 0x3e38aa3b, v156
	v_and_b32_e32 v157, 0xfcf0, v128
	v_lshlrev_b64 v[160:161], 6, v[154:155]
	v_lshlrev_b64 v[158:159], 9, v[154:155]
	s_cselect_b64 s[20:21], -1, 0
	v_mov_b32_e32 v152, v150
	v_mov_b32_e32 v153, v145
	s_mov_b64 s[36:37], -1
	s_and_b64 vcc, exec, s[28:29]
	s_cbranch_vccz .LBB0_714
	s_and_b64 vcc, exec, s[46:47]
	s_cbranch_vccz .LBB0_711
	s_and_b64 vcc, exec, s[40:41]
	s_cbranch_vccz .LBB0_704
	s_and_b64 vcc, exec, s[34:35]
	s_cbranch_vccz .LBB0_701
	s_and_b64 vcc, exec, s[22:23]
	s_cbranch_vccz .LBB0_698
	s_andn2_b64 vcc, exec, s[20:21]
	s_cbranch_vccnz .LBB0_697
	v_lshl_add_u64 v[128:129], s[2:3], 0, v[164:165]
	v_lshl_add_u64 v[132:133], v[152:153], 1, v[128:129]
	v_pk_mul_f32 v[128:129], v[124:125], v[156:157] op_sel_hi:[1,0]
	v_pk_mul_f32 v[130:131], v[126:127], v[156:157] op_sel_hi:[1,0]
	v_cvt_pk_bf16_f32 v128, v128, v129
	v_cvt_pk_bf16_f32 v129, v130, v131
	v_pk_mul_f32 v[130:131], v[120:121], v[156:157] op_sel_hi:[1,0]
	v_pk_mul_f32 v[134:135], v[122:123], v[156:157] op_sel_hi:[1,0]
	v_add_co_u32_e32 v132, vcc, 0x69ff000, v132
	v_cvt_pk_bf16_f32 v130, v130, v131
	v_cvt_pk_bf16_f32 v131, v134, v135
	v_addc_co_u32_e32 v133, vcc, 0, v133, vcc
	global_store_dwordx4 v[132:133], v[128:131], off offset:704

; #define PG8_STAGE(bufoff, gbase, voff) do { _Pragma("unroll") for (int _i = 0; _i < 2; ++_i) \
;     __builtin_amdgcn_global_load_lds((const unsigned*)((const char*)(gbase) + (voff)[_i]), (LAS unsigned*)(lds + (bufoff) + ldsw + _i * 8192), 16, 0, 0); } while (0)
; #define PG8_LDA(dst, b, h) do { _Pragma("unroll") for (int m = 0; m < 4; ++m) _Pragma("unroll") for (int k = 0; k < 2; ++k) dst[m][k] = *(const LAS bf16x8*)(lds + PG8_SA(b, h) + aoff + m * 2048 + k * 1024); } while (0)
; #define PG8_LDB(dst, b, h) do { _Pragma("unroll") for (int n = 0; n < 2; ++n) _Pragma("unroll") for (int k = 0; k < 2; ++k) dst[n][k] = *(const LAS bf16x8*)(lds + PG8_SB(b, h) + boff + n * 2048 + k * 1024); } while (0)
; #define PG8_MMA(ai, bj, At, Bt) do { __builtin_amdgcn_s_setprio(1); _Pragma("unroll") for (int m = 0; m < 4; ++m) _Pragma("unroll") for (int n = 0; n < 2; ++n) _Pragma("unroll") for (int k = 0; k < 2; ++k) \
;     acc[ai][bj][m][n] = __builtin_amdgcn_mfma_f32_16x16x32_bf16(Bt[n][k], At[m][k], acc[ai][bj][m][n], 0, 0, 0); __builtin_amdgcn_s_setprio(0); } while (0)
; #define PG8_WAIT_V(n) asm volatile("s_waitcnt vmcnt(" #n ")" ::: "memory")
; #define PG8_WAIT_L(n) asm volatile("s_waitcnt lgkmcnt(" #n ")" ::: "memory")
; #define PG8_BAR __builtin_amdgcn_s_barrier()
; #define PG8_SCHED __builtin_amdgcn_sched_barrier(0)
; template <class Epi, class Sched>
; DI void gemm_phase(LAS unsigned char* lds, const Gemm g, const Sched& S, const Epi& E) {
;     ...
;       PG8_LDB(B0, 0, 0); PG8_SCHED; PG8_LDA(At, 0, 0); PG8_STAGE(PG8_SA(1, 1), a1 + hstep, voffA);
;       PG8_WAIT_L(8); PG8_BAR; PG8_WAIT_L(0); PG8_MMA(0, 0, At, B0); PG8_BAR; PG8_SCHED;
;       PG8_LDB(B1, 0, 1); PG8_STAGE(PG8_SB(0, 0), b2, voffB);
;       PG8_BAR; PG8_WAIT_L(0); PG8_MMA(0, 1, At, B1); PG8_BAR;
;       PG8_LDA(At, 0, 1); PG8_STAGE(PG8_SA(0, 0), a2, voffA);
;       PG8_BAR; PG8_WAIT_L(0); PG8_MMA(1, 0, At, B0); PG8_BAR; PG8_SCHED;
;       PG8_STAGE(PG8_SB(0, 1), b2 + hstep, voffB);
;       PG8_WAIT_V(6); PG8_BAR; PG8_MMA(1, 1, At, B1); PG8_BAR;
.LBB0_1202:
	s_add_u32 s20, s18, 0x100
	s_addc_u32 s21, s19, 0
	s_add_i32 s55, 0, 0x10000
	ds_read_b128 v[140:143], v224
	ds_read_b128 v[146:149], v224 offset:1024
	ds_read_b128 v[150:153], v224 offset:2048
	ds_read_b128 v[154:157], v224 offset:3072
	s_cmp_eq_u32 s54, 2
	s_cselect_b32 s29, s3, s21
	s_cselect_b32 s28, s2, s20
	s_cselect_b32 s23, s5, s53
	s_cselect_b32 s22, s4, s52
	s_add_i32 m0, s38, 0xc000
	ds_read_b128 v[158:161], v163
	ds_read_b128 v[164:167], v163 offset:1024
	ds_read_b128 v[168:171], v163 offset:2048
	ds_read_b128 v[172:175], v163 offset:3072
	ds_read_b128 v[176:179], v163 offset:4096
	ds_read_b128 v[196:199], v163 offset:5120
	ds_read_b128 v[200:203], v163 offset:6144
	ds_read_b128 v[204:207], v163 offset:7168
	global_load_lds_dwordx4 v136, s[18:19]
	s_add_i32 m0, s38, 0xe000
	s_nop 0
	global_load_lds_dwordx4 v138, s[18:19]
	s_waitcnt lgkmcnt(8)
	s_barrier
	s_waitcnt lgkmcnt(0)
	v_mfma_f32_16x16x32_bf16 v[124:127], v[140:143], v[158:161], v[124:127]
	v_mfma_f32_16x16x32_bf16 v[120:123], v[150:153], v[158:161], v[120:123]
	v_mfma_f32_16x16x32_bf16 v[108:111], v[140:143], v[168:171], v[108:111]
	v_mfma_f32_16x16x32_bf16 v[104:107], v[150:153], v[168:171], v[104:107]
	v_mfma_f32_16x16x32_bf16 v[92:95], v[140:143], v[176:179], v[92:95]
	v_mfma_f32_16x16x32_bf16 v[88:91], v[150:153], v[176:179], v[88:91]
	v_mfma_f32_16x16x32_bf16 v[76:79], v[140:143], v[200:203], v[76:79]
	v_mfma_f32_16x16x32_bf16 v[72:75], v[150:153], v[200:203], v[72:75]
	v_mfma_f32_16x16x32_bf16 v[124:127], v[146:149], v[164:167], v[124:127]
	v_mfma_f32_16x16x32_bf16 v[120:123], v[154:157], v[164:167], v[120:123]
	v_mfma_f32_16x16x32_bf16 v[108:111], v[146:149], v[172:175], v[108:111]
	v_mfma_f32_16x16x32_bf16 v[104:107], v[154:157], v[172:175], v[104:107]
	v_mfma_f32_16x16x32_bf16 v[92:95], v[146:149], v[196:199], v[92:95]
	v_mfma_f32_16x16x32_bf16 v[88:91], v[154:157], v[196:199], v[88:91]
	v_mfma_f32_16x16x32_bf16 v[76:79], v[146:149], v[204:207], v[76:79]
	v_mfma_f32_16x16x32_bf16 v[72:75], v[154:157], v[204:207], v[72:75]
	s_barrier
	s_add_i32 s56, 0, 0x14000
	s_add_i32 s18, s55, s35
	s_add_u32 vcc_lo, s22, s0
	s_addc_u32 vcc_hi, s23, s1
	s_mov_b32 m0, s18
	ds_read_b128 v[208:211], v225
	ds_read_b128 v[212:215], v225 offset:1024
	ds_read_b128 v[216:219], v225 offset:2048
	ds_read_b128 v[220:223], v225 offset:3072
	global_load_lds_dwordx4 v130, s[22:23]
	s_add_i32 m0, s18, 0x2000
	s_nop 0
	global_load_lds_dwordx4 v134, s[22:23]
	s_barrier
	s_waitcnt lgkmcnt(0)
	v_mfma_f32_16x16x32_bf16 v[116:119], v[208:211], v[158:161], v[116:119]
	v_mfma_f32_16x16x32_bf16 v[112:115], v[216:219], v[158:161], v[112:115]
	v_mfma_f32_16x16x32_bf16 v[100:103], v[208:211], v[168:171], v[100:103]
	v_mfma_f32_16x16x32_bf16 v[96:99], v[216:219], v[168:171], v[96:99]
	v_mfma_f32_16x16x32_bf16 v[84:87], v[208:211], v[176:179], v[84:87]
	v_mfma_f32_16x16x32_bf16 v[80:83], v[216:219], v[176:179], v[80:83]
	v_mfma_f32_16x16x32_bf16 v[68:71], v[208:211], v[200:203], v[68:71]
	v_mfma_f32_16x16x32_bf16 v[64:67], v[216:219], v[200:203], v[64:67]
	v_mfma_f32_16x16x32_bf16 v[116:119], v[212:215], v[164:167], v[116:119]
	v_mfma_f32_16x16x32_bf16 v[112:115], v[220:223], v[164:167], v[112:115]
	v_mfma_f32_16x16x32_bf16 v[100:103], v[212:215], v[172:175], v[100:103]
	v_mfma_f32_16x16x32_bf16 v[96:99], v[220:223], v[172:175], v[96:99]
	v_mfma_f32_16x16x32_bf16 v[84:87], v[212:215], v[196:199], v[84:87]
	v_mfma_f32_16x16x32_bf16 v[80:83], v[220:223], v[196:199], v[80:83]
	v_mfma_f32_16x16x32_bf16 v[68:71], v[212:215], v[204:207], v[68:71]
	v_mfma_f32_16x16x32_bf16 v[64:67], v[220:223], v[204:207], v[64:67]
	s_mov_b32 m0, s38
	s_add_u32 s100, s28, s0
	s_addc_u32 s101, s29, s1
	s_barrier
	ds_read_b128 v[158:161], v163 offset:16384
	ds_read_b128 v[164:167], v163 offset:17408
	ds_read_b128 v[168:171], v163 offset:18432
	ds_read_b128 v[172:175], v163 offset:19456
	ds_read_b128 v[176:179], v163 offset:20480
	ds_read_b128 v[196:199], v163 offset:21504
	ds_read_b128 v[200:203], v163 offset:22528
	ds_read_b128 v[204:207], v163 offset:23552
	global_load_lds_dwordx4 v128, s[28:29]
	s_mov_b32 m0, s39
	s_nop 0
	global_load_lds_dwordx4 v132, s[28:29]
	s_barrier
	s_waitcnt lgkmcnt(0)
	v_mfma_f32_16x16x32_bf16 v[60:63], v[140:143], v[158:161], v[60:63]
	v_mfma_f32_16x16x32_bf16 v[56:59], v[150:153], v[158:161], v[56:59]
	v_mfma_f32_16x16x32_bf16 v[44:47], v[140:143], v[168:171], v[44:47]
	v_mfma_f32_16x16x32_bf16 v[40:43], v[150:153], v[168:171], v[40:43]
	v_mfma_f32_16x16x32_bf16 v[28:31], v[140:143], v[176:179], v[28:31]
	v_mfma_f32_16x16x32_bf16 v[24:27], v[150:153], v[176:179], v[24:27]
	v_mfma_f32_16x16x32_bf16 v[12:15], v[140:143], v[200:203], v[12:15]
	v_mfma_f32_16x16x32_bf16 v[8:11], v[150:153], v[200:203], v[8:11]
	v_mfma_f32_16x16x32_bf16 v[60:63], v[146:149], v[164:167], v[60:63]
	v_mfma_f32_16x16x32_bf16 v[56:59], v[154:157], v[164:167], v[56:59]
	v_mfma_f32_16x16x32_bf16 v[44:47], v[146:149], v[172:175], v[44:47]
	v_mfma_f32_16x16x32_bf16 v[40:43], v[154:157], v[172:175], v[40:43]
	v_mfma_f32_16x16x32_bf16 v[28:31], v[146:149], v[196:199], v[28:31]
	v_mfma_f32_16x16x32_bf16 v[24:27], v[154:157], v[196:199], v[24:27]
	v_mfma_f32_16x16x32_bf16 v[12:15], v[146:149], v[204:207], v[12:15]
	v_mfma_f32_16x16x32_bf16 v[8:11], v[154:157], v[204:207], v[8:11]
	s_barrier
	s_add_u32 s18, s22, 0x18000
	s_addc_u32 s19, s23, 0
	s_add_i32 s55, s56, s35
	s_mov_b32 m0, s55
	s_nop 0
	global_load_lds_dwordx4 v130, s[18:19]
	s_add_i32 m0, s55, 0x2000
	s_nop 0
	global_load_lds_dwordx4 v134, s[18:19]
	s_waitcnt vmcnt(6)
	s_barrier
; #define PG8_STAGE(bufoff, gbase, voff) do { _Pragma("unroll") for (int _i = 0; _i < 2; ++_i) \
;     __builtin_amdgcn_global_load_lds((const unsigned*)((const char*)(gbase) + (voff)[_i]), (LAS unsigned*)(lds + (bufoff) + ldsw + _i * 8192), 16, 0, 0); } while (0)
; #define PG8_LDA(dst, b, h) do { _Pragma("unroll") for (int m = 0; m < 4; ++m) _Pragma("unroll") for (int k = 0; k < 2; ++k) dst[m][k] = *(const LAS bf16x8*)(lds + PG8_SA(b, h) + aoff + m * 2048 + k * 1024); } while (0)
; #define PG8_LDB(dst, b, h) do { _Pragma("unroll") for (int n = 0; n < 2; ++n) _Pragma("unroll") for (int k = 0; k < 2; ++k) dst[n][k] = *(const LAS bf16x8*)(lds + PG8_SB(b, h) + boff + n * 2048 + k * 1024); } while (0)
; #define PG8_MMA(ai, bj, At, Bt) do { __builtin_amdgcn_s_setprio(1); _Pragma("unroll") for (int m = 0; m < 4; ++m) _Pragma("unroll") for (int n = 0; n < 2; ++n) _Pragma("unroll") for (int k = 0; k < 2; ++k) \
;     acc[ai][bj][m][n] = __builtin_amdgcn_mfma_f32_16x16x32_bf16(Bt[n][k], At[m][k], acc[ai][bj][m][n], 0, 0, 0); __builtin_amdgcn_s_setprio(0); } while (0)
; #define PG8_WAIT_V(n) asm volatile("s_waitcnt vmcnt(" #n ")" ::: "memory")
; #define PG8_WAIT_L(n) asm volatile("s_waitcnt lgkmcnt(" #n ")" ::: "memory")
; #define PG8_BAR __builtin_amdgcn_s_barrier()
; #define PG8_SCHED __builtin_amdgcn_sched_barrier(0)
; template <class Epi, class Sched>
; DI void gemm_phase(LAS unsigned char* lds, const Gemm g, const Sched& S, const Epi& E) {
;     ...
;       PG8_WAIT_V(6); PG8_BAR; PG8_MMA(1, 1, At, B1); PG8_BAR;
;       PG8_LDB(B0, 1, 0); PG8_SCHED; PG8_LDA(At, 1, 0); PG8_STAGE(PG8_SA(0, 1), a2 + hstep, voffA);
;       PG8_WAIT_L(8); PG8_BAR; PG8_WAIT_L(0); PG8_MMA(0, 0, At, B0); PG8_BAR; PG8_SCHED;
;       PG8_LDB(B1, 1, 1); PG8_STAGE(PG8_SB(1, 0), b3, voffB);
;       PG8_BAR; PG8_WAIT_L(0); PG8_MMA(0, 1, At, B1); PG8_BAR;
;       PG8_LDA(At, 1, 1); PG8_STAGE(PG8_SA(1, 0), a3, voffA);
;       PG8_BAR; PG8_WAIT_L(0); PG8_MMA(1, 0, At, B0); PG8_BAR; PG8_SCHED;
	v_mfma_f32_16x16x32_bf16 v[52:55], v[208:211], v[158:161], v[52:55]
	v_mfma_f32_16x16x32_bf16 v[48:51], v[216:219], v[158:161], v[48:51]
	v_mfma_f32_16x16x32_bf16 v[36:39], v[208:211], v[168:171], v[36:39]
	v_mfma_f32_16x16x32_bf16 v[32:35], v[216:219], v[168:171], v[32:35]
	v_mfma_f32_16x16x32_bf16 v[20:23], v[208:211], v[176:179], v[20:23]
	v_mfma_f32_16x16x32_bf16 v[16:19], v[216:219], v[176:179], v[16:19]
	v_mfma_f32_16x16x32_bf16 v[4:7], v[208:211], v[200:203], v[4:7]
	v_mfma_f32_16x16x32_bf16 v[0:3], v[216:219], v[200:203], v[0:3]
	v_mfma_f32_16x16x32_bf16 v[52:55], v[212:215], v[164:167], v[52:55]
	v_mfma_f32_16x16x32_bf16 v[48:51], v[220:223], v[164:167], v[48:51]
	v_mfma_f32_16x16x32_bf16 v[36:39], v[212:215], v[172:175], v[36:39]
	v_mfma_f32_16x16x32_bf16 v[32:35], v[220:223], v[172:175], v[32:35]
	v_mfma_f32_16x16x32_bf16 v[20:23], v[212:215], v[196:199], v[20:23]
	v_mfma_f32_16x16x32_bf16 v[16:19], v[220:223], v[196:199], v[16:19]
	v_mfma_f32_16x16x32_bf16 v[4:7], v[212:215], v[204:207], v[4:7]
	v_mfma_f32_16x16x32_bf16 v[0:3], v[220:223], v[204:207], v[0:3]
	s_add_i32 s55, 0, 0x18000
	s_barrier
	ds_read_b128 v[140:143], v226
	ds_read_b128 v[146:149], v226 offset:1024
	ds_read_b128 v[150:153], v226 offset:2048
	ds_read_b128 v[154:157], v226 offset:3072
	s_add_u32 s18, s28, 0x18000
	s_addc_u32 s19, s29, 0
	s_mov_b32 m0, s40
	ds_read_b128 v[158:161], v163 offset:32768
	ds_read_b128 v[164:167], v163 offset:33792
	ds_read_b128 v[168:171], v163 offset:34816
	ds_read_b128 v[172:175], v163 offset:35840
	ds_read_b128 v[176:179], v163 offset:36864
	ds_read_b128 v[196:199], v163 offset:37888
	ds_read_b128 v[200:203], v163 offset:38912
	ds_read_b128 v[204:207], v163 offset:39936
	global_load_lds_dwordx4 v128, s[18:19]
	s_mov_b32 m0, s41
	s_nop 0
	global_load_lds_dwordx4 v132, s[18:19]
	s_waitcnt lgkmcnt(8)
	s_barrier
	s_waitcnt lgkmcnt(0)
	v_mfma_f32_16x16x32_bf16 v[124:127], v[140:143], v[158:161], v[124:127]
	v_mfma_f32_16x16x32_bf16 v[120:123], v[150:153], v[158:161], v[120:123]
	v_mfma_f32_16x16x32_bf16 v[108:111], v[140:143], v[168:171], v[108:111]
	v_mfma_f32_16x16x32_bf16 v[104:107], v[150:153], v[168:171], v[104:107]
	v_mfma_f32_16x16x32_bf16 v[92:95], v[140:143], v[176:179], v[92:95]
	v_mfma_f32_16x16x32_bf16 v[88:91], v[150:153], v[176:179], v[88:91]
	v_mfma_f32_16x16x32_bf16 v[76:79], v[140:143], v[200:203], v[76:79]
	v_mfma_f32_16x16x32_bf16 v[72:75], v[150:153], v[200:203], v[72:75]
	v_mfma_f32_16x16x32_bf16 v[124:127], v[146:149], v[164:167], v[124:127]
	v_mfma_f32_16x16x32_bf16 v[120:123], v[154:157], v[164:167], v[120:123]
	v_mfma_f32_16x16x32_bf16 v[108:111], v[146:149], v[172:175], v[108:111]
	v_mfma_f32_16x16x32_bf16 v[104:107], v[154:157], v[172:175], v[104:107]
	v_mfma_f32_16x16x32_bf16 v[92:95], v[146:149], v[196:199], v[92:95]
	v_mfma_f32_16x16x32_bf16 v[88:91], v[154:157], v[196:199], v[88:91]
	v_mfma_f32_16x16x32_bf16 v[76:79], v[146:149], v[204:207], v[76:79]
	v_mfma_f32_16x16x32_bf16 v[72:75], v[154:157], v[204:207], v[72:75]
	s_barrier
	s_add_i32 s28, 0, 0x1c000
	s_add_i32 s18, s55, s35
	s_mov_b32 m0, s18
	ds_read_b128 v[208:211], v227
	ds_read_b128 v[212:215], v227 offset:1024
	ds_read_b128 v[216:219], v227 offset:2048
	ds_read_b128 v[220:223], v227 offset:3072
	global_load_lds_dwordx4 v130, vcc
	s_add_i32 m0, s18, 0x2000
	s_nop 0
	global_load_lds_dwordx4 v134, vcc
	s_barrier
	s_waitcnt lgkmcnt(0)
	v_mfma_f32_16x16x32_bf16 v[116:119], v[208:211], v[158:161], v[116:119]
	v_mfma_f32_16x16x32_bf16 v[112:115], v[216:219], v[158:161], v[112:115]
	v_mfma_f32_16x16x32_bf16 v[100:103], v[208:211], v[168:171], v[100:103]
	v_mfma_f32_16x16x32_bf16 v[96:99], v[216:219], v[168:171], v[96:99]
	v_mfma_f32_16x16x32_bf16 v[84:87], v[208:211], v[176:179], v[84:87]
	v_mfma_f32_16x16x32_bf16 v[80:83], v[216:219], v[176:179], v[80:83]
	v_mfma_f32_16x16x32_bf16 v[68:71], v[208:211], v[200:203], v[68:71]
	v_mfma_f32_16x16x32_bf16 v[64:67], v[216:219], v[200:203], v[64:67]
	v_mfma_f32_16x16x32_bf16 v[116:119], v[212:215], v[164:167], v[116:119]
	v_mfma_f32_16x16x32_bf16 v[112:115], v[220:223], v[164:167], v[112:115]
	v_mfma_f32_16x16x32_bf16 v[100:103], v[212:215], v[172:175], v[100:103]
	v_mfma_f32_16x16x32_bf16 v[96:99], v[220:223], v[172:175], v[96:99]
	v_mfma_f32_16x16x32_bf16 v[84:87], v[212:215], v[196:199], v[84:87]
	v_mfma_f32_16x16x32_bf16 v[80:83], v[220:223], v[196:199], v[80:83]
	v_mfma_f32_16x16x32_bf16 v[68:71], v[212:215], v[204:207], v[68:71]
	v_mfma_f32_16x16x32_bf16 v[64:67], v[220:223], v[204:207], v[64:67]
	s_mov_b32 m0, s44
	s_barrier
	ds_read_b128 v[158:161], v163 offset:49152
	ds_read_b128 v[164:167], v163 offset:50176
	ds_read_b128 v[168:171], v163 offset:51200
	ds_read_b128 v[172:175], v163 offset:52224
	ds_read_b128 v[176:179], v163 offset:53248
	ds_read_b128 v[196:199], v163 offset:54272
	ds_read_b128 v[200:203], v163 offset:55296
	ds_read_b128 v[204:207], v163 offset:56320
	global_load_lds_dwordx4 v128, s[100:101]
	s_mov_b32 m0, s45
	s_nop 0
	global_load_lds_dwordx4 v132, s[100:101]
	s_barrier
; #define PG8_STAGE(bufoff, gbase, voff) do { _Pragma("unroll") for (int _i = 0; _i < 2; ++_i) \
;     __builtin_amdgcn_global_load_lds((const unsigned*)((const char*)(gbase) + (voff)[_i]), (LAS unsigned*)(lds + (bufoff) + ldsw + _i * 8192), 16, 0, 0); } while (0)
; #define PG8_MMA(ai, bj, At, Bt) do { __builtin_amdgcn_s_setprio(1); _Pragma("unroll") for (int m = 0; m < 4; ++m) _Pragma("unroll") for (int n = 0; n < 2; ++n) _Pragma("unroll") for (int k = 0; k < 2; ++k) \
;     acc[ai][bj][m][n] = __builtin_amdgcn_mfma_f32_16x16x32_bf16(Bt[n][k], At[m][k], acc[ai][bj][m][n], 0, 0, 0); __builtin_amdgcn_s_setprio(0); } while (0)
; #define PG8_WAIT_V(n) asm volatile("s_waitcnt vmcnt(" #n ")" ::: "memory")
; #define PG8_WAIT_L(n) asm volatile("s_waitcnt lgkmcnt(" #n ")" ::: "memory")
; #define PG8_BAR __builtin_amdgcn_s_barrier()
; #define PG8_SCHED __builtin_amdgcn_sched_barrier(0)
; template <class Epi, class Sched>
; DI void gemm_phase(LAS unsigned char* lds, const Gemm g, const Sched& S, const Epi& E) {
;     ...
;       PG8_BAR; PG8_WAIT_L(0); PG8_MMA(1, 0, At, B0); PG8_BAR; PG8_SCHED;
;       PG8_STAGE(PG8_SB(1, 1), b3 + hstep, voffB);
;       PG8_WAIT_V(6); PG8_BAR; PG8_MMA(1, 1, At, B1); PG8_BAR;
;     }
; DI void rope_perm(f32x4& a0, f32x4& a1, int fq, int lane, const float* tcos, const float* tsin, int pos) {
;   f32x4 p0, p1;
; #pragma unroll
;   for (int e = 0; e < 4; ++e) { p0[e] = shx(a0[e], 32, lane); p1[e] = shx(a1[e], 32, lane); }
;   const int jb = 8 * (fq & 1);
;   const f32x4 c0 = *(const f32x4*)(tcos + pos * 16 + jb), c1 = *(const f32x4*)(tcos + pos * 16 + jb + 4);
;   const f32x4 s0 = *(const f32x4*)(tsin + pos * 16 + jb), s1 = *(const f32x4*)(tsin + pos * 16 + jb + 4);
;   if (fq < 2) { a0 = a0 * c0 - p0 * s0; a1 = a1 * c1 - p1 * s1; }
;   else        { a0 = a0 * c0 + p0 * s0; a1 = a1 * c1 + p1 * s1; }
; }
	s_waitcnt lgkmcnt(0)
	v_mfma_f32_16x16x32_bf16 v[60:63], v[140:143], v[158:161], v[60:63]
	v_mfma_f32_16x16x32_bf16 v[56:59], v[150:153], v[158:161], v[56:59]
	v_mfma_f32_16x16x32_bf16 v[44:47], v[140:143], v[168:171], v[44:47]
	v_mfma_f32_16x16x32_bf16 v[40:43], v[150:153], v[168:171], v[40:43]
	v_mfma_f32_16x16x32_bf16 v[28:31], v[140:143], v[176:179], v[28:31]
	v_mfma_f32_16x16x32_bf16 v[24:27], v[150:153], v[176:179], v[24:27]
	v_mfma_f32_16x16x32_bf16 v[12:15], v[140:143], v[200:203], v[12:15]
	v_mfma_f32_16x16x32_bf16 v[8:11], v[150:153], v[200:203], v[8:11]
	v_mfma_f32_16x16x32_bf16 v[60:63], v[146:149], v[164:167], v[60:63]
	v_mfma_f32_16x16x32_bf16 v[56:59], v[154:157], v[164:167], v[56:59]
	v_mfma_f32_16x16x32_bf16 v[44:47], v[146:149], v[172:175], v[44:47]
	v_mfma_f32_16x16x32_bf16 v[40:43], v[154:157], v[172:175], v[40:43]
	v_mfma_f32_16x16x32_bf16 v[28:31], v[146:149], v[196:199], v[28:31]
	v_mfma_f32_16x16x32_bf16 v[24:27], v[154:157], v[196:199], v[24:27]
	v_mfma_f32_16x16x32_bf16 v[12:15], v[146:149], v[204:207], v[12:15]
	v_mfma_f32_16x16x32_bf16 v[8:11], v[154:157], v[204:207], v[8:11]
	s_barrier
	s_add_u32 s18, s22, 0x18080
	s_addc_u32 s19, s23, 0
	s_add_i32 s22, s28, s35
	s_mov_b32 m0, s22
	s_nop 0
	global_load_lds_dwordx4 v130, s[18:19]
	s_add_i32 m0, s22, 0x2000
	s_nop 0
	global_load_lds_dwordx4 v134, s[18:19]
	s_waitcnt vmcnt(6)
	s_barrier
	v_mfma_f32_16x16x32_bf16 v[52:55], v[208:211], v[158:161], v[52:55]
	v_mfma_f32_16x16x32_bf16 v[48:51], v[216:219], v[158:161], v[48:51]
	v_mfma_f32_16x16x32_bf16 v[36:39], v[208:211], v[168:171], v[36:39]
	v_mfma_f32_16x16x32_bf16 v[32:35], v[216:219], v[168:171], v[32:35]
	v_mfma_f32_16x16x32_bf16 v[20:23], v[208:211], v[176:179], v[20:23]
	v_mfma_f32_16x16x32_bf16 v[16:19], v[216:219], v[176:179], v[16:19]
	v_mfma_f32_16x16x32_bf16 v[4:7], v[208:211], v[200:203], v[4:7]
	v_mfma_f32_16x16x32_bf16 v[0:3], v[216:219], v[200:203], v[0:3]
	v_mfma_f32_16x16x32_bf16 v[52:55], v[212:215], v[164:167], v[52:55]
	v_mfma_f32_16x16x32_bf16 v[48:51], v[220:223], v[164:167], v[48:51]
	v_mfma_f32_16x16x32_bf16 v[36:39], v[212:215], v[172:175], v[36:39]
	v_mfma_f32_16x16x32_bf16 v[32:35], v[220:223], v[172:175], v[32:35]
	v_mfma_f32_16x16x32_bf16 v[20:23], v[212:215], v[196:199], v[20:23]
	v_mfma_f32_16x16x32_bf16 v[16:19], v[220:223], v[196:199], v[16:19]
	v_mfma_f32_16x16x32_bf16 v[4:7], v[212:215], v[204:207], v[4:7]
	v_mfma_f32_16x16x32_bf16 v[0:3], v[220:223], v[204:207], v[0:3]
	s_add_i32 s54, s54, 2
	s_add_u32 s52, s52, 0x100
	s_addc_u32 s53, s53, 0
	s_cmp_gt_u32 s54, 3
	s_mov_b64 s[18:19], s[20:21]
	s_barrier
	s_cbranch_scc0 .LBB0_1202
	v_mov_b32_e32 v140, v182
	s_lshl_b32 s19, s51, 10
	s_lshl_b32 s18, s49, 8
	s_or_b32 s18, s18, s43
	v_and_or_b32 v167, v140, 15, s42
	v_lshlrev_b32_e32 v141, 2, v140
	s_movk_i32 s20, 0x80
	s_add_i32 s19, s19, 0
	v_bitop3_b32 v164, v141, s20, v190 bitop3:0x6c
	v_lshl_add_u32 v141, v167, 2, s19
	s_mul_hi_i32 s19, s18, 0x2aaaaaab
	v_add_u32_e32 v166, 0x20000, v141
	s_lshr_b32 s20, s19, 31
	s_lshr_b32 s19, s19, 4
	s_lshl_b32 s50, s50, 8
	ds_read_b32 v144, v166
	s_add_i32 s19, s19, s20
	v_add_u32_e32 v165, s50, v167
	s_mulk_i32 s19, 0x60
	v_bfe_u32 v168, v140, 4, 2
	v_lshrrev_b32_e32 v140, 1, v140
	v_lshlrev_b32_e32 v141, 4, v165
	s_sub_i32 s19, s18, s19
	v_and_b32_e32 v140, 8, v140
	v_and_b32_e32 v141, 0xfcf0, v141
	s_cmp_eq_u32 s19, 64
	v_cmp_lt_u32_e64 s[78:79], 1, v168
	s_cselect_b64 s[20:21], -1, 0
	s_cmp_lg_u32 s19, 64
	v_lshlrev_b32_e32 v142, 2, v141
	v_lshlrev_b32_e32 v140, 2, v140
	s_cbranch_scc1 .LBB0_1209
	v_mov_b32_e32 v143, v145
	v_lshl_add_u64 v[146:147], s[12:13], 0, v[142:143]
	v_mov_b32_e32 v141, v145
	v_lshl_add_u64 v[152:153], s[14:15], 0, v[142:143]
	v_lshl_add_u64 v[146:147], v[146:147], 0, v[140:141]
	v_lshl_add_u64 v[152:153], v[152:153], 0, v[140:141]
	global_load_dwordx4 v[148:151], v[146:147], off
	global_load_dwordx4 v[154:157], v[152:153], off
	global_load_dwordx4 v[170:173], v[152:153], off offset:16
	global_load_dwordx4 v[174:177], v[146:147], off offset:16
	ds_bpermute_b32 v152, v164, v124
	ds_bpermute_b32 v160, v164, v120
	ds_bpermute_b32 v153, v164, v125
	ds_bpermute_b32 v161, v164, v121
	ds_bpermute_b32 v158, v164, v126
	ds_bpermute_b32 v178, v164, v122
	ds_bpermute_b32 v159, v164, v127
	ds_bpermute_b32 v179, v164, v123
	s_waitcnt vmcnt(0) lgkmcnt(0)
	v_pk_mul_f32 v[154:155], v[154:155], v[152:153]
	v_pk_mul_f32 v[146:147], v[126:127], v[150:151]
	v_pk_mul_f32 v[150:151], v[124:125], v[148:149]
	v_pk_mul_f32 v[158:159], v[156:157], v[158:159]
	v_pk_mul_f32 v[148:149], v[170:171], v[160:161]
	v_pk_mul_f32 v[152:153], v[172:173], v[178:179]
	v_pk_mul_f32 v[156:157], v[122:123], v[176:177]
	v_pk_mul_f32 v[160:161], v[120:121], v[174:175]
	s_and_saveexec_b64 s[22:23], s[78:79]
	s_xor_b64 s[22:23], exec, s[22:23]
	v_pk_add_f32 v[126:127], v[146:147], v[158:159]
	v_pk_add_f32 v[124:125], v[150:151], v[154:155]
	v_pk_add_f32 v[122:123], v[156:157], v[152:153]
	v_pk_add_f32 v[120:121], v[160:161], v[148:149]
	s_andn2_saveexec_b64 s[22:23], s[22:23]
	v_sub_f32_e32 v127, v147, v159
	v_sub_f32_e32 v126, v146, v158
	v_sub_f32_e32 v125, v151, v155
	v_sub_f32_e32 v124, v150, v154
	v_sub_f32_e32 v123, v157, v153
	v_sub_f32_e32 v122, v156, v152
	v_sub_f32_e32 v121, v161, v149
	v_sub_f32_e32 v120, v160, v148
	s_or_b64 exec, exec, s[22:23]

; #define PG8_STAGE(bufoff, gbase, voff) do { _Pragma("unroll") for (int _i = 0; _i < 2; ++_i) \
;     __builtin_amdgcn_global_load_lds((const unsigned*)((const char*)(gbase) + (voff)[_i]), (LAS unsigned*)(lds + (bufoff) + ldsw + _i * 8192), 16, 0, 0); } while (0)
; #define PG8_LDA(dst, b, h) do { _Pragma("unroll") for (int m = 0; m < 4; ++m) _Pragma("unroll") for (int k = 0; k < 2; ++k) dst[m][k] = *(const LAS bf16x8*)(lds + PG8_SA(b, h) + aoff + m * 2048 + k * 1024); } while (0)
; #define PG8_LDB(dst, b, h) do { _Pragma("unroll") for (int n = 0; n < 2; ++n) _Pragma("unroll") for (int k = 0; k < 2; ++k) dst[n][k] = *(const LAS bf16x8*)(lds + PG8_SB(b, h) + boff + n * 2048 + k * 1024); } while (0)
; #define PG8_MMA(ai, bj, At, Bt) do { __builtin_amdgcn_s_setprio(1); _Pragma("unroll") for (int m = 0; m < 4; ++m) _Pragma("unroll") for (int n = 0; n < 2; ++n) _Pragma("unroll") for (int k = 0; k < 2; ++k) \
;     acc[ai][bj][m][n] = __builtin_amdgcn_mfma_f32_16x16x32_bf16(Bt[n][k], At[m][k], acc[ai][bj][m][n], 0, 0, 0); __builtin_amdgcn_s_setprio(0); } while (0)
; #define PG8_WAIT_V(n) asm volatile("s_waitcnt vmcnt(" #n ")" ::: "memory")
; #define PG8_WAIT_L(n) asm volatile("s_waitcnt lgkmcnt(" #n ")" ::: "memory")
; #define PG8_BAR __builtin_amdgcn_s_barrier()
; #define PG8_SCHED __builtin_amdgcn_sched_barrier(0)
; template <class Epi, class Sched>
; DI void gemm_phase(LAS unsigned char* lds, const Gemm g, const Sched& S, const Epi& E) {
;     ...
;       PG8_LDB(B0, 0, 0); PG8_SCHED; PG8_LDA(At, 0, 0); PG8_STAGE(PG8_SA(1, 1), a1 + hstep, voffA);
;       PG8_WAIT_L(8); PG8_BAR; PG8_WAIT_L(0); PG8_MMA(0, 0, At, B0); PG8_BAR; PG8_SCHED;
;       PG8_LDB(B1, 0, 1); PG8_STAGE(PG8_SB(0, 0), b2, voffB);
;       PG8_BAR; PG8_WAIT_L(0); PG8_MMA(0, 1, At, B1); PG8_BAR;
;       PG8_LDA(At, 0, 1); PG8_STAGE(PG8_SA(0, 0), a2, voffA);
;       PG8_BAR; PG8_WAIT_L(0); PG8_MMA(1, 0, At, B0); PG8_BAR; PG8_SCHED;
;       PG8_STAGE(PG8_SB(0, 1), b2 + hstep, voffB);
;       PG8_WAIT_V(6); PG8_BAR; PG8_MMA(1, 1, At, B1); PG8_BAR;
.LBB0_1346:
	s_add_u32 s48, s28, s40
	s_addc_u32 s49, s29, s41
	s_add_u32 s44, s48, 0x100
	s_addc_u32 s45, s49, 0
	s_and_b64 s[42:43], s[36:37], exec
	s_cselect_b32 s45, s15, s45
	s_cselect_b32 s44, s21, s44
	s_add_u32 s40, s22, s40
	s_addc_u32 s41, s23, s41
	s_add_u32 s40, s40, 0x100
	s_addc_u32 s41, s41, 0
	s_add_i32 s70, 0, 0x10000
	s_and_b64 s[36:37], s[36:37], exec
	s_cselect_b32 s47, s13, s41
	s_cselect_b32 s46, s24, s40
	s_add_u32 s48, s48, 0x10080
	s_addc_u32 s49, s49, 0
	s_add_i32 s74, s70, s51
	s_add_i32 m0, s56, 0xc000
	s_add_i32 s75, s56, 0xe000
	s_add_i32 s73, 0, 0x14000
	s_add_i32 s72, s74, 0x2000
	s_add_u32 s42, s46, 0x10000
	s_addc_u32 s43, s47, 0
	s_add_i32 s69, s73, s51
	ds_read_b128 v[136:139], v220
	ds_read_b128 v[146:149], v220 offset:1024
	ds_read_b128 v[150:153], v220 offset:2048
	ds_read_b128 v[154:157], v220 offset:3072
	s_add_i32 s68, s69, 0x2000
	s_add_i32 s67, 0, 0x18000
	s_add_u32 s40, s44, 0x10000
	s_addc_u32 s41, s45, 0
	s_add_i32 s66, s67, s51
	s_add_i32 s65, 0, 0x1c000
	s_add_i32 s64, s66, 0x2000
	s_add_u32 s36, s46, 0x10080
	s_addc_u32 s37, s47, 0
	s_add_i32 s71, s65, s51
	s_add_i32 s70, s71, 0x2000
	ds_read_b128 v[158:161], v143
	ds_read_b128 v[162:165], v143 offset:1024
	ds_read_b128 v[166:169], v143 offset:2048
	ds_read_b128 v[170:173], v143 offset:3072
	ds_read_b128 v[174:177], v143 offset:4096
	ds_read_b128 v[178:181], v143 offset:5120
	ds_read_b128 v[196:199], v143 offset:6144
	ds_read_b128 v[200:203], v143 offset:7168
	global_load_lds_dwordx4 v128, s[48:49]
	s_mov_b32 m0, s75
	s_nop 0
	global_load_lds_dwordx4 v132, s[48:49]
	s_waitcnt lgkmcnt(8)
	s_barrier
	s_waitcnt lgkmcnt(0)
	v_mfma_f32_16x16x32_bf16 v[124:127], v[136:139], v[158:161], v[124:127]
	v_mfma_f32_16x16x32_bf16 v[120:123], v[150:153], v[158:161], v[120:123]
	v_mfma_f32_16x16x32_bf16 v[108:111], v[136:139], v[166:169], v[108:111]
	v_mfma_f32_16x16x32_bf16 v[104:107], v[150:153], v[166:169], v[104:107]
	v_mfma_f32_16x16x32_bf16 v[92:95], v[136:139], v[174:177], v[92:95]
	v_mfma_f32_16x16x32_bf16 v[88:91], v[150:153], v[174:177], v[88:91]
	v_mfma_f32_16x16x32_bf16 v[76:79], v[136:139], v[196:199], v[76:79]
	v_mfma_f32_16x16x32_bf16 v[72:75], v[150:153], v[196:199], v[72:75]
	v_mfma_f32_16x16x32_bf16 v[124:127], v[146:149], v[162:165], v[124:127]
	v_mfma_f32_16x16x32_bf16 v[120:123], v[154:157], v[162:165], v[120:123]
	v_mfma_f32_16x16x32_bf16 v[108:111], v[146:149], v[170:173], v[108:111]
	v_mfma_f32_16x16x32_bf16 v[104:107], v[154:157], v[170:173], v[104:107]
	v_mfma_f32_16x16x32_bf16 v[92:95], v[146:149], v[178:181], v[92:95]
	v_mfma_f32_16x16x32_bf16 v[88:91], v[154:157], v[178:181], v[88:91]
	v_mfma_f32_16x16x32_bf16 v[76:79], v[146:149], v[200:203], v[76:79]
	v_mfma_f32_16x16x32_bf16 v[72:75], v[154:157], v[200:203], v[72:75]
	s_barrier
	s_mov_b32 m0, s74
	ds_read_b128 v[204:207], v221
	ds_read_b128 v[208:211], v221 offset:1024
	ds_read_b128 v[212:215], v221 offset:2048
	ds_read_b128 v[216:219], v221 offset:3072
	s_add_u32 vcc_lo, s46, s0
	s_addc_u32 vcc_hi, s47, s1
	global_load_lds_dwordx4 v130, s[46:47]
	s_mov_b32 m0, s72
	s_nop 0
	global_load_lds_dwordx4 v134, s[46:47]
	s_barrier
	s_waitcnt lgkmcnt(0)
	v_mfma_f32_16x16x32_bf16 v[116:119], v[204:207], v[158:161], v[116:119]
	v_mfma_f32_16x16x32_bf16 v[112:115], v[212:215], v[158:161], v[112:115]
	v_mfma_f32_16x16x32_bf16 v[100:103], v[204:207], v[166:169], v[100:103]
	v_mfma_f32_16x16x32_bf16 v[96:99], v[212:215], v[166:169], v[96:99]
	v_mfma_f32_16x16x32_bf16 v[84:87], v[204:207], v[174:177], v[84:87]
	v_mfma_f32_16x16x32_bf16 v[80:83], v[212:215], v[174:177], v[80:83]
	v_mfma_f32_16x16x32_bf16 v[68:71], v[204:207], v[196:199], v[68:71]
	v_mfma_f32_16x16x32_bf16 v[64:67], v[212:215], v[196:199], v[64:67]
	v_mfma_f32_16x16x32_bf16 v[116:119], v[208:211], v[162:165], v[116:119]
	v_mfma_f32_16x16x32_bf16 v[112:115], v[216:219], v[162:165], v[112:115]
	v_mfma_f32_16x16x32_bf16 v[100:103], v[208:211], v[170:173], v[100:103]
	v_mfma_f32_16x16x32_bf16 v[96:99], v[216:219], v[170:173], v[96:99]
	v_mfma_f32_16x16x32_bf16 v[84:87], v[208:211], v[178:181], v[84:87]
	v_mfma_f32_16x16x32_bf16 v[80:83], v[216:219], v[178:181], v[80:83]
	v_mfma_f32_16x16x32_bf16 v[68:71], v[208:211], v[200:203], v[68:71]
	v_mfma_f32_16x16x32_bf16 v[64:67], v[216:219], v[200:203], v[64:67]
	s_mov_b32 m0, s56
	s_add_u32 s100, s44, s0
	s_addc_u32 s101, s45, s1
	s_barrier
	ds_read_b128 v[158:161], v143 offset:16384
	ds_read_b128 v[162:165], v143 offset:17408
	ds_read_b128 v[166:169], v143 offset:18432
	ds_read_b128 v[170:173], v143 offset:19456
	ds_read_b128 v[174:177], v143 offset:20480
	ds_read_b128 v[178:181], v143 offset:21504
	ds_read_b128 v[196:199], v143 offset:22528
	ds_read_b128 v[200:203], v143 offset:23552
	global_load_lds_dwordx4 v128, s[44:45]
	s_mov_b32 m0, s57
	s_nop 0
	global_load_lds_dwordx4 v132, s[44:45]
	s_barrier
	s_waitcnt lgkmcnt(0)
	v_mfma_f32_16x16x32_bf16 v[60:63], v[136:139], v[158:161], v[60:63]
	v_mfma_f32_16x16x32_bf16 v[56:59], v[150:153], v[158:161], v[56:59]
	v_mfma_f32_16x16x32_bf16 v[44:47], v[136:139], v[166:169], v[44:47]
	v_mfma_f32_16x16x32_bf16 v[40:43], v[150:153], v[166:169], v[40:43]
	v_mfma_f32_16x16x32_bf16 v[28:31], v[136:139], v[174:177], v[28:31]
	v_mfma_f32_16x16x32_bf16 v[24:27], v[150:153], v[174:177], v[24:27]
	v_mfma_f32_16x16x32_bf16 v[12:15], v[136:139], v[196:199], v[12:15]
	v_mfma_f32_16x16x32_bf16 v[8:11], v[150:153], v[196:199], v[8:11]
	v_mfma_f32_16x16x32_bf16 v[60:63], v[146:149], v[162:165], v[60:63]
	v_mfma_f32_16x16x32_bf16 v[56:59], v[154:157], v[162:165], v[56:59]
	v_mfma_f32_16x16x32_bf16 v[44:47], v[146:149], v[170:173], v[44:47]
	v_mfma_f32_16x16x32_bf16 v[40:43], v[154:157], v[170:173], v[40:43]
	v_mfma_f32_16x16x32_bf16 v[28:31], v[146:149], v[178:181], v[28:31]
	v_mfma_f32_16x16x32_bf16 v[24:27], v[154:157], v[178:181], v[24:27]
	v_mfma_f32_16x16x32_bf16 v[12:15], v[146:149], v[200:203], v[12:15]
	v_mfma_f32_16x16x32_bf16 v[8:11], v[154:157], v[200:203], v[8:11]
	s_barrier
; #define PG8_STAGE(bufoff, gbase, voff) do { _Pragma("unroll") for (int _i = 0; _i < 2; ++_i) \
;     __builtin_amdgcn_global_load_lds((const unsigned*)((const char*)(gbase) + (voff)[_i]), (LAS unsigned*)(lds + (bufoff) + ldsw + _i * 8192), 16, 0, 0); } while (0)
; #define PG8_LDA(dst, b, h) do { _Pragma("unroll") for (int m = 0; m < 4; ++m) _Pragma("unroll") for (int k = 0; k < 2; ++k) dst[m][k] = *(const LAS bf16x8*)(lds + PG8_SA(b, h) + aoff + m * 2048 + k * 1024); } while (0)
; #define PG8_LDB(dst, b, h) do { _Pragma("unroll") for (int n = 0; n < 2; ++n) _Pragma("unroll") for (int k = 0; k < 2; ++k) dst[n][k] = *(const LAS bf16x8*)(lds + PG8_SB(b, h) + boff + n * 2048 + k * 1024); } while (0)
; #define PG8_MMA(ai, bj, At, Bt) do { __builtin_amdgcn_s_setprio(1); _Pragma("unroll") for (int m = 0; m < 4; ++m) _Pragma("unroll") for (int n = 0; n < 2; ++n) _Pragma("unroll") for (int k = 0; k < 2; ++k) \
;     acc[ai][bj][m][n] = __builtin_amdgcn_mfma_f32_16x16x32_bf16(Bt[n][k], At[m][k], acc[ai][bj][m][n], 0, 0, 0); __builtin_amdgcn_s_setprio(0); } while (0)
; #define PG8_WAIT_V(n) asm volatile("s_waitcnt vmcnt(" #n ")" ::: "memory")
; #define PG8_WAIT_L(n) asm volatile("s_waitcnt lgkmcnt(" #n ")" ::: "memory")
; #define PG8_BAR __builtin_amdgcn_s_barrier()
; #define PG8_SCHED __builtin_amdgcn_sched_barrier(0)
; template <class Epi, class Sched>
; DI void gemm_phase(LAS unsigned char* lds, const Gemm g, const Sched& S, const Epi& E) {
;     ...
;       PG8_WAIT_V(6); PG8_BAR; PG8_MMA(1, 1, At, B1); PG8_BAR;
;       PG8_LDB(B0, 1, 0); PG8_SCHED; PG8_LDA(At, 1, 0); PG8_STAGE(PG8_SA(0, 1), a2 + hstep, voffA);
;       PG8_WAIT_L(8); PG8_BAR; PG8_WAIT_L(0); PG8_MMA(0, 0, At, B0); PG8_BAR; PG8_SCHED;
;       PG8_LDB(B1, 1, 1); PG8_STAGE(PG8_SB(1, 0), b3, voffB);
;       PG8_BAR; PG8_WAIT_L(0); PG8_MMA(0, 1, At, B1); PG8_BAR;
;       PG8_LDA(At, 1, 1); PG8_STAGE(PG8_SA(1, 0), a3, voffA);
;       PG8_BAR; PG8_WAIT_L(0); PG8_MMA(1, 0, At, B0); PG8_BAR; PG8_SCHED;
	s_mov_b32 m0, s69
	s_nop 0
	global_load_lds_dwordx4 v130, s[42:43]
	s_mov_b32 m0, s68
	s_nop 0
	global_load_lds_dwordx4 v134, s[42:43]
	s_waitcnt vmcnt(6)
	s_barrier
	v_mfma_f32_16x16x32_bf16 v[52:55], v[204:207], v[158:161], v[52:55]
	v_mfma_f32_16x16x32_bf16 v[48:51], v[212:215], v[158:161], v[48:51]
	v_mfma_f32_16x16x32_bf16 v[36:39], v[204:207], v[166:169], v[36:39]
	v_mfma_f32_16x16x32_bf16 v[32:35], v[212:215], v[166:169], v[32:35]
	v_mfma_f32_16x16x32_bf16 v[20:23], v[204:207], v[174:177], v[20:23]
	v_mfma_f32_16x16x32_bf16 v[16:19], v[212:215], v[174:177], v[16:19]
	v_mfma_f32_16x16x32_bf16 v[4:7], v[204:207], v[196:199], v[4:7]
	v_mfma_f32_16x16x32_bf16 v[0:3], v[212:215], v[196:199], v[0:3]
	v_mfma_f32_16x16x32_bf16 v[52:55], v[208:211], v[162:165], v[52:55]
	v_mfma_f32_16x16x32_bf16 v[48:51], v[216:219], v[162:165], v[48:51]
	v_mfma_f32_16x16x32_bf16 v[36:39], v[208:211], v[170:173], v[36:39]
	v_mfma_f32_16x16x32_bf16 v[32:35], v[216:219], v[170:173], v[32:35]
	v_mfma_f32_16x16x32_bf16 v[20:23], v[208:211], v[178:181], v[20:23]
	v_mfma_f32_16x16x32_bf16 v[16:19], v[216:219], v[178:181], v[16:19]
	v_mfma_f32_16x16x32_bf16 v[4:7], v[208:211], v[200:203], v[4:7]
	v_mfma_f32_16x16x32_bf16 v[0:3], v[216:219], v[200:203], v[0:3]
	s_barrier
	ds_read_b128 v[136:139], v222
	ds_read_b128 v[146:149], v222 offset:1024
	ds_read_b128 v[150:153], v222 offset:2048
	ds_read_b128 v[154:157], v222 offset:3072
	s_mov_b32 m0, s58
	ds_read_b128 v[158:161], v143 offset:32768
	ds_read_b128 v[162:165], v143 offset:33792
	ds_read_b128 v[166:169], v143 offset:34816
	ds_read_b128 v[170:173], v143 offset:35840
	ds_read_b128 v[174:177], v143 offset:36864
	ds_read_b128 v[178:181], v143 offset:37888
	ds_read_b128 v[196:199], v143 offset:38912
	ds_read_b128 v[200:203], v143 offset:39936
	global_load_lds_dwordx4 v128, s[40:41]
	s_mov_b32 m0, s59
	s_nop 0
	global_load_lds_dwordx4 v132, s[40:41]
	s_waitcnt lgkmcnt(8)
	s_barrier
	s_waitcnt lgkmcnt(0)
	v_mfma_f32_16x16x32_bf16 v[124:127], v[136:139], v[158:161], v[124:127]
	v_mfma_f32_16x16x32_bf16 v[120:123], v[150:153], v[158:161], v[120:123]
	v_mfma_f32_16x16x32_bf16 v[108:111], v[136:139], v[166:169], v[108:111]
	v_mfma_f32_16x16x32_bf16 v[104:107], v[150:153], v[166:169], v[104:107]
	v_mfma_f32_16x16x32_bf16 v[92:95], v[136:139], v[174:177], v[92:95]
	v_mfma_f32_16x16x32_bf16 v[88:91], v[150:153], v[174:177], v[88:91]
	v_mfma_f32_16x16x32_bf16 v[76:79], v[136:139], v[196:199], v[76:79]
	v_mfma_f32_16x16x32_bf16 v[72:75], v[150:153], v[196:199], v[72:75]
	v_mfma_f32_16x16x32_bf16 v[124:127], v[146:149], v[162:165], v[124:127]
	v_mfma_f32_16x16x32_bf16 v[120:123], v[154:157], v[162:165], v[120:123]
	v_mfma_f32_16x16x32_bf16 v[108:111], v[146:149], v[170:173], v[108:111]
	v_mfma_f32_16x16x32_bf16 v[104:107], v[154:157], v[170:173], v[104:107]
	v_mfma_f32_16x16x32_bf16 v[92:95], v[146:149], v[178:181], v[92:95]
	v_mfma_f32_16x16x32_bf16 v[88:91], v[154:157], v[178:181], v[88:91]
	v_mfma_f32_16x16x32_bf16 v[76:79], v[146:149], v[200:203], v[76:79]
	v_mfma_f32_16x16x32_bf16 v[72:75], v[154:157], v[200:203], v[72:75]
	s_barrier
	s_mov_b32 m0, s66
	ds_read_b128 v[204:207], v223
	ds_read_b128 v[208:211], v223 offset:1024
	ds_read_b128 v[212:215], v223 offset:2048
	ds_read_b128 v[216:219], v223 offset:3072
	global_load_lds_dwordx4 v130, vcc
	s_mov_b32 m0, s64
	s_nop 0
	global_load_lds_dwordx4 v134, vcc
	s_barrier
	s_waitcnt lgkmcnt(0)
	v_mfma_f32_16x16x32_bf16 v[116:119], v[204:207], v[158:161], v[116:119]
	v_mfma_f32_16x16x32_bf16 v[112:115], v[212:215], v[158:161], v[112:115]
	v_mfma_f32_16x16x32_bf16 v[100:103], v[204:207], v[166:169], v[100:103]
	v_mfma_f32_16x16x32_bf16 v[96:99], v[212:215], v[166:169], v[96:99]
	v_mfma_f32_16x16x32_bf16 v[84:87], v[204:207], v[174:177], v[84:87]
	v_mfma_f32_16x16x32_bf16 v[80:83], v[212:215], v[174:177], v[80:83]
	v_mfma_f32_16x16x32_bf16 v[68:71], v[204:207], v[196:199], v[68:71]
	v_mfma_f32_16x16x32_bf16 v[64:67], v[212:215], v[196:199], v[64:67]
	v_mfma_f32_16x16x32_bf16 v[116:119], v[208:211], v[162:165], v[116:119]
	v_mfma_f32_16x16x32_bf16 v[112:115], v[216:219], v[162:165], v[112:115]
	v_mfma_f32_16x16x32_bf16 v[100:103], v[208:211], v[170:173], v[100:103]
	v_mfma_f32_16x16x32_bf16 v[96:99], v[216:219], v[170:173], v[96:99]
	v_mfma_f32_16x16x32_bf16 v[84:87], v[208:211], v[178:181], v[84:87]
	v_mfma_f32_16x16x32_bf16 v[80:83], v[216:219], v[178:181], v[80:83]
	v_mfma_f32_16x16x32_bf16 v[68:71], v[208:211], v[200:203], v[68:71]
	v_mfma_f32_16x16x32_bf16 v[64:67], v[216:219], v[200:203], v[64:67]
	s_mov_b32 m0, s62
	s_barrier
; #define PG8_STAGE(bufoff, gbase, voff) do { _Pragma("unroll") for (int _i = 0; _i < 2; ++_i) \
;     __builtin_amdgcn_global_load_lds((const unsigned*)((const char*)(gbase) + (voff)[_i]), (LAS unsigned*)(lds + (bufoff) + ldsw + _i * 8192), 16, 0, 0); } while (0)
; #define PG8_MMA(ai, bj, At, Bt) do { __builtin_amdgcn_s_setprio(1); _Pragma("unroll") for (int m = 0; m < 4; ++m) _Pragma("unroll") for (int n = 0; n < 2; ++n) _Pragma("unroll") for (int k = 0; k < 2; ++k) \
;     acc[ai][bj][m][n] = __builtin_amdgcn_mfma_f32_16x16x32_bf16(Bt[n][k], At[m][k], acc[ai][bj][m][n], 0, 0, 0); __builtin_amdgcn_s_setprio(0); } while (0)
; #define PG8_WAIT_V(n) asm volatile("s_waitcnt vmcnt(" #n ")" ::: "memory")
; #define PG8_WAIT_L(n) asm volatile("s_waitcnt lgkmcnt(" #n ")" ::: "memory")
; #define PG8_BAR __builtin_amdgcn_s_barrier()
; #define PG8_SCHED __builtin_amdgcn_sched_barrier(0)
; template <class Epi, class Sched>
; DI void gemm_phase(LAS unsigned char* lds, const Gemm g, const Sched& S, const Epi& E) {
;     ...
;       PG8_BAR; PG8_WAIT_L(0); PG8_MMA(1, 0, At, B0); PG8_BAR; PG8_SCHED;
;       PG8_STAGE(PG8_SB(1, 1), b3 + hstep, voffB);
;       PG8_WAIT_V(6); PG8_BAR; PG8_MMA(1, 1, At, B1); PG8_BAR;
;     }
;   DI void operator()(const f32x4 (&acc)[2][2][4][2], const pg8::Unit& u, int wr, int wc, int fr_, int fq_) const {
;     ...
;             } else if (EPI == EPI_UKV) {
;               if (n == 0) {
;                 const int gb = u.pn * 256 + bj * 128 + wc * 32;
;                 const int hd = gb >> 7, within = (gb & 127) + 8 * fq;
;                 const f32x4 v1 = acc[ai][bj][m][1];
;                 if (within < 64) st_bf8((u16*)(big + E_KNOPE) + (size_t)token * 512 + hd * 64 + within, v, v1, rinv);
;                 else st_bf8((u16*)(big + E_VMLAT) + (size_t)token * 512 + hd * 64 + (within - 64), v, v1, rinv);
;               }
	ds_read_b128 v[158:161], v143 offset:49152
	ds_read_b128 v[162:165], v143 offset:50176
	ds_read_b128 v[166:169], v143 offset:51200
	ds_read_b128 v[170:173], v143 offset:52224
	ds_read_b128 v[174:177], v143 offset:53248
	ds_read_b128 v[178:181], v143 offset:54272
	ds_read_b128 v[196:199], v143 offset:55296
	ds_read_b128 v[200:203], v143 offset:56320
	global_load_lds_dwordx4 v128, s[100:101]
	s_mov_b32 m0, s63
	s_nop 0
	global_load_lds_dwordx4 v132, s[100:101]
	s_barrier
	s_waitcnt lgkmcnt(0)
	v_mfma_f32_16x16x32_bf16 v[60:63], v[136:139], v[158:161], v[60:63]
	v_mfma_f32_16x16x32_bf16 v[56:59], v[150:153], v[158:161], v[56:59]
	v_mfma_f32_16x16x32_bf16 v[44:47], v[136:139], v[166:169], v[44:47]
	v_mfma_f32_16x16x32_bf16 v[40:43], v[150:153], v[166:169], v[40:43]
	v_mfma_f32_16x16x32_bf16 v[28:31], v[136:139], v[174:177], v[28:31]
	v_mfma_f32_16x16x32_bf16 v[24:27], v[150:153], v[174:177], v[24:27]
	v_mfma_f32_16x16x32_bf16 v[12:15], v[136:139], v[196:199], v[12:15]
	v_mfma_f32_16x16x32_bf16 v[8:11], v[150:153], v[196:199], v[8:11]
	v_mfma_f32_16x16x32_bf16 v[60:63], v[146:149], v[162:165], v[60:63]
	v_mfma_f32_16x16x32_bf16 v[56:59], v[154:157], v[162:165], v[56:59]
	v_mfma_f32_16x16x32_bf16 v[44:47], v[146:149], v[170:173], v[44:47]
	v_mfma_f32_16x16x32_bf16 v[40:43], v[154:157], v[170:173], v[40:43]
	v_mfma_f32_16x16x32_bf16 v[28:31], v[146:149], v[178:181], v[28:31]
	v_mfma_f32_16x16x32_bf16 v[24:27], v[154:157], v[178:181], v[24:27]
	v_mfma_f32_16x16x32_bf16 v[12:15], v[146:149], v[200:203], v[12:15]
	v_mfma_f32_16x16x32_bf16 v[8:11], v[154:157], v[200:203], v[8:11]
	s_barrier
	s_mov_b32 m0, s71
	s_nop 0
	global_load_lds_dwordx4 v130, s[36:37]
	s_mov_b32 m0, s70
	s_nop 0
	global_load_lds_dwordx4 v134, s[36:37]
	s_waitcnt vmcnt(6)
	s_barrier
	v_mfma_f32_16x16x32_bf16 v[52:55], v[204:207], v[158:161], v[52:55]
	v_mfma_f32_16x16x32_bf16 v[48:51], v[212:215], v[158:161], v[48:51]
	v_mfma_f32_16x16x32_bf16 v[36:39], v[204:207], v[166:169], v[36:39]
	v_mfma_f32_16x16x32_bf16 v[32:35], v[212:215], v[166:169], v[32:35]
	v_mfma_f32_16x16x32_bf16 v[20:23], v[204:207], v[174:177], v[20:23]
	v_mfma_f32_16x16x32_bf16 v[16:19], v[212:215], v[174:177], v[16:19]
	v_mfma_f32_16x16x32_bf16 v[4:7], v[204:207], v[196:199], v[4:7]
	v_mfma_f32_16x16x32_bf16 v[0:3], v[212:215], v[196:199], v[0:3]
	v_mfma_f32_16x16x32_bf16 v[52:55], v[208:211], v[162:165], v[52:55]
	v_mfma_f32_16x16x32_bf16 v[48:51], v[216:219], v[162:165], v[48:51]
	v_mfma_f32_16x16x32_bf16 v[36:39], v[208:211], v[170:173], v[36:39]
	v_mfma_f32_16x16x32_bf16 v[32:35], v[216:219], v[170:173], v[32:35]
	v_mfma_f32_16x16x32_bf16 v[20:23], v[208:211], v[178:181], v[20:23]
	v_mfma_f32_16x16x32_bf16 v[16:19], v[216:219], v[178:181], v[16:19]
	v_mfma_f32_16x16x32_bf16 v[4:7], v[208:211], v[200:203], v[4:7]
	v_mfma_f32_16x16x32_bf16 v[0:3], v[216:219], v[200:203], v[0:3]
	s_andn2_b64 vcc, exec, s[34:35]
	s_mov_b64 s[36:37], -1
	s_mov_b64 s[34:35], 0
	s_mov_b64 s[40:41], 0x100
	s_barrier
	s_cbranch_vccz .LBB0_1346
	v_mov_b32_e32 v136, v182
	s_lshl_b32 s3, s3, 10
	s_add_i32 s3, s3, 0
	v_and_or_b32 v147, v136, 15, s60
	v_lshl_add_u32 v137, v147, 2, s3
	v_add_u32_e32 v146, 0x20000, v137
	ds_read_b32 v138, v146
	s_lshl_b32 s13, s20, 8
	v_lshrrev_b32_e32 v136, 1, v136
	v_and_or_b32 v139, v136, 24, s61
	v_add_u32_e32 v136, s13, v147
	v_ashrrev_i32_e32 v137, 31, v136
	s_waitcnt lgkmcnt(0)
	v_pk_mul_f32 v[124:125], v[124:125], v[138:139] op_sel_hi:[1,0]
	v_pk_mul_f32 v[126:127], v[126:127], v[138:139] op_sel_hi:[1,0]
	v_pk_mul_f32 v[120:121], v[120:121], v[138:139] op_sel_hi:[1,0]
	v_lshlrev_b64 v[140:141], 10, v[136:137]
	s_lshl_b32 s20, s2, 7
	v_cvt_pk_bf16_f32 v124, v124, v125
	v_cvt_pk_bf16_f32 v125, v126, v127
	v_cvt_pk_bf16_f32 v126, v120, v121
	v_pk_mul_f32 v[120:121], v[122:123], v[138:139] op_sel_hi:[1,0]
	s_ashr_i32 s21, s20, 31
	v_cvt_pk_bf16_f32 v127, v120, v121
	v_lshl_add_u64 v[120:121], s[6:7], 0, v[140:141]
	s_mov_b64 s[2:3], -1
	s_and_b64 vcc, exec, s[4:5]
	v_lshl_add_u64 v[120:121], s[20:21], 1, v[120:121]
	v_lshlrev_b32_e32 v144, 1, v139
	s_cbranch_vccz .LBB0_1349
	v_lshl_add_u64 v[122:123], v[120:121], 0, v[144:145]
	v_add_co_u32_e32 v122, vcc, 0xd9ff000, v122
	s_mov_b64 s[2:3], 0
	s_nop 0
	v_addc_co_u32_e32 v123, vcc, 0, v123, vcc
	global_store_dwordx4 v[122:123], v[124:127], off offset:3968

; #define PG8_STAGE(bufoff, gbase, voff) do { _Pragma("unroll") for (int _i = 0; _i < 2; ++_i) \
;     __builtin_amdgcn_global_load_lds((const unsigned*)((const char*)(gbase) + (voff)[_i]), (LAS unsigned*)(lds + (bufoff) + ldsw + _i * 8192), 16, 0, 0); } while (0)
; #define PG8_LDA(dst, b, h) do { _Pragma("unroll") for (int m = 0; m < 4; ++m) _Pragma("unroll") for (int k = 0; k < 2; ++k) dst[m][k] = *(const LAS bf16x8*)(lds + PG8_SA(b, h) + aoff + m * 2048 + k * 1024); } while (0)
; #define PG8_LDB(dst, b, h) do { _Pragma("unroll") for (int n = 0; n < 2; ++n) _Pragma("unroll") for (int k = 0; k < 2; ++k) dst[n][k] = *(const LAS bf16x8*)(lds + PG8_SB(b, h) + boff + n * 2048 + k * 1024); } while (0)
; #define PG8_MMA(ai, bj, At, Bt) do { __builtin_amdgcn_s_setprio(1); _Pragma("unroll") for (int m = 0; m < 4; ++m) _Pragma("unroll") for (int n = 0; n < 2; ++n) _Pragma("unroll") for (int k = 0; k < 2; ++k) \
;     acc[ai][bj][m][n] = __builtin_amdgcn_mfma_f32_16x16x32_bf16(Bt[n][k], At[m][k], acc[ai][bj][m][n], 0, 0, 0); __builtin_amdgcn_s_setprio(0); } while (0)
; #define PG8_WAIT_V(n) asm volatile("s_waitcnt vmcnt(" #n ")" ::: "memory")
; #define PG8_WAIT_L(n) asm volatile("s_waitcnt lgkmcnt(" #n ")" ::: "memory")
; #define PG8_BAR __builtin_amdgcn_s_barrier()
; #define PG8_SCHED __builtin_amdgcn_sched_barrier(0)
; template <class Epi, class Sched>
; DI void gemm_phase(LAS unsigned char* lds, const Gemm g, const Sched& S, const Epi& E) {
;     ...
;       PG8_LDB(B0, 0, 0); PG8_SCHED; PG8_LDA(At, 0, 0); PG8_STAGE(PG8_SA(1, 1), a1 + hstep, voffA);
;       PG8_WAIT_L(8); PG8_BAR; PG8_WAIT_L(0); PG8_MMA(0, 0, At, B0); PG8_BAR; PG8_SCHED;
;       PG8_LDB(B1, 0, 1); PG8_STAGE(PG8_SB(0, 0), b2, voffB);
;       PG8_BAR; PG8_WAIT_L(0); PG8_MMA(0, 1, At, B1); PG8_BAR;
;       PG8_LDA(At, 0, 1); PG8_STAGE(PG8_SA(0, 0), a2, voffA);
;       PG8_BAR; PG8_WAIT_L(0); PG8_MMA(1, 0, At, B0); PG8_BAR; PG8_SCHED;
;       PG8_STAGE(PG8_SB(0, 1), b2 + hstep, voffB);
;       PG8_WAIT_V(6); PG8_BAR; PG8_MMA(1, 1, At, B1); PG8_BAR;
.LBB0_1644:
	s_add_u32 s4, s2, 0xfffc0080
	s_addc_u32 s5, s3, -1
	s_add_i32 s55, 0, 0x10000
	ds_read_b128 v[128:131], v224
	ds_read_b128 v[132:135], v224 offset:1024
	ds_read_b128 v[148:151], v224 offset:2048
	ds_read_b128 v[152:155], v224 offset:3072
	s_cmp_eq_u32 s54, 12
	s_cselect_b32 s29, s19, s5
	s_cselect_b32 s28, s35, s4
	s_cselect_b32 s5, s17, s53
	s_cselect_b32 s4, s51, s52
	s_add_i32 m0, s41, 0xc000
	ds_read_b128 v[160:163], v159
	ds_read_b128 v[164:167], v159 offset:1024
	ds_read_b128 v[168:171], v159 offset:2048
	ds_read_b128 v[172:175], v159 offset:3072
	ds_read_b128 v[176:179], v159 offset:4096
	ds_read_b128 v[196:199], v159 offset:5120
	ds_read_b128 v[200:203], v159 offset:6144
	ds_read_b128 v[204:207], v159 offset:7168
	global_load_lds_dwordx4 v142, s[2:3]
	s_add_i32 m0, s41, 0xe000
	s_nop 0
	global_load_lds_dwordx4 v146, s[2:3]
	s_waitcnt lgkmcnt(8)
	s_barrier
	s_waitcnt lgkmcnt(0)
	v_mfma_f32_16x16x32_bf16 v[124:127], v[128:131], v[160:163], v[124:127]
	v_mfma_f32_16x16x32_bf16 v[120:123], v[148:151], v[160:163], v[120:123]
	v_mfma_f32_16x16x32_bf16 v[108:111], v[128:131], v[168:171], v[108:111]
	v_mfma_f32_16x16x32_bf16 v[104:107], v[148:151], v[168:171], v[104:107]
	v_mfma_f32_16x16x32_bf16 v[92:95], v[128:131], v[176:179], v[92:95]
	v_mfma_f32_16x16x32_bf16 v[88:91], v[148:151], v[176:179], v[88:91]
	v_mfma_f32_16x16x32_bf16 v[76:79], v[128:131], v[200:203], v[76:79]
	v_mfma_f32_16x16x32_bf16 v[72:75], v[148:151], v[200:203], v[72:75]
	v_mfma_f32_16x16x32_bf16 v[124:127], v[132:135], v[164:167], v[124:127]
	v_mfma_f32_16x16x32_bf16 v[120:123], v[152:155], v[164:167], v[120:123]
	v_mfma_f32_16x16x32_bf16 v[108:111], v[132:135], v[172:175], v[108:111]
	v_mfma_f32_16x16x32_bf16 v[104:107], v[152:155], v[172:175], v[104:107]
	v_mfma_f32_16x16x32_bf16 v[92:95], v[132:135], v[196:199], v[92:95]
	v_mfma_f32_16x16x32_bf16 v[88:91], v[152:155], v[196:199], v[88:91]
	v_mfma_f32_16x16x32_bf16 v[76:79], v[132:135], v[204:207], v[76:79]
	v_mfma_f32_16x16x32_bf16 v[72:75], v[152:155], v[204:207], v[72:75]
	s_barrier
	s_add_i32 s58, 0, 0x14000
	s_add_i32 s55, s55, s40
	ds_read_b128 v[208:211], v225
	ds_read_b128 v[212:215], v225 offset:1024
	ds_read_b128 v[216:219], v225 offset:2048
	ds_read_b128 v[220:223], v225 offset:3072
	s_add_u32 vcc_lo, s4, s0
	s_addc_u32 vcc_hi, s5, s1
	s_mov_b32 m0, s55
	s_nop 0
	global_load_lds_dwordx4 v144, s[4:5]
	s_add_i32 m0, s55, 0x2000
	s_nop 0
	global_load_lds_dwordx4 v136, s[4:5]
	s_barrier
	s_waitcnt lgkmcnt(0)
	v_mfma_f32_16x16x32_bf16 v[116:119], v[208:211], v[160:163], v[116:119]
	v_mfma_f32_16x16x32_bf16 v[112:115], v[216:219], v[160:163], v[112:115]
	v_mfma_f32_16x16x32_bf16 v[100:103], v[208:211], v[168:171], v[100:103]
	v_mfma_f32_16x16x32_bf16 v[96:99], v[216:219], v[168:171], v[96:99]
	v_mfma_f32_16x16x32_bf16 v[84:87], v[208:211], v[176:179], v[84:87]
	v_mfma_f32_16x16x32_bf16 v[80:83], v[216:219], v[176:179], v[80:83]
	v_mfma_f32_16x16x32_bf16 v[68:71], v[208:211], v[200:203], v[68:71]
	v_mfma_f32_16x16x32_bf16 v[64:67], v[216:219], v[200:203], v[64:67]
	v_mfma_f32_16x16x32_bf16 v[116:119], v[212:215], v[164:167], v[116:119]
	v_mfma_f32_16x16x32_bf16 v[112:115], v[220:223], v[164:167], v[112:115]
	v_mfma_f32_16x16x32_bf16 v[100:103], v[212:215], v[172:175], v[100:103]
	v_mfma_f32_16x16x32_bf16 v[96:99], v[220:223], v[172:175], v[96:99]
	v_mfma_f32_16x16x32_bf16 v[84:87], v[212:215], v[196:199], v[84:87]
	v_mfma_f32_16x16x32_bf16 v[80:83], v[220:223], v[196:199], v[80:83]
	v_mfma_f32_16x16x32_bf16 v[68:71], v[212:215], v[204:207], v[68:71]
	v_mfma_f32_16x16x32_bf16 v[64:67], v[220:223], v[204:207], v[64:67]
	s_mov_b32 m0, s41
	s_add_u32 s100, s28, s0
	s_addc_u32 s101, s29, s1
	s_barrier
	ds_read_b128 v[160:163], v159 offset:16384
	ds_read_b128 v[164:167], v159 offset:17408
	ds_read_b128 v[168:171], v159 offset:18432
	ds_read_b128 v[172:175], v159 offset:19456
	ds_read_b128 v[176:179], v159 offset:20480
	ds_read_b128 v[196:199], v159 offset:21504
	ds_read_b128 v[200:203], v159 offset:22528
	ds_read_b128 v[204:207], v159 offset:23552
	global_load_lds_dwordx4 v140, s[28:29]
	s_mov_b32 m0, s42
	s_nop 0
	global_load_lds_dwordx4 v138, s[28:29]
	s_barrier
	s_waitcnt lgkmcnt(0)
	v_mfma_f32_16x16x32_bf16 v[60:63], v[128:131], v[160:163], v[60:63]
	v_mfma_f32_16x16x32_bf16 v[56:59], v[148:151], v[160:163], v[56:59]
	v_mfma_f32_16x16x32_bf16 v[44:47], v[128:131], v[168:171], v[44:47]
	v_mfma_f32_16x16x32_bf16 v[40:43], v[148:151], v[168:171], v[40:43]
	v_mfma_f32_16x16x32_bf16 v[28:31], v[128:131], v[176:179], v[28:31]
	v_mfma_f32_16x16x32_bf16 v[24:27], v[148:151], v[176:179], v[24:27]
	v_mfma_f32_16x16x32_bf16 v[12:15], v[128:131], v[200:203], v[12:15]
	v_mfma_f32_16x16x32_bf16 v[8:11], v[148:151], v[200:203], v[8:11]
	v_mfma_f32_16x16x32_bf16 v[60:63], v[132:135], v[164:167], v[60:63]
	v_mfma_f32_16x16x32_bf16 v[56:59], v[152:155], v[164:167], v[56:59]
	v_mfma_f32_16x16x32_bf16 v[44:47], v[132:135], v[172:175], v[44:47]
	v_mfma_f32_16x16x32_bf16 v[40:43], v[152:155], v[172:175], v[40:43]
	v_mfma_f32_16x16x32_bf16 v[28:31], v[132:135], v[196:199], v[28:31]
	v_mfma_f32_16x16x32_bf16 v[24:27], v[152:155], v[196:199], v[24:27]
	v_mfma_f32_16x16x32_bf16 v[12:15], v[132:135], v[204:207], v[12:15]
	v_mfma_f32_16x16x32_bf16 v[8:11], v[152:155], v[204:207], v[8:11]
	s_barrier
	s_add_u32 s56, s4, 0x40000
	s_addc_u32 s57, s5, 0
	s_add_i32 s55, s58, s40
	s_mov_b32 m0, s55
	s_nop 0
	global_load_lds_dwordx4 v144, s[56:57]
	s_add_i32 m0, s55, 0x2000
	s_nop 0
	global_load_lds_dwordx4 v136, s[56:57]
	s_waitcnt vmcnt(6)
	s_barrier
; #define PG8_STAGE(bufoff, gbase, voff) do { _Pragma("unroll") for (int _i = 0; _i < 2; ++_i) \
;     __builtin_amdgcn_global_load_lds((const unsigned*)((const char*)(gbase) + (voff)[_i]), (LAS unsigned*)(lds + (bufoff) + ldsw + _i * 8192), 16, 0, 0); } while (0)
; #define PG8_LDA(dst, b, h) do { _Pragma("unroll") for (int m = 0; m < 4; ++m) _Pragma("unroll") for (int k = 0; k < 2; ++k) dst[m][k] = *(const LAS bf16x8*)(lds + PG8_SA(b, h) + aoff + m * 2048 + k * 1024); } while (0)
; #define PG8_LDB(dst, b, h) do { _Pragma("unroll") for (int n = 0; n < 2; ++n) _Pragma("unroll") for (int k = 0; k < 2; ++k) dst[n][k] = *(const LAS bf16x8*)(lds + PG8_SB(b, h) + boff + n * 2048 + k * 1024); } while (0)
; #define PG8_MMA(ai, bj, At, Bt) do { __builtin_amdgcn_s_setprio(1); _Pragma("unroll") for (int m = 0; m < 4; ++m) _Pragma("unroll") for (int n = 0; n < 2; ++n) _Pragma("unroll") for (int k = 0; k < 2; ++k) \
;     acc[ai][bj][m][n] = __builtin_amdgcn_mfma_f32_16x16x32_bf16(Bt[n][k], At[m][k], acc[ai][bj][m][n], 0, 0, 0); __builtin_amdgcn_s_setprio(0); } while (0)
; #define PG8_WAIT_V(n) asm volatile("s_waitcnt vmcnt(" #n ")" ::: "memory")
; #define PG8_WAIT_L(n) asm volatile("s_waitcnt lgkmcnt(" #n ")" ::: "memory")
; #define PG8_BAR __builtin_amdgcn_s_barrier()
; #define PG8_SCHED __builtin_amdgcn_sched_barrier(0)
; template <class Epi, class Sched>
; DI void gemm_phase(LAS unsigned char* lds, const Gemm g, const Sched& S, const Epi& E) {
;     ...
;       PG8_WAIT_V(6); PG8_BAR; PG8_MMA(1, 1, At, B1); PG8_BAR;
;       PG8_LDB(B0, 1, 0); PG8_SCHED; PG8_LDA(At, 1, 0); PG8_STAGE(PG8_SA(0, 1), a2 + hstep, voffA);
;       PG8_WAIT_L(8); PG8_BAR; PG8_WAIT_L(0); PG8_MMA(0, 0, At, B0); PG8_BAR; PG8_SCHED;
;       PG8_LDB(B1, 1, 1); PG8_STAGE(PG8_SB(1, 0), b3, voffB);
;       PG8_BAR; PG8_WAIT_L(0); PG8_MMA(0, 1, At, B1); PG8_BAR;
;       PG8_LDA(At, 1, 1); PG8_STAGE(PG8_SA(1, 0), a3, voffA);
;       PG8_BAR; PG8_WAIT_L(0); PG8_MMA(1, 0, At, B0); PG8_BAR; PG8_SCHED;
	v_mfma_f32_16x16x32_bf16 v[52:55], v[208:211], v[160:163], v[52:55]
	v_mfma_f32_16x16x32_bf16 v[48:51], v[216:219], v[160:163], v[48:51]
	v_mfma_f32_16x16x32_bf16 v[36:39], v[208:211], v[168:171], v[36:39]
	v_mfma_f32_16x16x32_bf16 v[32:35], v[216:219], v[168:171], v[32:35]
	v_mfma_f32_16x16x32_bf16 v[20:23], v[208:211], v[176:179], v[20:23]
	v_mfma_f32_16x16x32_bf16 v[16:19], v[216:219], v[176:179], v[16:19]
	v_mfma_f32_16x16x32_bf16 v[4:7], v[208:211], v[200:203], v[4:7]
	v_mfma_f32_16x16x32_bf16 v[0:3], v[216:219], v[200:203], v[0:3]
	v_mfma_f32_16x16x32_bf16 v[52:55], v[212:215], v[164:167], v[52:55]
	v_mfma_f32_16x16x32_bf16 v[48:51], v[220:223], v[164:167], v[48:51]
	v_mfma_f32_16x16x32_bf16 v[36:39], v[212:215], v[172:175], v[36:39]
	v_mfma_f32_16x16x32_bf16 v[32:35], v[220:223], v[172:175], v[32:35]
	v_mfma_f32_16x16x32_bf16 v[20:23], v[212:215], v[196:199], v[20:23]
	v_mfma_f32_16x16x32_bf16 v[16:19], v[220:223], v[196:199], v[16:19]
	v_mfma_f32_16x16x32_bf16 v[4:7], v[212:215], v[204:207], v[4:7]
	v_mfma_f32_16x16x32_bf16 v[0:3], v[220:223], v[204:207], v[0:3]
	s_add_i32 s55, 0, 0x18000
	s_barrier
	ds_read_b128 v[128:131], v226
	ds_read_b128 v[132:135], v226 offset:1024
	ds_read_b128 v[148:151], v226 offset:2048
	ds_read_b128 v[152:155], v226 offset:3072
	s_add_u32 s28, s28, 0x40000
	s_addc_u32 s29, s29, 0
	s_mov_b32 m0, s43
	ds_read_b128 v[160:163], v159 offset:32768
	ds_read_b128 v[164:167], v159 offset:33792
	ds_read_b128 v[168:171], v159 offset:34816
	ds_read_b128 v[172:175], v159 offset:35840
	ds_read_b128 v[176:179], v159 offset:36864
	ds_read_b128 v[196:199], v159 offset:37888
	ds_read_b128 v[200:203], v159 offset:38912
	ds_read_b128 v[204:207], v159 offset:39936
	global_load_lds_dwordx4 v140, s[28:29]
	s_mov_b32 m0, s44
	s_nop 0
	global_load_lds_dwordx4 v138, s[28:29]
	s_waitcnt lgkmcnt(8)
	s_barrier
	s_waitcnt lgkmcnt(0)
	v_mfma_f32_16x16x32_bf16 v[124:127], v[128:131], v[160:163], v[124:127]
	v_mfma_f32_16x16x32_bf16 v[120:123], v[148:151], v[160:163], v[120:123]
	v_mfma_f32_16x16x32_bf16 v[108:111], v[128:131], v[168:171], v[108:111]
	v_mfma_f32_16x16x32_bf16 v[104:107], v[148:151], v[168:171], v[104:107]
	v_mfma_f32_16x16x32_bf16 v[92:95], v[128:131], v[176:179], v[92:95]
	v_mfma_f32_16x16x32_bf16 v[88:91], v[148:151], v[176:179], v[88:91]
	v_mfma_f32_16x16x32_bf16 v[76:79], v[128:131], v[200:203], v[76:79]
	v_mfma_f32_16x16x32_bf16 v[72:75], v[148:151], v[200:203], v[72:75]
	v_mfma_f32_16x16x32_bf16 v[124:127], v[132:135], v[164:167], v[124:127]
	v_mfma_f32_16x16x32_bf16 v[120:123], v[152:155], v[164:167], v[120:123]
	v_mfma_f32_16x16x32_bf16 v[108:111], v[132:135], v[172:175], v[108:111]
	v_mfma_f32_16x16x32_bf16 v[104:107], v[152:155], v[172:175], v[104:107]
	v_mfma_f32_16x16x32_bf16 v[92:95], v[132:135], v[196:199], v[92:95]
	v_mfma_f32_16x16x32_bf16 v[88:91], v[152:155], v[196:199], v[88:91]
	v_mfma_f32_16x16x32_bf16 v[76:79], v[132:135], v[204:207], v[76:79]
	v_mfma_f32_16x16x32_bf16 v[72:75], v[152:155], v[204:207], v[72:75]
	s_barrier
	s_add_i32 s28, 0, 0x1c000
	s_add_i32 s29, s55, s40
	s_mov_b32 m0, s29
	ds_read_b128 v[208:211], v227
	ds_read_b128 v[212:215], v227 offset:1024
	ds_read_b128 v[216:219], v227 offset:2048
	ds_read_b128 v[220:223], v227 offset:3072
	global_load_lds_dwordx4 v144, vcc
	s_add_i32 m0, s29, 0x2000
	s_nop 0
	global_load_lds_dwordx4 v136, vcc
	s_barrier
	s_waitcnt lgkmcnt(0)
	v_mfma_f32_16x16x32_bf16 v[116:119], v[208:211], v[160:163], v[116:119]
	v_mfma_f32_16x16x32_bf16 v[112:115], v[216:219], v[160:163], v[112:115]
	v_mfma_f32_16x16x32_bf16 v[100:103], v[208:211], v[168:171], v[100:103]
	v_mfma_f32_16x16x32_bf16 v[96:99], v[216:219], v[168:171], v[96:99]
	v_mfma_f32_16x16x32_bf16 v[84:87], v[208:211], v[176:179], v[84:87]
	v_mfma_f32_16x16x32_bf16 v[80:83], v[216:219], v[176:179], v[80:83]
	v_mfma_f32_16x16x32_bf16 v[68:71], v[208:211], v[200:203], v[68:71]
	v_mfma_f32_16x16x32_bf16 v[64:67], v[216:219], v[200:203], v[64:67]
	v_mfma_f32_16x16x32_bf16 v[116:119], v[212:215], v[164:167], v[116:119]
	v_mfma_f32_16x16x32_bf16 v[112:115], v[220:223], v[164:167], v[112:115]
	v_mfma_f32_16x16x32_bf16 v[100:103], v[212:215], v[172:175], v[100:103]
	v_mfma_f32_16x16x32_bf16 v[96:99], v[220:223], v[172:175], v[96:99]
	v_mfma_f32_16x16x32_bf16 v[84:87], v[212:215], v[196:199], v[84:87]
	v_mfma_f32_16x16x32_bf16 v[80:83], v[220:223], v[196:199], v[80:83]
	v_mfma_f32_16x16x32_bf16 v[68:71], v[212:215], v[204:207], v[68:71]
	v_mfma_f32_16x16x32_bf16 v[64:67], v[220:223], v[204:207], v[64:67]
	s_mov_b32 m0, s49
	s_barrier
; #define PG8_STAGE(bufoff, gbase, voff) do { _Pragma("unroll") for (int _i = 0; _i < 2; ++_i) \
;     __builtin_amdgcn_global_load_lds((const unsigned*)((const char*)(gbase) + (voff)[_i]), (LAS unsigned*)(lds + (bufoff) + ldsw + _i * 8192), 16, 0, 0); } while (0)
; #define PG8_MMA(ai, bj, At, Bt) do { __builtin_amdgcn_s_setprio(1); _Pragma("unroll") for (int m = 0; m < 4; ++m) _Pragma("unroll") for (int n = 0; n < 2; ++n) _Pragma("unroll") for (int k = 0; k < 2; ++k) \
;     acc[ai][bj][m][n] = __builtin_amdgcn_mfma_f32_16x16x32_bf16(Bt[n][k], At[m][k], acc[ai][bj][m][n], 0, 0, 0); __builtin_amdgcn_s_setprio(0); } while (0)
; #define PG8_WAIT_V(n) asm volatile("s_waitcnt vmcnt(" #n ")" ::: "memory")
; #define PG8_WAIT_L(n) asm volatile("s_waitcnt lgkmcnt(" #n ")" ::: "memory")
; #define PG8_BAR __builtin_amdgcn_s_barrier()
; #define PG8_SCHED __builtin_amdgcn_sched_barrier(0)
; template <class Epi, class Sched>
; DI void gemm_phase(LAS unsigned char* lds, const Gemm g, const Sched& S, const Epi& E) {
;     ...
;       PG8_BAR; PG8_WAIT_L(0); PG8_MMA(1, 0, At, B0); PG8_BAR; PG8_SCHED;
;       PG8_STAGE(PG8_SB(1, 1), b3 + hstep, voffB);
;       PG8_WAIT_V(6); PG8_BAR; PG8_MMA(1, 1, At, B1); PG8_BAR;
;     }
;   DI void operator()(const f32x4 (&acc)[2][2][4][2], const pg8::Unit& u, int wr, int wc, int fr_, int fq_) const {
;     ...
;             } else if (EPI == EPI_RESID) {
;               if (n == 0) {
;                 const int f8 = u.pn * 256 + bj * 128 + wc * 32 + 8 * fq;
;                 const f32x4 v1 = acc[ai][bj][m][1];
;                 f32x4 r0, r1;
;                 if (rsrc) {
;                   r0 = *(const f32x4*)(rsrc + (size_t)token * 1024 + f8); r1 = *(const f32x4*)(rsrc + (size_t)token * 1024 + f8 + 4);
	ds_read_b128 v[160:163], v159 offset:49152
	ds_read_b128 v[164:167], v159 offset:50176
	ds_read_b128 v[168:171], v159 offset:51200
	ds_read_b128 v[172:175], v159 offset:52224
	ds_read_b128 v[176:179], v159 offset:53248
	ds_read_b128 v[196:199], v159 offset:54272
	ds_read_b128 v[200:203], v159 offset:55296
	ds_read_b128 v[204:207], v159 offset:56320
	global_load_lds_dwordx4 v140, s[100:101]
	s_mov_b32 m0, s50
	s_nop 0
	global_load_lds_dwordx4 v138, s[100:101]
	s_barrier
	s_waitcnt lgkmcnt(0)
	v_mfma_f32_16x16x32_bf16 v[60:63], v[128:131], v[160:163], v[60:63]
	v_mfma_f32_16x16x32_bf16 v[56:59], v[148:151], v[160:163], v[56:59]
	v_mfma_f32_16x16x32_bf16 v[44:47], v[128:131], v[168:171], v[44:47]
	v_mfma_f32_16x16x32_bf16 v[40:43], v[148:151], v[168:171], v[40:43]
	v_mfma_f32_16x16x32_bf16 v[28:31], v[128:131], v[176:179], v[28:31]
	v_mfma_f32_16x16x32_bf16 v[24:27], v[148:151], v[176:179], v[24:27]
	v_mfma_f32_16x16x32_bf16 v[12:15], v[128:131], v[200:203], v[12:15]
	v_mfma_f32_16x16x32_bf16 v[8:11], v[148:151], v[200:203], v[8:11]
	v_mfma_f32_16x16x32_bf16 v[60:63], v[132:135], v[164:167], v[60:63]
	v_mfma_f32_16x16x32_bf16 v[56:59], v[152:155], v[164:167], v[56:59]
	v_mfma_f32_16x16x32_bf16 v[44:47], v[132:135], v[172:175], v[44:47]
	v_mfma_f32_16x16x32_bf16 v[40:43], v[152:155], v[172:175], v[40:43]
	v_mfma_f32_16x16x32_bf16 v[28:31], v[132:135], v[196:199], v[28:31]
	v_mfma_f32_16x16x32_bf16 v[24:27], v[152:155], v[196:199], v[24:27]
	v_mfma_f32_16x16x32_bf16 v[12:15], v[132:135], v[204:207], v[12:15]
	v_mfma_f32_16x16x32_bf16 v[8:11], v[152:155], v[204:207], v[8:11]
	s_barrier
	s_add_u32 s4, s4, 0x40080
	s_addc_u32 s5, s5, 0
	s_add_i32 s28, s28, s40
	s_mov_b32 m0, s28
	s_nop 0
	global_load_lds_dwordx4 v144, s[4:5]
	s_add_i32 m0, s28, 0x2000
	s_nop 0
	global_load_lds_dwordx4 v136, s[4:5]
	s_waitcnt vmcnt(6)
	s_barrier
	v_mfma_f32_16x16x32_bf16 v[52:55], v[208:211], v[160:163], v[52:55]
	v_mfma_f32_16x16x32_bf16 v[48:51], v[216:219], v[160:163], v[48:51]
	v_mfma_f32_16x16x32_bf16 v[36:39], v[208:211], v[168:171], v[36:39]
	v_mfma_f32_16x16x32_bf16 v[32:35], v[216:219], v[168:171], v[32:35]
	v_mfma_f32_16x16x32_bf16 v[20:23], v[208:211], v[176:179], v[20:23]
	v_mfma_f32_16x16x32_bf16 v[16:19], v[216:219], v[176:179], v[16:19]
	v_mfma_f32_16x16x32_bf16 v[4:7], v[208:211], v[200:203], v[4:7]
	v_mfma_f32_16x16x32_bf16 v[0:3], v[216:219], v[200:203], v[0:3]
	v_mfma_f32_16x16x32_bf16 v[52:55], v[212:215], v[164:167], v[52:55]
	v_mfma_f32_16x16x32_bf16 v[48:51], v[220:223], v[164:167], v[48:51]
	v_mfma_f32_16x16x32_bf16 v[36:39], v[212:215], v[172:175], v[36:39]
	v_mfma_f32_16x16x32_bf16 v[32:35], v[220:223], v[172:175], v[32:35]
	v_mfma_f32_16x16x32_bf16 v[20:23], v[212:215], v[196:199], v[20:23]
	v_mfma_f32_16x16x32_bf16 v[16:19], v[220:223], v[196:199], v[16:19]
	v_mfma_f32_16x16x32_bf16 v[4:7], v[212:215], v[204:207], v[4:7]
	v_mfma_f32_16x16x32_bf16 v[0:3], v[220:223], v[204:207], v[0:3]
	s_add_i32 s54, s54, 2
	s_add_u32 s2, s2, 0x100
	s_addc_u32 s3, s3, 0
	s_add_u32 s52, s52, 0x100
	s_addc_u32 s53, s53, 0
	s_cmp_gt_u32 s54, 13
	s_barrier
	s_cbranch_scc0 .LBB0_1644
	s_lshl_b32 s2, s34, 8
	v_mov_b32_e32 v161, v182
	s_add_i32 s2, s2, s47
	v_cndmask_b32_e64 v130, 0, 1, s[14:15]
	v_and_or_b32 v150, v161, 15, s2
	s_lshl_b32 s2, s24, 8
	v_bfe_u32 v160, v161, 4, 2
	s_or_b32 s2, s2, s48
	v_ashrrev_i32_e32 v151, 31, v150
	v_lshl_or_b32 v148, v160, 3, s2
	v_lshlrev_b64 v[128:129], 12, v[150:151]
	v_ashrrev_i32_e32 v149, 31, v148
	v_lshl_add_u64 v[128:129], s[6:7], 0, v[128:129]
	v_cmp_ne_u32_e64 s[2:3], 1, v130
	s_andn2_b64 vcc, exec, s[14:15]
	v_lshl_add_u64 v[154:155], v[148:149], 2, v[128:129]
	s_cbranch_vccnz .LBB0_1647
	global_load_dwordx4 v[132:135], v[154:155], off offset:16
	global_load_dwordx4 v[128:131], v[154:155], off
	s_mov_b64 s[4:5], 0
	s_branch .LBB0_1648

; #define PG8_STAGE(bufoff, gbase, voff) do { _Pragma("unroll") for (int _i = 0; _i < 2; ++_i) \
;     __builtin_amdgcn_global_load_lds((const unsigned*)((const char*)(gbase) + (voff)[_i]), (LAS unsigned*)(lds + (bufoff) + ldsw + _i * 8192), 16, 0, 0); } while (0)
; #define PG8_LDA(dst, b, h) do { _Pragma("unroll") for (int m = 0; m < 4; ++m) _Pragma("unroll") for (int k = 0; k < 2; ++k) dst[m][k] = *(const LAS bf16x8*)(lds + PG8_SA(b, h) + aoff + m * 2048 + k * 1024); } while (0)
; #define PG8_LDB(dst, b, h) do { _Pragma("unroll") for (int n = 0; n < 2; ++n) _Pragma("unroll") for (int k = 0; k < 2; ++k) dst[n][k] = *(const LAS bf16x8*)(lds + PG8_SB(b, h) + boff + n * 2048 + k * 1024); } while (0)
; #define PG8_MMA(ai, bj, At, Bt) do { __builtin_amdgcn_s_setprio(1); _Pragma("unroll") for (int m = 0; m < 4; ++m) _Pragma("unroll") for (int n = 0; n < 2; ++n) _Pragma("unroll") for (int k = 0; k < 2; ++k) \
;     acc[ai][bj][m][n] = __builtin_amdgcn_mfma_f32_16x16x32_bf16(Bt[n][k], At[m][k], acc[ai][bj][m][n], 0, 0, 0); __builtin_amdgcn_s_setprio(0); } while (0)
; #define PG8_WAIT_V(n) asm volatile("s_waitcnt vmcnt(" #n ")" ::: "memory")
; #define PG8_WAIT_L(n) asm volatile("s_waitcnt lgkmcnt(" #n ")" ::: "memory")
; #define PG8_BAR __builtin_amdgcn_s_barrier()
; #define PG8_SCHED __builtin_amdgcn_sched_barrier(0)
; template <class Epi, class Sched>
; DI void gemm_phase(LAS unsigned char* lds, const Gemm g, const Sched& S, const Epi& E) {
;     ...
;       PG8_LDB(B0, 0, 0); PG8_SCHED; PG8_LDA(At, 0, 0); PG8_STAGE(PG8_SA(1, 1), a1 + hstep, voffA);
;       PG8_WAIT_L(8); PG8_BAR; PG8_WAIT_L(0); PG8_MMA(0, 0, At, B0); PG8_BAR; PG8_SCHED;
;       PG8_LDB(B1, 0, 1); PG8_STAGE(PG8_SB(0, 0), b2, voffB);
;       PG8_BAR; PG8_WAIT_L(0); PG8_MMA(0, 1, At, B1); PG8_BAR;
;       PG8_LDA(At, 0, 1); PG8_STAGE(PG8_SA(0, 0), a2, voffA);
;       PG8_BAR; PG8_WAIT_L(0); PG8_MMA(1, 0, At, B0); PG8_BAR; PG8_SCHED;
;       PG8_STAGE(PG8_SB(0, 1), b2 + hstep, voffB);
;       PG8_WAIT_V(6); PG8_BAR; PG8_MMA(1, 1, At, B1); PG8_BAR;
.LBB0_1829:
	s_add_u32 s16, s14, 0xfffc0080
	s_addc_u32 s17, s15, -1
	s_add_i32 s51, 0, 0x10000
	ds_read_b128 v[146:149], v224
	ds_read_b128 v[150:153], v224 offset:1024
	ds_read_b128 v[154:157], v224 offset:2048
	ds_read_b128 v[158:161], v224 offset:3072
	s_cmp_eq_u32 s50, 12
	s_cselect_b32 s19, s7, s17
	s_cselect_b32 s18, s46, s16
	s_cselect_b32 s17, s5, s49
	s_cselect_b32 s16, s47, s48
	s_add_i32 m0, s29, 0xc000
	ds_read_b128 v[162:165], v143
	ds_read_b128 v[166:169], v143 offset:1024
	ds_read_b128 v[170:173], v143 offset:2048
	ds_read_b128 v[174:177], v143 offset:3072
	ds_read_b128 v[178:181], v143 offset:4096
	ds_read_b128 v[196:199], v143 offset:5120
	ds_read_b128 v[200:203], v143 offset:6144
	ds_read_b128 v[204:207], v143 offset:7168
	global_load_lds_dwordx4 v136, s[14:15]
	s_add_i32 m0, s29, 0xe000
	s_nop 0
	global_load_lds_dwordx4 v138, s[14:15]
	s_waitcnt lgkmcnt(8)
	s_barrier
	s_waitcnt lgkmcnt(0)
	v_mfma_f32_16x16x32_bf16 v[124:127], v[146:149], v[162:165], v[124:127]
	v_mfma_f32_16x16x32_bf16 v[120:123], v[154:157], v[162:165], v[120:123]
	v_mfma_f32_16x16x32_bf16 v[112:115], v[146:149], v[170:173], v[112:115]
	v_mfma_f32_16x16x32_bf16 v[104:107], v[154:157], v[170:173], v[104:107]
	v_mfma_f32_16x16x32_bf16 v[92:95], v[146:149], v[178:181], v[92:95]
	v_mfma_f32_16x16x32_bf16 v[88:91], v[154:157], v[178:181], v[88:91]
	v_mfma_f32_16x16x32_bf16 v[80:83], v[146:149], v[200:203], v[80:83]
	v_mfma_f32_16x16x32_bf16 v[72:75], v[154:157], v[200:203], v[72:75]
	v_mfma_f32_16x16x32_bf16 v[124:127], v[150:153], v[166:169], v[124:127]
	v_mfma_f32_16x16x32_bf16 v[120:123], v[158:161], v[166:169], v[120:123]
	v_mfma_f32_16x16x32_bf16 v[112:115], v[150:153], v[174:177], v[112:115]
	v_mfma_f32_16x16x32_bf16 v[104:107], v[158:161], v[174:177], v[104:107]
	v_mfma_f32_16x16x32_bf16 v[92:95], v[150:153], v[196:199], v[92:95]
	v_mfma_f32_16x16x32_bf16 v[88:91], v[158:161], v[196:199], v[88:91]
	v_mfma_f32_16x16x32_bf16 v[80:83], v[150:153], v[204:207], v[80:83]
	v_mfma_f32_16x16x32_bf16 v[72:75], v[158:161], v[204:207], v[72:75]
	s_barrier
	s_add_i32 s54, 0, 0x14000
	s_add_i32 s51, s51, s20
	ds_read_b128 v[208:211], v225
	ds_read_b128 v[212:215], v225 offset:1024
	ds_read_b128 v[216:219], v225 offset:2048
	ds_read_b128 v[220:223], v225 offset:3072
	s_add_u32 vcc_lo, s16, s0
	s_addc_u32 vcc_hi, s17, s1
	s_mov_b32 m0, s51
	s_nop 0
	global_load_lds_dwordx4 v132, s[16:17]
	s_add_i32 m0, s51, 0x2000
	s_nop 0
	global_load_lds_dwordx4 v128, s[16:17]
	s_barrier
	s_waitcnt lgkmcnt(0)
	v_mfma_f32_16x16x32_bf16 v[116:119], v[208:211], v[162:165], v[116:119]
	v_mfma_f32_16x16x32_bf16 v[108:111], v[216:219], v[162:165], v[108:111]
	v_mfma_f32_16x16x32_bf16 v[100:103], v[208:211], v[170:173], v[100:103]
	v_mfma_f32_16x16x32_bf16 v[96:99], v[216:219], v[170:173], v[96:99]
	v_mfma_f32_16x16x32_bf16 v[84:87], v[208:211], v[178:181], v[84:87]
	v_mfma_f32_16x16x32_bf16 v[76:79], v[216:219], v[178:181], v[76:79]
	v_mfma_f32_16x16x32_bf16 v[68:71], v[208:211], v[200:203], v[68:71]
	v_mfma_f32_16x16x32_bf16 v[64:67], v[216:219], v[200:203], v[64:67]
	v_mfma_f32_16x16x32_bf16 v[116:119], v[212:215], v[166:169], v[116:119]
	v_mfma_f32_16x16x32_bf16 v[108:111], v[220:223], v[166:169], v[108:111]
	v_mfma_f32_16x16x32_bf16 v[100:103], v[212:215], v[174:177], v[100:103]
	v_mfma_f32_16x16x32_bf16 v[96:99], v[220:223], v[174:177], v[96:99]
	v_mfma_f32_16x16x32_bf16 v[84:87], v[212:215], v[196:199], v[84:87]
	v_mfma_f32_16x16x32_bf16 v[76:79], v[220:223], v[196:199], v[76:79]
	v_mfma_f32_16x16x32_bf16 v[68:71], v[212:215], v[204:207], v[68:71]
	v_mfma_f32_16x16x32_bf16 v[64:67], v[220:223], v[204:207], v[64:67]
	s_mov_b32 m0, s29
	s_add_u32 s100, s18, s0
	s_addc_u32 s101, s19, s1
	s_barrier
	ds_read_b128 v[162:165], v143 offset:16384
	ds_read_b128 v[166:169], v143 offset:17408
	ds_read_b128 v[170:173], v143 offset:18432
	ds_read_b128 v[174:177], v143 offset:19456
	ds_read_b128 v[178:181], v143 offset:20480
	ds_read_b128 v[196:199], v143 offset:21504
	ds_read_b128 v[200:203], v143 offset:22528
	ds_read_b128 v[204:207], v143 offset:23552
	global_load_lds_dwordx4 v134, s[18:19]
	s_mov_b32 m0, s34
	s_nop 0
	global_load_lds_dwordx4 v130, s[18:19]
	s_barrier
	s_waitcnt lgkmcnt(0)
	v_mfma_f32_16x16x32_bf16 v[60:63], v[146:149], v[162:165], v[60:63]
	v_mfma_f32_16x16x32_bf16 v[56:59], v[154:157], v[162:165], v[56:59]
	v_mfma_f32_16x16x32_bf16 v[48:51], v[146:149], v[170:173], v[48:51]
	v_mfma_f32_16x16x32_bf16 v[40:43], v[154:157], v[170:173], v[40:43]
	v_mfma_f32_16x16x32_bf16 v[28:31], v[146:149], v[178:181], v[28:31]
	v_mfma_f32_16x16x32_bf16 v[24:27], v[154:157], v[178:181], v[24:27]
	v_mfma_f32_16x16x32_bf16 v[16:19], v[146:149], v[200:203], v[16:19]
	v_mfma_f32_16x16x32_bf16 v[8:11], v[154:157], v[200:203], v[8:11]
	v_mfma_f32_16x16x32_bf16 v[60:63], v[150:153], v[166:169], v[60:63]
	v_mfma_f32_16x16x32_bf16 v[56:59], v[158:161], v[166:169], v[56:59]
	v_mfma_f32_16x16x32_bf16 v[48:51], v[150:153], v[174:177], v[48:51]
	v_mfma_f32_16x16x32_bf16 v[40:43], v[158:161], v[174:177], v[40:43]
	v_mfma_f32_16x16x32_bf16 v[28:31], v[150:153], v[196:199], v[28:31]
	v_mfma_f32_16x16x32_bf16 v[24:27], v[158:161], v[196:199], v[24:27]
	v_mfma_f32_16x16x32_bf16 v[16:19], v[150:153], v[204:207], v[16:19]
	v_mfma_f32_16x16x32_bf16 v[8:11], v[158:161], v[204:207], v[8:11]
	s_barrier
	s_add_u32 s52, s16, 0x40000
	s_addc_u32 s53, s17, 0
	s_add_i32 s51, s54, s20
	s_mov_b32 m0, s51
	s_nop 0
	global_load_lds_dwordx4 v132, s[52:53]
	s_add_i32 m0, s51, 0x2000
	s_nop 0
	global_load_lds_dwordx4 v128, s[52:53]
	s_waitcnt vmcnt(6)
	s_barrier
; #define PG8_STAGE(bufoff, gbase, voff) do { _Pragma("unroll") for (int _i = 0; _i < 2; ++_i) \
;     __builtin_amdgcn_global_load_lds((const unsigned*)((const char*)(gbase) + (voff)[_i]), (LAS unsigned*)(lds + (bufoff) + ldsw + _i * 8192), 16, 0, 0); } while (0)
; #define PG8_LDA(dst, b, h) do { _Pragma("unroll") for (int m = 0; m < 4; ++m) _Pragma("unroll") for (int k = 0; k < 2; ++k) dst[m][k] = *(const LAS bf16x8*)(lds + PG8_SA(b, h) + aoff + m * 2048 + k * 1024); } while (0)
; #define PG8_LDB(dst, b, h) do { _Pragma("unroll") for (int n = 0; n < 2; ++n) _Pragma("unroll") for (int k = 0; k < 2; ++k) dst[n][k] = *(const LAS bf16x8*)(lds + PG8_SB(b, h) + boff + n * 2048 + k * 1024); } while (0)
; #define PG8_MMA(ai, bj, At, Bt) do { __builtin_amdgcn_s_setprio(1); _Pragma("unroll") for (int m = 0; m < 4; ++m) _Pragma("unroll") for (int n = 0; n < 2; ++n) _Pragma("unroll") for (int k = 0; k < 2; ++k) \
;     acc[ai][bj][m][n] = __builtin_amdgcn_mfma_f32_16x16x32_bf16(Bt[n][k], At[m][k], acc[ai][bj][m][n], 0, 0, 0); __builtin_amdgcn_s_setprio(0); } while (0)
; #define PG8_WAIT_V(n) asm volatile("s_waitcnt vmcnt(" #n ")" ::: "memory")
; #define PG8_WAIT_L(n) asm volatile("s_waitcnt lgkmcnt(" #n ")" ::: "memory")
; #define PG8_BAR __builtin_amdgcn_s_barrier()
; #define PG8_SCHED __builtin_amdgcn_sched_barrier(0)
; template <class Epi, class Sched>
; DI void gemm_phase(LAS unsigned char* lds, const Gemm g, const Sched& S, const Epi& E) {
;     ...
;       PG8_WAIT_V(6); PG8_BAR; PG8_MMA(1, 1, At, B1); PG8_BAR;
;       PG8_LDB(B0, 1, 0); PG8_SCHED; PG8_LDA(At, 1, 0); PG8_STAGE(PG8_SA(0, 1), a2 + hstep, voffA);
;       PG8_WAIT_L(8); PG8_BAR; PG8_WAIT_L(0); PG8_MMA(0, 0, At, B0); PG8_BAR; PG8_SCHED;
;       PG8_LDB(B1, 1, 1); PG8_STAGE(PG8_SB(1, 0), b3, voffB);
;       PG8_BAR; PG8_WAIT_L(0); PG8_MMA(0, 1, At, B1); PG8_BAR;
;       PG8_LDA(At, 1, 1); PG8_STAGE(PG8_SA(1, 0), a3, voffA);
;       PG8_BAR; PG8_WAIT_L(0); PG8_MMA(1, 0, At, B0); PG8_BAR; PG8_SCHED;
	v_mfma_f32_16x16x32_bf16 v[52:55], v[208:211], v[162:165], v[52:55]
	v_mfma_f32_16x16x32_bf16 v[44:47], v[216:219], v[162:165], v[44:47]
	v_mfma_f32_16x16x32_bf16 v[36:39], v[208:211], v[170:173], v[36:39]
	v_mfma_f32_16x16x32_bf16 v[32:35], v[216:219], v[170:173], v[32:35]
	v_mfma_f32_16x16x32_bf16 v[20:23], v[208:211], v[178:181], v[20:23]
	v_mfma_f32_16x16x32_bf16 v[12:15], v[216:219], v[178:181], v[12:15]
	v_mfma_f32_16x16x32_bf16 v[4:7], v[208:211], v[200:203], v[4:7]
	v_mfma_f32_16x16x32_bf16 v[0:3], v[216:219], v[200:203], v[0:3]
	v_mfma_f32_16x16x32_bf16 v[52:55], v[212:215], v[166:169], v[52:55]
	v_mfma_f32_16x16x32_bf16 v[44:47], v[220:223], v[166:169], v[44:47]
	v_mfma_f32_16x16x32_bf16 v[36:39], v[212:215], v[174:177], v[36:39]
	v_mfma_f32_16x16x32_bf16 v[32:35], v[220:223], v[174:177], v[32:35]
	v_mfma_f32_16x16x32_bf16 v[20:23], v[212:215], v[196:199], v[20:23]
	v_mfma_f32_16x16x32_bf16 v[12:15], v[220:223], v[196:199], v[12:15]
	v_mfma_f32_16x16x32_bf16 v[4:7], v[212:215], v[204:207], v[4:7]
	v_mfma_f32_16x16x32_bf16 v[0:3], v[220:223], v[204:207], v[0:3]
	s_add_i32 s51, 0, 0x18000
	s_barrier
	ds_read_b128 v[146:149], v226
	ds_read_b128 v[150:153], v226 offset:1024
	ds_read_b128 v[154:157], v226 offset:2048
	ds_read_b128 v[158:161], v226 offset:3072
	s_add_u32 s18, s18, 0x40000
	s_addc_u32 s19, s19, 0
	s_mov_b32 m0, s35
	ds_read_b128 v[162:165], v143 offset:32768
	ds_read_b128 v[166:169], v143 offset:33792
	ds_read_b128 v[170:173], v143 offset:34816
	ds_read_b128 v[174:177], v143 offset:35840
	ds_read_b128 v[178:181], v143 offset:36864
	ds_read_b128 v[196:199], v143 offset:37888
	ds_read_b128 v[200:203], v143 offset:38912
	ds_read_b128 v[204:207], v143 offset:39936
	global_load_lds_dwordx4 v134, s[18:19]
	s_mov_b32 m0, s38
	s_nop 0
	global_load_lds_dwordx4 v130, s[18:19]
	s_waitcnt lgkmcnt(8)
	s_barrier
	s_waitcnt lgkmcnt(0)
	v_mfma_f32_16x16x32_bf16 v[124:127], v[146:149], v[162:165], v[124:127]
	v_mfma_f32_16x16x32_bf16 v[120:123], v[154:157], v[162:165], v[120:123]
	v_mfma_f32_16x16x32_bf16 v[112:115], v[146:149], v[170:173], v[112:115]
	v_mfma_f32_16x16x32_bf16 v[104:107], v[154:157], v[170:173], v[104:107]
	v_mfma_f32_16x16x32_bf16 v[92:95], v[146:149], v[178:181], v[92:95]
	v_mfma_f32_16x16x32_bf16 v[88:91], v[154:157], v[178:181], v[88:91]
	v_mfma_f32_16x16x32_bf16 v[80:83], v[146:149], v[200:203], v[80:83]
	v_mfma_f32_16x16x32_bf16 v[72:75], v[154:157], v[200:203], v[72:75]
	v_mfma_f32_16x16x32_bf16 v[124:127], v[150:153], v[166:169], v[124:127]
	v_mfma_f32_16x16x32_bf16 v[120:123], v[158:161], v[166:169], v[120:123]
	v_mfma_f32_16x16x32_bf16 v[112:115], v[150:153], v[174:177], v[112:115]
	v_mfma_f32_16x16x32_bf16 v[104:107], v[158:161], v[174:177], v[104:107]
	v_mfma_f32_16x16x32_bf16 v[92:95], v[150:153], v[196:199], v[92:95]
	v_mfma_f32_16x16x32_bf16 v[88:91], v[158:161], v[196:199], v[88:91]
	v_mfma_f32_16x16x32_bf16 v[80:83], v[150:153], v[204:207], v[80:83]
	v_mfma_f32_16x16x32_bf16 v[72:75], v[158:161], v[204:207], v[72:75]
	s_barrier
	s_add_i32 s18, 0, 0x1c000
	s_add_i32 s19, s51, s20
	s_mov_b32 m0, s19
	ds_read_b128 v[208:211], v227
	ds_read_b128 v[212:215], v227 offset:1024
	ds_read_b128 v[216:219], v227 offset:2048
	ds_read_b128 v[220:223], v227 offset:3072
	global_load_lds_dwordx4 v132, vcc
	s_add_i32 m0, s19, 0x2000
	s_nop 0
	global_load_lds_dwordx4 v128, vcc
	s_barrier
	s_waitcnt lgkmcnt(0)
	v_mfma_f32_16x16x32_bf16 v[116:119], v[208:211], v[162:165], v[116:119]
	v_mfma_f32_16x16x32_bf16 v[108:111], v[216:219], v[162:165], v[108:111]
	v_mfma_f32_16x16x32_bf16 v[100:103], v[208:211], v[170:173], v[100:103]
	v_mfma_f32_16x16x32_bf16 v[96:99], v[216:219], v[170:173], v[96:99]
	v_mfma_f32_16x16x32_bf16 v[84:87], v[208:211], v[178:181], v[84:87]
	v_mfma_f32_16x16x32_bf16 v[76:79], v[216:219], v[178:181], v[76:79]
	v_mfma_f32_16x16x32_bf16 v[68:71], v[208:211], v[200:203], v[68:71]
	v_mfma_f32_16x16x32_bf16 v[64:67], v[216:219], v[200:203], v[64:67]
	v_mfma_f32_16x16x32_bf16 v[116:119], v[212:215], v[166:169], v[116:119]
	v_mfma_f32_16x16x32_bf16 v[108:111], v[220:223], v[166:169], v[108:111]
	v_mfma_f32_16x16x32_bf16 v[100:103], v[212:215], v[174:177], v[100:103]
	v_mfma_f32_16x16x32_bf16 v[96:99], v[220:223], v[174:177], v[96:99]
	v_mfma_f32_16x16x32_bf16 v[84:87], v[212:215], v[196:199], v[84:87]
	v_mfma_f32_16x16x32_bf16 v[76:79], v[220:223], v[196:199], v[76:79]
	v_mfma_f32_16x16x32_bf16 v[68:71], v[212:215], v[204:207], v[68:71]
	v_mfma_f32_16x16x32_bf16 v[64:67], v[220:223], v[204:207], v[64:67]
	s_mov_b32 m0, s40
	s_barrier
	ds_read_b128 v[162:165], v143 offset:49152
	ds_read_b128 v[166:169], v143 offset:50176
	ds_read_b128 v[170:173], v143 offset:51200
	ds_read_b128 v[174:177], v143 offset:52224
	ds_read_b128 v[178:181], v143 offset:53248
	ds_read_b128 v[196:199], v143 offset:54272
	ds_read_b128 v[200:203], v143 offset:55296
	ds_read_b128 v[204:207], v143 offset:56320
	global_load_lds_dwordx4 v134, s[100:101]
	s_mov_b32 m0, s41
	s_nop 0
	global_load_lds_dwordx4 v130, s[100:101]
	s_barrier
	s_waitcnt lgkmcnt(0)
	v_mfma_f32_16x16x32_bf16 v[60:63], v[146:149], v[162:165], v[60:63]
	v_mfma_f32_16x16x32_bf16 v[56:59], v[154:157], v[162:165], v[56:59]
	v_mfma_f32_16x16x32_bf16 v[48:51], v[146:149], v[170:173], v[48:51]
	v_mfma_f32_16x16x32_bf16 v[40:43], v[154:157], v[170:173], v[40:43]
	v_mfma_f32_16x16x32_bf16 v[28:31], v[146:149], v[178:181], v[28:31]
	v_mfma_f32_16x16x32_bf16 v[24:27], v[154:157], v[178:181], v[24:27]
	v_mfma_f32_16x16x32_bf16 v[16:19], v[146:149], v[200:203], v[16:19]
	v_mfma_f32_16x16x32_bf16 v[8:11], v[154:157], v[200:203], v[8:11]
	v_mfma_f32_16x16x32_bf16 v[60:63], v[150:153], v[166:169], v[60:63]
	v_mfma_f32_16x16x32_bf16 v[56:59], v[158:161], v[166:169], v[56:59]
	v_mfma_f32_16x16x32_bf16 v[48:51], v[150:153], v[174:177], v[48:51]
	v_mfma_f32_16x16x32_bf16 v[40:43], v[158:161], v[174:177], v[40:43]
	v_mfma_f32_16x16x32_bf16 v[28:31], v[150:153], v[196:199], v[28:31]
	v_mfma_f32_16x16x32_bf16 v[24:27], v[158:161], v[196:199], v[24:27]
	v_mfma_f32_16x16x32_bf16 v[16:19], v[150:153], v[204:207], v[16:19]
	v_mfma_f32_16x16x32_bf16 v[8:11], v[158:161], v[204:207], v[8:11]
	s_barrier
; #define PG8_STAGE(bufoff, gbase, voff) do { _Pragma("unroll") for (int _i = 0; _i < 2; ++_i) \
;     __builtin_amdgcn_global_load_lds((const unsigned*)((const char*)(gbase) + (voff)[_i]), (LAS unsigned*)(lds + (bufoff) + ldsw + _i * 8192), 16, 0, 0); } while (0)
; #define PG8_MMA(ai, bj, At, Bt) do { __builtin_amdgcn_s_setprio(1); _Pragma("unroll") for (int m = 0; m < 4; ++m) _Pragma("unroll") for (int n = 0; n < 2; ++n) _Pragma("unroll") for (int k = 0; k < 2; ++k) \
;     acc[ai][bj][m][n] = __builtin_amdgcn_mfma_f32_16x16x32_bf16(Bt[n][k], At[m][k], acc[ai][bj][m][n], 0, 0, 0); __builtin_amdgcn_s_setprio(0); } while (0)
; #define PG8_WAIT_V(n) asm volatile("s_waitcnt vmcnt(" #n ")" ::: "memory")
; #define PG8_WAIT_L(n) asm volatile("s_waitcnt lgkmcnt(" #n ")" ::: "memory")
; #define PG8_BAR __builtin_amdgcn_s_barrier()
; #define PG8_SCHED __builtin_amdgcn_sched_barrier(0)
; template <class Epi, class Sched>
; DI void gemm_phase(LAS unsigned char* lds, const Gemm g, const Sched& S, const Epi& E) {
;     ...
;       PG8_BAR; PG8_WAIT_L(0); PG8_MMA(1, 0, At, B0); PG8_BAR; PG8_SCHED;
;       PG8_STAGE(PG8_SB(1, 1), b3 + hstep, voffB);
;       PG8_WAIT_V(6); PG8_BAR; PG8_MMA(1, 1, At, B1); PG8_BAR;
;     }
;   DI void operator()(const f32x4 (&acc)[2][2][4][2], const pg8::Unit& u, int wr, int wc, int fr_, int fq_) const {
;     ...
;               if (n == 0) {
;                 const f32x4 v1 = acc[ai][bj][m][1];
;                 u32x4 o4;
;                 { const float t0 = fmaxf(v[0], 0.f) * rinv, t1 = fmaxf(v[1], 0.f) * rinv, t2 = fmaxf(v[2], 0.f) * rinv, t3 = fmaxf(v[3], 0.f) * rinv;
;                   o4.x = pack2(t0 * t0, t1 * t1); o4.y = pack2(t2 * t2, t3 * t3); }
;                 { const float t0 = fmaxf(v1[0], 0.f) * rinv, t1 = fmaxf(v1[1], 0.f) * rinv, t2 = fmaxf(v1[2], 0.f) * rinv, t3 = fmaxf(v1[3], 0.f) * rinv;
;                   o4.z = pack2(t0 * t0, t1 * t1); o4.w = pack2(t2 * t2, t3 * t3); }
;                 *(u32x4*)((u16*)big + (size_t)token * 4096 + u.pn * 256 + bj * 128 + wc * 32 + 8 * fq) = o4;
	s_add_u32 s16, s16, 0x40080
	s_addc_u32 s17, s17, 0
	s_add_i32 s18, s18, s20
	s_mov_b32 m0, s18
	s_nop 0
	global_load_lds_dwordx4 v132, s[16:17]
	s_add_i32 m0, s18, 0x2000
	s_nop 0
	global_load_lds_dwordx4 v128, s[16:17]
	s_waitcnt vmcnt(6)
	s_barrier
	v_mfma_f32_16x16x32_bf16 v[52:55], v[208:211], v[162:165], v[52:55]
	v_mfma_f32_16x16x32_bf16 v[44:47], v[216:219], v[162:165], v[44:47]
	v_mfma_f32_16x16x32_bf16 v[36:39], v[208:211], v[170:173], v[36:39]
	v_mfma_f32_16x16x32_bf16 v[32:35], v[216:219], v[170:173], v[32:35]
	v_mfma_f32_16x16x32_bf16 v[20:23], v[208:211], v[178:181], v[20:23]
	v_mfma_f32_16x16x32_bf16 v[12:15], v[216:219], v[178:181], v[12:15]
	v_mfma_f32_16x16x32_bf16 v[4:7], v[208:211], v[200:203], v[4:7]
	v_mfma_f32_16x16x32_bf16 v[0:3], v[216:219], v[200:203], v[0:3]
	v_mfma_f32_16x16x32_bf16 v[52:55], v[212:215], v[166:169], v[52:55]
	v_mfma_f32_16x16x32_bf16 v[44:47], v[220:223], v[166:169], v[44:47]
	v_mfma_f32_16x16x32_bf16 v[36:39], v[212:215], v[174:177], v[36:39]
	v_mfma_f32_16x16x32_bf16 v[32:35], v[220:223], v[174:177], v[32:35]
	v_mfma_f32_16x16x32_bf16 v[20:23], v[212:215], v[196:199], v[20:23]
	v_mfma_f32_16x16x32_bf16 v[12:15], v[220:223], v[196:199], v[12:15]
	v_mfma_f32_16x16x32_bf16 v[4:7], v[212:215], v[204:207], v[4:7]
	v_mfma_f32_16x16x32_bf16 v[0:3], v[220:223], v[204:207], v[0:3]
	s_add_i32 s50, s50, 2
	s_add_u32 s14, s14, 0x100
	s_addc_u32 s15, s15, 0
	s_add_u32 s48, s48, 0x100
	s_addc_u32 s49, s49, 0
	s_cmp_gt_u32 s50, 13
	s_barrier
	s_cbranch_scc0 .LBB0_1829
	v_mov_b32_e32 v144, v182
	s_lshl_b32 s5, s43, 10
	s_add_i32 s5, s5, 0
	v_and_or_b32 v141, v144, 15, s39
	v_lshl_add_u32 v140, s44, 8, v141
	v_lshl_add_u32 v141, v141, 2, s5
	v_add_u32_e32 v146, 0x20000, v141
	ds_read2_b32 v[148:149], v146 offset1:16
	v_max_f32_e32 v124, 0, v124
	v_max_f32_e32 v125, 0, v125
	v_max_f32_e32 v126, 0, v126
	v_max_f32_e32 v127, 0, v127
	v_max_f32_e32 v120, 0, v120
	v_max_f32_e32 v121, 0, v121
	s_waitcnt lgkmcnt(0)
	v_pk_mul_f32 v[124:125], v[124:125], v[148:149] op_sel_hi:[1,0]
	v_pk_mul_f32 v[126:127], v[126:127], v[148:149] op_sel_hi:[1,0]
	v_pk_mul_f32 v[120:121], v[120:121], v[148:149] op_sel_hi:[1,0]
	v_pk_mul_f32 v[124:125], v[124:125], v[124:125]
	v_pk_mul_f32 v[126:127], v[126:127], v[126:127]
	v_max_f32_e32 v122, 0, v122
	v_max_f32_e32 v123, 0, v123
	v_pk_mul_f32 v[120:121], v[120:121], v[120:121]
	v_max_f32_e32 v116, 0, v116
	v_max_f32_e32 v117, 0, v117
	v_max_f32_e32 v118, 0, v118
	v_max_f32_e32 v119, 0, v119
	v_max_f32_e32 v108, 0, v108
	v_max_f32_e32 v109, 0, v109
	s_lshl_b32 s14, s45, 8
	v_ashrrev_i32_e32 v141, 31, v140
	v_cvt_pk_bf16_f32 v124, v124, v125
	v_cvt_pk_bf16_f32 v125, v126, v127
	v_cvt_pk_bf16_f32 v126, v120, v121
	v_pk_mul_f32 v[120:121], v[122:123], v[148:149] op_sel_hi:[1,0]
	v_pk_mul_f32 v[116:117], v[116:117], v[148:149] op_sel_hi:[1,0]
	v_pk_mul_f32 v[118:119], v[118:119], v[148:149] op_sel_hi:[1,0]
	v_pk_mul_f32 v[108:109], v[108:109], v[148:149] op_sel_hi:[1,0]
	s_ashr_i32 s15, s14, 31
	v_lshlrev_b64 v[150:151], 13, v[140:141]
	v_pk_mul_f32 v[120:121], v[120:121], v[120:121]
	v_pk_mul_f32 v[116:117], v[116:117], v[116:117]
	v_pk_mul_f32 v[118:119], v[118:119], v[118:119]
	v_max_f32_e32 v110, 0, v110
	v_max_f32_e32 v111, 0, v111
	v_pk_mul_f32 v[108:109], v[108:109], v[108:109]
	v_cvt_pk_bf16_f32 v127, v120, v121
	v_lshl_add_u64 v[120:121], s[2:3], 0, v[150:151]
	s_lshl_b64 s[14:15], s[14:15], 1
	v_cvt_pk_bf16_f32 v116, v116, v117
	v_cvt_pk_bf16_f32 v117, v118, v119
	v_cvt_pk_bf16_f32 v118, v108, v109
	v_pk_mul_f32 v[108:109], v[110:111], v[148:149] op_sel_hi:[1,0]
	v_lshl_add_u64 v[120:121], v[120:121], 0, s[14:15]
	v_pk_mul_f32 v[108:109], v[108:109], v[108:109]
	v_lshl_add_u64 v[120:121], v[120:121], 0, s[24:25]
	v_and_b32_e32 v144, 48, v144
	v_cvt_pk_bf16_f32 v119, v108, v109
	v_add_u32_e32 v108, 16, v140
	v_lshl_add_u64 v[120:121], v[120:121], 0, v[144:145]
	v_ashrrev_i32_e32 v109, 31, v108
	global_store_dwordx4 v[120:121], v[116:119], off offset:256
	v_max_f32_e32 v100, 0, v100
	v_max_f32_e32 v101, 0, v101
	v_lshlrev_b64 v[116:117], 13, v[108:109]
	v_max_f32_e32 v108, v112, v112
	v_mov_b32_e32 v112, v149
	v_max_f32_e32 v102, 0, v102
	v_max_f32_e32 v103, 0, v103
	v_max_f32_e32 v96, 0, v96
	v_max_f32_e32 v97, 0, v97
	v_pk_mul_f32 v[100:101], v[100:101], v[112:113] op_sel_hi:[1,0]
	v_pk_mul_f32 v[102:103], v[102:103], v[112:113] op_sel_hi:[1,0]
	v_pk_mul_f32 v[96:97], v[96:97], v[112:113] op_sel_hi:[1,0]
	v_pk_mul_f32 v[100:101], v[100:101], v[100:101]
	v_pk_mul_f32 v[102:103], v[102:103], v[102:103]
	v_max_f32_e32 v98, 0, v98
	v_max_f32_e32 v99, 0, v99
	v_pk_mul_f32 v[96:97], v[96:97], v[96:97]
	v_cvt_pk_bf16_f32 v100, v100, v101
	v_cvt_pk_bf16_f32 v101, v102, v103
	v_cvt_pk_bf16_f32 v102, v96, v97
	v_pk_mul_f32 v[96:97], v[98:99], v[112:113] op_sel_hi:[1,0]
	ds_read2_b32 v[98:99], v146 offset0:32 offset1:48
	v_max_f32_e32 v92, 0, v92
	v_max_f32_e32 v93, 0, v93
	v_max_f32_e32 v94, 0, v94
	v_max_f32_e32 v95, 0, v95
	v_max_f32_e32 v88, 0, v88
	v_max_f32_e32 v89, 0, v89
	v_pk_mul_f32 v[96:97], v[96:97], v[96:97]
	s_waitcnt lgkmcnt(0)
;   DI void operator()(const f32x4 (&acc)[2][2][4][2], const pg8::Unit& u, int wr, int wc, int fr_, int fq_) const {
;     ...
;               if (n == 0) {
;                 const f32x4 v1 = acc[ai][bj][m][1];
;                 u32x4 o4;
;                 { const float t0 = fmaxf(v[0], 0.f) * rinv, t1 = fmaxf(v[1], 0.f) * rinv, t2 = fmaxf(v[2], 0.f) * rinv, t3 = fmaxf(v[3], 0.f) * rinv;
;                   o4.x = pack2(t0 * t0, t1 * t1); o4.y = pack2(t2 * t2, t3 * t3); }
;                 { const float t0 = fmaxf(v1[0], 0.f) * rinv, t1 = fmaxf(v1[1], 0.f) * rinv, t2 = fmaxf(v1[2], 0.f) * rinv, t3 = fmaxf(v1[3], 0.f) * rinv;
;                   o4.z = pack2(t0 * t0, t1 * t1); o4.w = pack2(t2 * t2, t3 * t3); }
;                 *(u32x4*)((u16*)big + (size_t)token * 4096 + u.pn * 256 + bj * 128 + wc * 32 + 8 * fq) = o4;
	v_pk_mul_f32 v[92:93], v[92:93], v[98:99] op_sel_hi:[1,0]
	v_pk_mul_f32 v[94:95], v[94:95], v[98:99] op_sel_hi:[1,0]
	v_pk_mul_f32 v[88:89], v[88:89], v[98:99] op_sel_hi:[1,0]
	v_cvt_pk_bf16_f32 v103, v96, v97
	v_add_u32_e32 v96, 32, v140
	v_pk_mul_f32 v[92:93], v[92:93], v[92:93]
	v_pk_mul_f32 v[94:95], v[94:95], v[94:95]
	v_max_f32_e32 v90, 0, v90
	v_max_f32_e32 v91, 0, v91
	v_pk_mul_f32 v[88:89], v[88:89], v[88:89]
	v_max_f32_e32 v84, 0, v84
	v_max_f32_e32 v85, 0, v85
	v_max_f32_e32 v86, 0, v86
	v_max_f32_e32 v87, 0, v87
	v_max_f32_e32 v76, 0, v76
	v_max_f32_e32 v77, 0, v77
	v_ashrrev_i32_e32 v97, 31, v96
	v_cvt_pk_bf16_f32 v92, v92, v93
	v_cvt_pk_bf16_f32 v93, v94, v95
	v_cvt_pk_bf16_f32 v94, v88, v89
	v_pk_mul_f32 v[88:89], v[90:91], v[98:99] op_sel_hi:[1,0]
	v_pk_mul_f32 v[84:85], v[84:85], v[98:99] op_sel_hi:[1,0]
	v_pk_mul_f32 v[86:87], v[86:87], v[98:99] op_sel_hi:[1,0]
	v_pk_mul_f32 v[76:77], v[76:77], v[98:99] op_sel_hi:[1,0]
	v_lshlrev_b64 v[96:97], 13, v[96:97]
	v_pk_mul_f32 v[88:89], v[88:89], v[88:89]
	v_pk_mul_f32 v[84:85], v[84:85], v[84:85]
	v_pk_mul_f32 v[86:87], v[86:87], v[86:87]
	v_max_f32_e32 v78, 0, v78
	v_max_f32_e32 v79, 0, v79
	v_pk_mul_f32 v[76:77], v[76:77], v[76:77]
	v_cvt_pk_bf16_f32 v95, v88, v89
	v_lshl_add_u64 v[88:89], s[2:3], 0, v[96:97]
	v_cvt_pk_bf16_f32 v84, v84, v85
	v_cvt_pk_bf16_f32 v85, v86, v87
	v_cvt_pk_bf16_f32 v86, v76, v77
	v_pk_mul_f32 v[76:77], v[78:79], v[98:99] op_sel_hi:[1,0]
	v_lshl_add_u64 v[88:89], v[88:89], 0, s[14:15]
	v_pk_mul_f32 v[76:77], v[76:77], v[76:77]
	v_lshl_add_u64 v[88:89], v[88:89], 0, s[24:25]
	v_cvt_pk_bf16_f32 v87, v76, v77
	v_add_u32_e32 v76, 48, v140
	v_lshl_add_u64 v[88:89], v[88:89], 0, v[144:145]
	v_ashrrev_i32_e32 v77, 31, v76
	global_store_dwordx4 v[88:89], v[84:87], off offset:256
	v_max_f32_e32 v68, 0, v68
	v_max_f32_e32 v69, 0, v69
	v_lshlrev_b64 v[84:85], 13, v[76:77]
	v_max_f32_e32 v76, v80, v80
	v_mov_b32_e32 v80, v99
	v_max_f32_e32 v70, 0, v70
	v_max_f32_e32 v71, 0, v71
	v_max_f32_e32 v64, 0, v64
	v_max_f32_e32 v65, 0, v65
	v_pk_mul_f32 v[68:69], v[68:69], v[80:81] op_sel_hi:[1,0]
	v_pk_mul_f32 v[70:71], v[70:71], v[80:81] op_sel_hi:[1,0]
	v_pk_mul_f32 v[64:65], v[64:65], v[80:81] op_sel_hi:[1,0]
	v_pk_mul_f32 v[68:69], v[68:69], v[68:69]
	v_pk_mul_f32 v[70:71], v[70:71], v[70:71]
	v_max_f32_e32 v66, 0, v66
	v_max_f32_e32 v67, 0, v67
	v_pk_mul_f32 v[64:65], v[64:65], v[64:65]
	v_cvt_pk_bf16_f32 v68, v68, v69
	v_cvt_pk_bf16_f32 v69, v70, v71
	v_cvt_pk_bf16_f32 v70, v64, v65
	v_pk_mul_f32 v[64:65], v[66:67], v[80:81] op_sel_hi:[1,0]
	ds_read2_b32 v[66:67], v146 offset0:128 offset1:144
	v_max_f32_e32 v60, 0, v60
	v_max_f32_e32 v61, 0, v61
	v_max_f32_e32 v62, 0, v62
	v_max_f32_e32 v63, 0, v63
	v_max_f32_e32 v56, 0, v56
	v_max_f32_e32 v57, 0, v57
	v_pk_mul_f32 v[64:65], v[64:65], v[64:65]
	s_waitcnt lgkmcnt(0)
	v_pk_mul_f32 v[60:61], v[60:61], v[66:67] op_sel_hi:[1,0]
	v_pk_mul_f32 v[62:63], v[62:63], v[66:67] op_sel_hi:[1,0]
	v_pk_mul_f32 v[56:57], v[56:57], v[66:67] op_sel_hi:[1,0]
	v_cvt_pk_bf16_f32 v71, v64, v65
	v_add_u32_e32 v64, 0x80, v140
	v_pk_mul_f32 v[60:61], v[60:61], v[60:61]
	v_pk_mul_f32 v[62:63], v[62:63], v[62:63]
	v_max_f32_e32 v58, 0, v58
	v_max_f32_e32 v59, 0, v59
	v_pk_mul_f32 v[56:57], v[56:57], v[56:57]
	v_max_f32_e32 v52, 0, v52
	v_max_f32_e32 v53, 0, v53
	v_max_f32_e32 v54, 0, v54
	v_max_f32_e32 v55, 0, v55
	v_max_f32_e32 v44, 0, v44
	v_max_f32_e32 v45, 0, v45
	v_ashrrev_i32_e32 v65, 31, v64
	v_cvt_pk_bf16_f32 v60, v60, v61
	v_cvt_pk_bf16_f32 v61, v62, v63
	v_cvt_pk_bf16_f32 v62, v56, v57
	v_pk_mul_f32 v[56:57], v[58:59], v[66:67] op_sel_hi:[1,0]
	v_pk_mul_f32 v[52:53], v[52:53], v[66:67] op_sel_hi:[1,0]
	v_pk_mul_f32 v[54:55], v[54:55], v[66:67] op_sel_hi:[1,0]
	v_pk_mul_f32 v[44:45], v[44:45], v[66:67] op_sel_hi:[1,0]
	v_lshlrev_b64 v[64:65], 13, v[64:65]
	v_pk_mul_f32 v[56:57], v[56:57], v[56:57]
	v_pk_mul_f32 v[52:53], v[52:53], v[52:53]
	v_pk_mul_f32 v[54:55], v[54:55], v[54:55]
	v_max_f32_e32 v46, 0, v46
	v_max_f32_e32 v47, 0, v47
	v_pk_mul_f32 v[44:45], v[44:45], v[44:45]
	v_cvt_pk_bf16_f32 v63, v56, v57
	v_lshl_add_u64 v[56:57], s[2:3], 0, v[64:65]
	v_cvt_pk_bf16_f32 v52, v52, v53
	v_cvt_pk_bf16_f32 v53, v54, v55
	v_cvt_pk_bf16_f32 v54, v44, v45
	v_pk_mul_f32 v[44:45], v[46:47], v[66:67] op_sel_hi:[1,0]
	v_lshl_add_u64 v[56:57], v[56:57], 0, s[14:15]
	v_pk_mul_f32 v[44:45], v[44:45], v[44:45]
	v_lshl_add_u64 v[56:57], v[56:57], 0, s[24:25]
	v_cvt_pk_bf16_f32 v55, v44, v45
	v_add_u32_e32 v44, 0x90, v140
	v_lshl_add_u64 v[56:57], v[56:57], 0, v[144:145]
	v_ashrrev_i32_e32 v45, 31, v44
	global_store_dwordx4 v[56:57], v[52:55], off offset:256
	v_max_f32_e32 v36, 0, v36
	v_max_f32_e32 v37, 0, v37
	v_lshlrev_b64 v[52:53], 13, v[44:45]
	v_max_f32_e32 v44, v48, v48
	v_mov_b32_e32 v48, v67
	v_max_f32_e32 v38, 0, v38
	v_max_f32_e32 v39, 0, v39
	v_max_f32_e32 v32, 0, v32
	v_max_f32_e32 v33, 0, v33
	v_pk_mul_f32 v[36:37], v[36:37], v[48:49] op_sel_hi:[1,0]
	v_pk_mul_f32 v[38:39], v[38:39], v[48:49] op_sel_hi:[1,0]
	v_pk_mul_f32 v[32:33], v[32:33], v[48:49] op_sel_hi:[1,0]
	v_pk_mul_f32 v[36:37], v[36:37], v[36:37]
	v_pk_mul_f32 v[38:39], v[38:39], v[38:39]
	v_max_f32_e32 v34, 0, v34
	v_max_f32_e32 v35, 0, v35
	v_pk_mul_f32 v[32:33], v[32:33], v[32:33]
	v_cvt_pk_bf16_f32 v36, v36, v37
	v_cvt_pk_bf16_f32 v37, v38, v39
	v_cvt_pk_bf16_f32 v38, v32, v33
	v_pk_mul_f32 v[32:33], v[34:35], v[48:49] op_sel_hi:[1,0]
	ds_read2_b32 v[34:35], v146 offset0:160 offset1:176
	v_max_f32_e32 v28, 0, v28
	v_max_f32_e32 v29, 0, v29
	v_max_f32_e32 v30, 0, v30
	v_max_f32_e32 v31, 0, v31
	v_max_f32_e32 v24, 0, v24
	v_max_f32_e32 v25, 0, v25
	v_pk_mul_f32 v[32:33], v[32:33], v[32:33]
	s_waitcnt lgkmcnt(0)
;   DI void operator()(const f32x4 (&acc)[2][2][4][2], const pg8::Unit& u, int wr, int wc, int fr_, int fq_) const {
;     ...
;               if (n == 0) {
;                 const f32x4 v1 = acc[ai][bj][m][1];
;                 u32x4 o4;
;                 { const float t0 = fmaxf(v[0], 0.f) * rinv, t1 = fmaxf(v[1], 0.f) * rinv, t2 = fmaxf(v[2], 0.f) * rinv, t3 = fmaxf(v[3], 0.f) * rinv;
;                   o4.x = pack2(t0 * t0, t1 * t1); o4.y = pack2(t2 * t2, t3 * t3); }
;                 { const float t0 = fmaxf(v1[0], 0.f) * rinv, t1 = fmaxf(v1[1], 0.f) * rinv, t2 = fmaxf(v1[2], 0.f) * rinv, t3 = fmaxf(v1[3], 0.f) * rinv;
;                   o4.z = pack2(t0 * t0, t1 * t1); o4.w = pack2(t2 * t2, t3 * t3); }
;                 *(u32x4*)((u16*)big + (size_t)token * 4096 + u.pn * 256 + bj * 128 + wc * 32 + 8 * fq) = o4;
;               }
	v_pk_mul_f32 v[28:29], v[28:29], v[34:35] op_sel_hi:[1,0]
	v_pk_mul_f32 v[30:31], v[30:31], v[34:35] op_sel_hi:[1,0]
	v_pk_mul_f32 v[24:25], v[24:25], v[34:35] op_sel_hi:[1,0]
	v_cvt_pk_bf16_f32 v39, v32, v33
	v_add_u32_e32 v32, 0xa0, v140
	v_pk_mul_f32 v[28:29], v[28:29], v[28:29]
	v_pk_mul_f32 v[30:31], v[30:31], v[30:31]
	v_max_f32_e32 v26, 0, v26
	v_max_f32_e32 v27, 0, v27
	v_pk_mul_f32 v[24:25], v[24:25], v[24:25]
	v_max_f32_e32 v20, 0, v20
	v_max_f32_e32 v21, 0, v21
	v_max_f32_e32 v22, 0, v22
	v_max_f32_e32 v23, 0, v23
	v_max_f32_e32 v12, 0, v12
	v_max_f32_e32 v13, 0, v13
	v_ashrrev_i32_e32 v33, 31, v32
	v_cvt_pk_bf16_f32 v28, v28, v29
	v_cvt_pk_bf16_f32 v29, v30, v31
	v_cvt_pk_bf16_f32 v30, v24, v25
	v_pk_mul_f32 v[24:25], v[26:27], v[34:35] op_sel_hi:[1,0]
	v_pk_mul_f32 v[20:21], v[20:21], v[34:35] op_sel_hi:[1,0]
	v_pk_mul_f32 v[22:23], v[22:23], v[34:35] op_sel_hi:[1,0]
	v_pk_mul_f32 v[12:13], v[12:13], v[34:35] op_sel_hi:[1,0]
	v_lshlrev_b64 v[32:33], 13, v[32:33]
	v_pk_mul_f32 v[24:25], v[24:25], v[24:25]
	v_pk_mul_f32 v[20:21], v[20:21], v[20:21]
	v_pk_mul_f32 v[22:23], v[22:23], v[22:23]
	v_max_f32_e32 v14, 0, v14
	v_max_f32_e32 v15, 0, v15
	v_pk_mul_f32 v[12:13], v[12:13], v[12:13]
	v_cvt_pk_bf16_f32 v31, v24, v25
	v_lshl_add_u64 v[24:25], s[2:3], 0, v[32:33]
	v_cvt_pk_bf16_f32 v20, v20, v21
	v_cvt_pk_bf16_f32 v21, v22, v23
	v_cvt_pk_bf16_f32 v22, v12, v13
	v_pk_mul_f32 v[12:13], v[14:15], v[34:35] op_sel_hi:[1,0]
	v_lshl_add_u64 v[24:25], v[24:25], 0, s[14:15]
	v_pk_mul_f32 v[12:13], v[12:13], v[12:13]
	v_lshl_add_u64 v[24:25], v[24:25], 0, s[24:25]
	v_cvt_pk_bf16_f32 v23, v12, v13
	v_add_u32_e32 v12, 0xb0, v140
	v_lshl_add_u64 v[24:25], v[24:25], 0, v[144:145]
	v_ashrrev_i32_e32 v13, 31, v12
	v_max_f32_e32 v109, v113, v113
	v_max_f32_e32 v110, v114, v114
	v_max_f32_e32 v111, v115, v115
	v_max_f32_e32 v77, v81, v81
	v_max_f32_e32 v78, v82, v82
	v_max_f32_e32 v79, v83, v83
	v_max_f32_e32 v45, v49, v49
	v_max_f32_e32 v46, v50, v50
	v_max_f32_e32 v47, v51, v51
	global_store_dwordx4 v[24:25], v[20:23], off offset:256
	v_max_f32_e32 v14, v18, v18
	v_max_f32_e32 v15, v19, v19
	v_lshlrev_b64 v[20:21], 13, v[12:13]
	v_max_f32_e32 v12, v16, v16
	v_max_f32_e32 v13, v17, v17
	v_max_f32_e32 v108, 0, v108
	v_max_f32_e32 v109, 0, v109
	v_max_f32_e32 v110, 0, v110
	v_max_f32_e32 v111, 0, v111
	v_max_f32_e32 v104, 0, v104
	v_max_f32_e32 v105, 0, v105
	v_max_f32_e32 v76, 0, v76
	v_max_f32_e32 v77, 0, v77
	v_max_f32_e32 v78, 0, v78
	v_max_f32_e32 v79, 0, v79
	v_max_f32_e32 v72, 0, v72
	v_max_f32_e32 v73, 0, v73
	v_max_f32_e32 v44, 0, v44
	v_max_f32_e32 v45, 0, v45
	v_max_f32_e32 v46, 0, v46
	v_max_f32_e32 v47, 0, v47
	v_max_f32_e32 v40, 0, v40
	v_max_f32_e32 v41, 0, v41
	v_max_f32_e32 v12, 0, v12
	v_max_f32_e32 v13, 0, v13
	v_max_f32_e32 v14, 0, v14
	v_max_f32_e32 v15, 0, v15
	v_mov_b32_e32 v16, v35
	v_max_f32_e32 v8, 0, v8
	v_max_f32_e32 v9, 0, v9
	v_pk_mul_f32 v[108:109], v[108:109], v[112:113] op_sel_hi:[1,0]
	v_pk_mul_f32 v[110:111], v[110:111], v[112:113] op_sel_hi:[1,0]
	v_pk_mul_f32 v[104:105], v[104:105], v[112:113] op_sel_hi:[1,0]
	v_pk_mul_f32 v[76:77], v[76:77], v[80:81] op_sel_hi:[1,0]
	v_pk_mul_f32 v[78:79], v[78:79], v[80:81] op_sel_hi:[1,0]
	v_pk_mul_f32 v[72:73], v[72:73], v[80:81] op_sel_hi:[1,0]
	v_pk_mul_f32 v[44:45], v[44:45], v[48:49] op_sel_hi:[1,0]
	v_pk_mul_f32 v[46:47], v[46:47], v[48:49] op_sel_hi:[1,0]
	v_pk_mul_f32 v[40:41], v[40:41], v[48:49] op_sel_hi:[1,0]
	v_pk_mul_f32 v[12:13], v[12:13], v[16:17] op_sel_hi:[1,0]
	v_pk_mul_f32 v[14:15], v[14:15], v[16:17] op_sel_hi:[1,0]
	v_pk_mul_f32 v[8:9], v[8:9], v[16:17] op_sel_hi:[1,0]
	v_pk_mul_f32 v[108:109], v[108:109], v[108:109]
	v_pk_mul_f32 v[110:111], v[110:111], v[110:111]
	v_max_f32_e32 v106, 0, v106
	v_max_f32_e32 v107, 0, v107
	v_pk_mul_f32 v[104:105], v[104:105], v[104:105]
; #define PG8_WAIT_V(n) asm volatile("s_waitcnt vmcnt(" #n ")" ::: "memory")
; #define PG8_BAR __builtin_amdgcn_s_barrier()
; template <class Epi, class Sched>
; DI void gemm_phase(LAS unsigned char* lds, const Gemm g, const Sched& S, const Epi& E) {
;     ...
;     E(acc, cur, wr, wc, fr, fq);
;     if (!has_next) break;
; #pragma unroll
;     for (int a = 0; a < 2; ++a)
; #pragma unroll
;       for (int b = 0; b < 2; ++b)
; #pragma unroll
;         for (int m = 0; m < 4; ++m)
; #pragma unroll
;           for (int n = 0; n < 2; ++n) acc[a][b][m][n] = (f32x4){0.f, 0.f, 0.f, 0.f};
;     cur = nxt; cA = nA; cB = nB; ++ui;
;   }
;   PG8_WAIT_V(0);
;   if (wr == 0) PG8_BAR;
;   PG8_BAR;
;   DI void operator()(const f32x4 (&acc)[2][2][4][2], const pg8::Unit& u, int wr, int wc, int fr_, int fq_) const {
;     ...
;               if (n == 0) {
;                 const f32x4 v1 = acc[ai][bj][m][1];
;                 u32x4 o4;
;                 { const float t0 = fmaxf(v[0], 0.f) * rinv, t1 = fmaxf(v[1], 0.f) * rinv, t2 = fmaxf(v[2], 0.f) * rinv, t3 = fmaxf(v[3], 0.f) * rinv;
;                   o4.x = pack2(t0 * t0, t1 * t1); o4.y = pack2(t2 * t2, t3 * t3); }
;                 { const float t0 = fmaxf(v1[0], 0.f) * rinv, t1 = fmaxf(v1[1], 0.f) * rinv, t2 = fmaxf(v1[2], 0.f) * rinv, t3 = fmaxf(v1[3], 0.f) * rinv;
;                   o4.z = pack2(t0 * t0, t1 * t1); o4.w = pack2(t2 * t2, t3 * t3); }
;                 *(u32x4*)((u16*)big + (size_t)token * 4096 + u.pn * 256 + bj * 128 + wc * 32 + 8 * fq) = o4;
;               }
	v_pk_mul_f32 v[76:77], v[76:77], v[76:77]
	v_pk_mul_f32 v[78:79], v[78:79], v[78:79]
	v_max_f32_e32 v74, 0, v74
	v_max_f32_e32 v75, 0, v75
	v_pk_mul_f32 v[72:73], v[72:73], v[72:73]
	v_pk_mul_f32 v[44:45], v[44:45], v[44:45]
	v_pk_mul_f32 v[46:47], v[46:47], v[46:47]
	v_max_f32_e32 v42, 0, v42
	v_max_f32_e32 v43, 0, v43
	v_pk_mul_f32 v[40:41], v[40:41], v[40:41]
	v_pk_mul_f32 v[12:13], v[12:13], v[12:13]
	v_pk_mul_f32 v[14:15], v[14:15], v[14:15]
	v_max_f32_e32 v10, 0, v10
	v_max_f32_e32 v11, 0, v11
	v_pk_mul_f32 v[8:9], v[8:9], v[8:9]
	v_cvt_pk_bf16_f32 v108, v108, v109
	v_cvt_pk_bf16_f32 v109, v110, v111
	v_cvt_pk_bf16_f32 v110, v104, v105
	v_pk_mul_f32 v[104:105], v[106:107], v[112:113] op_sel_hi:[1,0]
	v_cvt_pk_bf16_f32 v76, v76, v77
	v_cvt_pk_bf16_f32 v77, v78, v79
	v_cvt_pk_bf16_f32 v78, v72, v73
	v_pk_mul_f32 v[72:73], v[74:75], v[80:81] op_sel_hi:[1,0]
	v_cvt_pk_bf16_f32 v44, v44, v45
	v_cvt_pk_bf16_f32 v45, v46, v47
	v_cvt_pk_bf16_f32 v46, v40, v41
	v_pk_mul_f32 v[40:41], v[42:43], v[48:49] op_sel_hi:[1,0]
	v_cvt_pk_bf16_f32 v12, v12, v13
	v_cvt_pk_bf16_f32 v13, v14, v15
	v_cvt_pk_bf16_f32 v14, v8, v9
	v_pk_mul_f32 v[8:9], v[10:11], v[16:17] op_sel_hi:[1,0]
	v_max_f32_e32 v4, 0, v4
	v_max_f32_e32 v5, 0, v5
	v_max_f32_e32 v6, 0, v6
	v_max_f32_e32 v7, 0, v7
	v_max_f32_e32 v0, 0, v0
	v_max_f32_e32 v1, 0, v1
	v_pk_mul_f32 v[104:105], v[104:105], v[104:105]
	v_pk_mul_f32 v[72:73], v[72:73], v[72:73]
	v_pk_mul_f32 v[40:41], v[40:41], v[40:41]
	v_pk_mul_f32 v[8:9], v[8:9], v[8:9]
	v_pk_mul_f32 v[4:5], v[4:5], v[16:17] op_sel_hi:[1,0]
	v_pk_mul_f32 v[6:7], v[6:7], v[16:17] op_sel_hi:[1,0]
	v_pk_mul_f32 v[0:1], v[0:1], v[16:17] op_sel_hi:[1,0]
	v_cvt_pk_bf16_f32 v111, v104, v105
	v_lshl_add_u64 v[104:105], s[2:3], 0, v[116:117]
	v_cvt_pk_bf16_f32 v79, v72, v73
	v_lshl_add_u64 v[72:73], s[2:3], 0, v[84:85]
	v_cvt_pk_bf16_f32 v47, v40, v41
	v_lshl_add_u64 v[40:41], s[2:3], 0, v[52:53]
	v_cvt_pk_bf16_f32 v15, v8, v9
	v_lshl_add_u64 v[8:9], s[2:3], 0, v[20:21]
	v_pk_mul_f32 v[4:5], v[4:5], v[4:5]
	v_pk_mul_f32 v[6:7], v[6:7], v[6:7]
	v_max_f32_e32 v2, 0, v2
	v_max_f32_e32 v3, 0, v3
	v_pk_mul_f32 v[0:1], v[0:1], v[0:1]
	v_lshl_add_u64 v[104:105], v[104:105], 0, s[14:15]
	v_lshl_add_u64 v[72:73], v[72:73], 0, s[14:15]
	v_lshl_add_u64 v[40:41], v[40:41], 0, s[14:15]
	v_lshl_add_u64 v[8:9], v[8:9], 0, s[14:15]
	v_cvt_pk_bf16_f32 v4, v4, v5
	v_cvt_pk_bf16_f32 v5, v6, v7
	v_cvt_pk_bf16_f32 v6, v0, v1
	v_pk_mul_f32 v[0:1], v[2:3], v[16:17] op_sel_hi:[1,0]
	v_lshl_add_u64 v[104:105], v[104:105], 0, s[24:25]
	v_lshl_add_u64 v[72:73], v[72:73], 0, s[24:25]
	v_lshl_add_u64 v[40:41], v[40:41], 0, s[24:25]
	v_lshl_add_u64 v[8:9], v[8:9], 0, s[24:25]
	v_pk_mul_f32 v[0:1], v[0:1], v[0:1]
	v_lshl_add_u64 v[104:105], v[104:105], 0, v[144:145]
	v_lshl_add_u64 v[72:73], v[72:73], 0, v[144:145]
	v_lshl_add_u64 v[40:41], v[40:41], 0, v[144:145]
	v_lshl_add_u64 v[8:9], v[8:9], 0, v[144:145]
	v_cvt_pk_bf16_f32 v7, v0, v1
	s_and_b64 vcc, exec, s[36:37]
	s_mov_b32 s43, s42
	s_mov_b32 s45, s4
	s_mov_b32 s44, s6
	s_mov_b64 s[16:17], s[12:13]
	s_mov_b64 s[14:15], s[10:11]
	v_readlane_b32 s51, v237, 11
	global_store_dwordx4 v[120:121], v[124:127], off
	global_store_dwordx4 v[104:105], v[108:111], off
	global_store_dwordx4 v[104:105], v[100:103], off offset:256
	global_store_dwordx4 v[88:89], v[92:95], off
	global_store_dwordx4 v[72:73], v[76:79], off
	global_store_dwordx4 v[72:73], v[68:71], off offset:256
	global_store_dwordx4 v[56:57], v[60:63], off
	global_store_dwordx4 v[40:41], v[44:47], off
	global_store_dwordx4 v[40:41], v[36:39], off offset:256
	global_store_dwordx4 v[24:25], v[28:31], off
	global_store_dwordx4 v[8:9], v[12:15], off
	global_store_dwordx4 v[8:9], v[4:7], off offset:256
	s_cbranch_vccz .LBB0_1822
	s_waitcnt vmcnt(0)
	s_cmpk_gt_u32 s9, 0xff
	s_cbranch_scc1 .LBB0_1833
	s_barrier

; #define PG8_STAGE(bufoff, gbase, voff) do { _Pragma("unroll") for (int _i = 0; _i < 2; ++_i) \
;     __builtin_amdgcn_global_load_lds((const unsigned*)((const char*)(gbase) + (voff)[_i]), (LAS unsigned*)(lds + (bufoff) + ldsw + _i * 8192), 16, 0, 0); } while (0)
; #define PG8_LDA(dst, b, h) do { _Pragma("unroll") for (int m = 0; m < 4; ++m) _Pragma("unroll") for (int k = 0; k < 2; ++k) dst[m][k] = *(const LAS bf16x8*)(lds + PG8_SA(b, h) + aoff + m * 2048 + k * 1024); } while (0)
; #define PG8_LDB(dst, b, h) do { _Pragma("unroll") for (int n = 0; n < 2; ++n) _Pragma("unroll") for (int k = 0; k < 2; ++k) dst[n][k] = *(const LAS bf16x8*)(lds + PG8_SB(b, h) + boff + n * 2048 + k * 1024); } while (0)
; #define PG8_MMA(ai, bj, At, Bt) do { __builtin_amdgcn_s_setprio(1); _Pragma("unroll") for (int m = 0; m < 4; ++m) _Pragma("unroll") for (int n = 0; n < 2; ++n) _Pragma("unroll") for (int k = 0; k < 2; ++k) \
;     acc[ai][bj][m][n] = __builtin_amdgcn_mfma_f32_16x16x32_bf16(Bt[n][k], At[m][k], acc[ai][bj][m][n], 0, 0, 0); __builtin_amdgcn_s_setprio(0); } while (0)
; #define PG8_WAIT_V(n) asm volatile("s_waitcnt vmcnt(" #n ")" ::: "memory")
; #define PG8_WAIT_L(n) asm volatile("s_waitcnt lgkmcnt(" #n ")" ::: "memory")
; #define PG8_BAR __builtin_amdgcn_s_barrier()
; #define PG8_SCHED __builtin_amdgcn_sched_barrier(0)
; template <class Epi, class Sched>
; DI void gemm_phase(LAS unsigned char* lds, const Gemm g, const Sched& S, const Epi& E) {
;     ...
;       const bool last = (t == nt - 2);
;       const char* a1 = cA + (size_t)(t + 1) * kstep;
;       const char* a2 = last ? nA : cA + (size_t)(t + 2) * kstep; const char* b2 = last ? nB : cB + (size_t)(t + 2) * kstep;
;       const char* a3 = a2 + kstep; const char* b3 = b2 + kstep;
;       PG8_LDB(B0, 0, 0); PG8_SCHED; PG8_LDA(At, 0, 0); PG8_STAGE(PG8_SA(1, 1), a1 + hstep, voffA);
;       PG8_WAIT_L(8); PG8_BAR; PG8_WAIT_L(0); PG8_MMA(0, 0, At, B0); PG8_BAR; PG8_SCHED;
;       PG8_LDB(B1, 0, 1); PG8_STAGE(PG8_SB(0, 0), b2, voffB);
;       PG8_BAR; PG8_WAIT_L(0); PG8_MMA(0, 1, At, B1); PG8_BAR;
;       PG8_LDA(At, 0, 1); PG8_STAGE(PG8_SA(0, 0), a2, voffA);
;       PG8_BAR; PG8_WAIT_L(0); PG8_MMA(1, 0, At, B0); PG8_BAR; PG8_SCHED;
;       PG8_STAGE(PG8_SB(0, 1), b2 + hstep, voffB);
;       PG8_WAIT_V(6); PG8_BAR; PG8_MMA(1, 1, At, B1); PG8_BAR;
.LBB0_1905:
	s_add_u32 s22, s20, 0xfff00080
	s_addc_u32 s23, s21, -1
	s_add_i32 s51, 0, 0x10000
	ds_read_b128 v[138:141], v224
	ds_read_b128 v[148:151], v224 offset:1024
	ds_read_b128 v[152:155], v224 offset:2048
	ds_read_b128 v[156:159], v224 offset:3072
	s_cmp_eq_u32 s50, 60
	s_cselect_b32 s29, s11, s23
	s_cselect_b32 s28, s17, s22
	s_cselect_b32 s23, s7, s49
	s_cselect_b32 s22, s19, s24
	s_add_i32 m0, s39, 0xc000
	ds_read_b128 v[160:163], v147
	ds_read_b128 v[164:167], v147 offset:1024
	ds_read_b128 v[168:171], v147 offset:2048
	ds_read_b128 v[172:175], v147 offset:3072
	ds_read_b128 v[176:179], v147 offset:4096
	ds_read_b128 v[196:199], v147 offset:5120
	ds_read_b128 v[200:203], v147 offset:6144
	ds_read_b128 v[204:207], v147 offset:7168
	global_load_lds_dwordx4 v134, s[20:21]
	s_add_i32 m0, s39, 0xe000
	s_nop 0
	global_load_lds_dwordx4 v136, s[20:21]
	s_waitcnt lgkmcnt(8)
	s_barrier
	s_waitcnt lgkmcnt(0)
	v_mfma_f32_16x16x32_bf16 v[124:127], v[138:141], v[160:163], v[124:127]
	v_mfma_f32_16x16x32_bf16 v[120:123], v[152:155], v[160:163], v[120:123]
	v_mfma_f32_16x16x32_bf16 v[108:111], v[138:141], v[168:171], v[108:111]
	v_mfma_f32_16x16x32_bf16 v[104:107], v[152:155], v[168:171], v[104:107]
	v_mfma_f32_16x16x32_bf16 v[92:95], v[138:141], v[176:179], v[92:95]
	v_mfma_f32_16x16x32_bf16 v[88:91], v[152:155], v[176:179], v[88:91]
	v_mfma_f32_16x16x32_bf16 v[76:79], v[138:141], v[200:203], v[76:79]
	v_mfma_f32_16x16x32_bf16 v[72:75], v[152:155], v[200:203], v[72:75]
	v_mfma_f32_16x16x32_bf16 v[124:127], v[148:151], v[164:167], v[124:127]
	v_mfma_f32_16x16x32_bf16 v[120:123], v[156:159], v[164:167], v[120:123]
	v_mfma_f32_16x16x32_bf16 v[108:111], v[148:151], v[172:175], v[108:111]
	v_mfma_f32_16x16x32_bf16 v[104:107], v[156:159], v[172:175], v[104:107]
	v_mfma_f32_16x16x32_bf16 v[92:95], v[148:151], v[196:199], v[92:95]
	v_mfma_f32_16x16x32_bf16 v[88:91], v[156:159], v[196:199], v[88:91]
	v_mfma_f32_16x16x32_bf16 v[76:79], v[148:151], v[204:207], v[76:79]
	v_mfma_f32_16x16x32_bf16 v[72:75], v[156:159], v[204:207], v[72:75]
	s_barrier
	s_add_i32 s54, 0, 0x14000
	s_add_i32 s51, s51, s38
	ds_read_b128 v[208:211], v225
	ds_read_b128 v[212:215], v225 offset:1024
	ds_read_b128 v[216:219], v225 offset:2048
	ds_read_b128 v[220:223], v225 offset:3072
	s_add_u32 vcc_lo, s22, s0
	s_addc_u32 vcc_hi, s23, s1
	s_mov_b32 m0, s51
	s_nop 0
	global_load_lds_dwordx4 v144, s[22:23]
	s_add_i32 m0, s51, 0x2000
	s_nop 0
	global_load_lds_dwordx4 v132, s[22:23]
	s_barrier
	s_waitcnt lgkmcnt(0)
	v_mfma_f32_16x16x32_bf16 v[116:119], v[208:211], v[160:163], v[116:119]
	v_mfma_f32_16x16x32_bf16 v[112:115], v[216:219], v[160:163], v[112:115]
	v_mfma_f32_16x16x32_bf16 v[100:103], v[208:211], v[168:171], v[100:103]
	v_mfma_f32_16x16x32_bf16 v[96:99], v[216:219], v[168:171], v[96:99]
	v_mfma_f32_16x16x32_bf16 v[84:87], v[208:211], v[176:179], v[84:87]
	v_mfma_f32_16x16x32_bf16 v[80:83], v[216:219], v[176:179], v[80:83]
	v_mfma_f32_16x16x32_bf16 v[68:71], v[208:211], v[200:203], v[68:71]
	v_mfma_f32_16x16x32_bf16 v[64:67], v[216:219], v[200:203], v[64:67]
	v_mfma_f32_16x16x32_bf16 v[116:119], v[212:215], v[164:167], v[116:119]
	v_mfma_f32_16x16x32_bf16 v[112:115], v[220:223], v[164:167], v[112:115]
	v_mfma_f32_16x16x32_bf16 v[100:103], v[212:215], v[172:175], v[100:103]
	v_mfma_f32_16x16x32_bf16 v[96:99], v[220:223], v[172:175], v[96:99]
	v_mfma_f32_16x16x32_bf16 v[84:87], v[212:215], v[196:199], v[84:87]
	v_mfma_f32_16x16x32_bf16 v[80:83], v[220:223], v[196:199], v[80:83]
	v_mfma_f32_16x16x32_bf16 v[68:71], v[212:215], v[204:207], v[68:71]
	v_mfma_f32_16x16x32_bf16 v[64:67], v[220:223], v[204:207], v[64:67]
	s_mov_b32 m0, s39
	s_add_u32 s100, s28, s0
	s_addc_u32 s101, s29, s1
	s_barrier
	ds_read_b128 v[160:163], v147 offset:16384
	ds_read_b128 v[164:167], v147 offset:17408
	ds_read_b128 v[168:171], v147 offset:18432
	ds_read_b128 v[172:175], v147 offset:19456
	ds_read_b128 v[176:179], v147 offset:20480
	ds_read_b128 v[196:199], v147 offset:21504
	ds_read_b128 v[200:203], v147 offset:22528
	ds_read_b128 v[204:207], v147 offset:23552
	global_load_lds_dwordx4 v128, s[28:29]
	s_mov_b32 m0, s40
	s_nop 0
	global_load_lds_dwordx4 v130, s[28:29]
	s_barrier
	s_waitcnt lgkmcnt(0)
	v_mfma_f32_16x16x32_bf16 v[60:63], v[138:141], v[160:163], v[60:63]
	v_mfma_f32_16x16x32_bf16 v[56:59], v[152:155], v[160:163], v[56:59]
	v_mfma_f32_16x16x32_bf16 v[44:47], v[138:141], v[168:171], v[44:47]
	v_mfma_f32_16x16x32_bf16 v[40:43], v[152:155], v[168:171], v[40:43]
	v_mfma_f32_16x16x32_bf16 v[28:31], v[138:141], v[176:179], v[28:31]
	v_mfma_f32_16x16x32_bf16 v[24:27], v[152:155], v[176:179], v[24:27]
	v_mfma_f32_16x16x32_bf16 v[12:15], v[138:141], v[200:203], v[12:15]
	v_mfma_f32_16x16x32_bf16 v[8:11], v[152:155], v[200:203], v[8:11]
	v_mfma_f32_16x16x32_bf16 v[60:63], v[148:151], v[164:167], v[60:63]
	v_mfma_f32_16x16x32_bf16 v[56:59], v[156:159], v[164:167], v[56:59]
	v_mfma_f32_16x16x32_bf16 v[44:47], v[148:151], v[172:175], v[44:47]
	v_mfma_f32_16x16x32_bf16 v[40:43], v[156:159], v[172:175], v[40:43]
	v_mfma_f32_16x16x32_bf16 v[28:31], v[148:151], v[196:199], v[28:31]
	v_mfma_f32_16x16x32_bf16 v[24:27], v[156:159], v[196:199], v[24:27]
	v_mfma_f32_16x16x32_bf16 v[12:15], v[148:151], v[204:207], v[12:15]
	v_mfma_f32_16x16x32_bf16 v[8:11], v[156:159], v[204:207], v[8:11]
	s_barrier
	s_add_u32 s52, s22, 0x100000
	s_addc_u32 s53, s23, 0
	s_add_i32 s51, s54, s38
	s_mov_b32 m0, s51
	s_nop 0
	global_load_lds_dwordx4 v144, s[52:53]
	s_add_i32 m0, s51, 0x2000
	s_nop 0
	global_load_lds_dwordx4 v132, s[52:53]
	s_waitcnt vmcnt(6)
	s_barrier
; #define PG8_STAGE(bufoff, gbase, voff) do { _Pragma("unroll") for (int _i = 0; _i < 2; ++_i) \
;     __builtin_amdgcn_global_load_lds((const unsigned*)((const char*)(gbase) + (voff)[_i]), (LAS unsigned*)(lds + (bufoff) + ldsw + _i * 8192), 16, 0, 0); } while (0)
; #define PG8_LDA(dst, b, h) do { _Pragma("unroll") for (int m = 0; m < 4; ++m) _Pragma("unroll") for (int k = 0; k < 2; ++k) dst[m][k] = *(const LAS bf16x8*)(lds + PG8_SA(b, h) + aoff + m * 2048 + k * 1024); } while (0)
; #define PG8_LDB(dst, b, h) do { _Pragma("unroll") for (int n = 0; n < 2; ++n) _Pragma("unroll") for (int k = 0; k < 2; ++k) dst[n][k] = *(const LAS bf16x8*)(lds + PG8_SB(b, h) + boff + n * 2048 + k * 1024); } while (0)
; #define PG8_MMA(ai, bj, At, Bt) do { __builtin_amdgcn_s_setprio(1); _Pragma("unroll") for (int m = 0; m < 4; ++m) _Pragma("unroll") for (int n = 0; n < 2; ++n) _Pragma("unroll") for (int k = 0; k < 2; ++k) \
;     acc[ai][bj][m][n] = __builtin_amdgcn_mfma_f32_16x16x32_bf16(Bt[n][k], At[m][k], acc[ai][bj][m][n], 0, 0, 0); __builtin_amdgcn_s_setprio(0); } while (0)
; #define PG8_WAIT_V(n) asm volatile("s_waitcnt vmcnt(" #n ")" ::: "memory")
; #define PG8_WAIT_L(n) asm volatile("s_waitcnt lgkmcnt(" #n ")" ::: "memory")
; #define PG8_BAR __builtin_amdgcn_s_barrier()
; #define PG8_SCHED __builtin_amdgcn_sched_barrier(0)
; template <class Epi, class Sched>
; DI void gemm_phase(LAS unsigned char* lds, const Gemm g, const Sched& S, const Epi& E) {
;     ...
;       PG8_WAIT_V(6); PG8_BAR; PG8_MMA(1, 1, At, B1); PG8_BAR;
;       PG8_LDB(B0, 1, 0); PG8_SCHED; PG8_LDA(At, 1, 0); PG8_STAGE(PG8_SA(0, 1), a2 + hstep, voffA);
;       PG8_WAIT_L(8); PG8_BAR; PG8_WAIT_L(0); PG8_MMA(0, 0, At, B0); PG8_BAR; PG8_SCHED;
;       PG8_LDB(B1, 1, 1); PG8_STAGE(PG8_SB(1, 0), b3, voffB);
;       PG8_BAR; PG8_WAIT_L(0); PG8_MMA(0, 1, At, B1); PG8_BAR;
;       PG8_LDA(At, 1, 1); PG8_STAGE(PG8_SA(1, 0), a3, voffA);
;       PG8_BAR; PG8_WAIT_L(0); PG8_MMA(1, 0, At, B0); PG8_BAR; PG8_SCHED;
	v_mfma_f32_16x16x32_bf16 v[52:55], v[208:211], v[160:163], v[52:55]
	v_mfma_f32_16x16x32_bf16 v[48:51], v[216:219], v[160:163], v[48:51]
	v_mfma_f32_16x16x32_bf16 v[36:39], v[208:211], v[168:171], v[36:39]
	v_mfma_f32_16x16x32_bf16 v[32:35], v[216:219], v[168:171], v[32:35]
	v_mfma_f32_16x16x32_bf16 v[20:23], v[208:211], v[176:179], v[20:23]
	v_mfma_f32_16x16x32_bf16 v[16:19], v[216:219], v[176:179], v[16:19]
	v_mfma_f32_16x16x32_bf16 v[4:7], v[208:211], v[200:203], v[4:7]
	v_mfma_f32_16x16x32_bf16 v[0:3], v[216:219], v[200:203], v[0:3]
	v_mfma_f32_16x16x32_bf16 v[52:55], v[212:215], v[164:167], v[52:55]
	v_mfma_f32_16x16x32_bf16 v[48:51], v[220:223], v[164:167], v[48:51]
	v_mfma_f32_16x16x32_bf16 v[36:39], v[212:215], v[172:175], v[36:39]
	v_mfma_f32_16x16x32_bf16 v[32:35], v[220:223], v[172:175], v[32:35]
	v_mfma_f32_16x16x32_bf16 v[20:23], v[212:215], v[196:199], v[20:23]
	v_mfma_f32_16x16x32_bf16 v[16:19], v[220:223], v[196:199], v[16:19]
	v_mfma_f32_16x16x32_bf16 v[4:7], v[212:215], v[204:207], v[4:7]
	v_mfma_f32_16x16x32_bf16 v[0:3], v[220:223], v[204:207], v[0:3]
	s_add_i32 s51, 0, 0x18000
	s_barrier
	ds_read_b128 v[138:141], v226
	ds_read_b128 v[148:151], v226 offset:1024
	ds_read_b128 v[152:155], v226 offset:2048
	ds_read_b128 v[156:159], v226 offset:3072
	s_add_u32 s28, s28, 0x100000
	s_addc_u32 s29, s29, 0
	s_mov_b32 m0, s41
	ds_read_b128 v[160:163], v147 offset:32768
	ds_read_b128 v[164:167], v147 offset:33792
	ds_read_b128 v[168:171], v147 offset:34816
	ds_read_b128 v[172:175], v147 offset:35840
	ds_read_b128 v[176:179], v147 offset:36864
	ds_read_b128 v[196:199], v147 offset:37888
	ds_read_b128 v[200:203], v147 offset:38912
	ds_read_b128 v[204:207], v147 offset:39936
	global_load_lds_dwordx4 v128, s[28:29]
	s_mov_b32 m0, s42
	s_nop 0
	global_load_lds_dwordx4 v130, s[28:29]
	s_waitcnt lgkmcnt(8)
	s_barrier
	s_waitcnt lgkmcnt(0)
	v_mfma_f32_16x16x32_bf16 v[124:127], v[138:141], v[160:163], v[124:127]
	v_mfma_f32_16x16x32_bf16 v[120:123], v[152:155], v[160:163], v[120:123]
	v_mfma_f32_16x16x32_bf16 v[108:111], v[138:141], v[168:171], v[108:111]
	v_mfma_f32_16x16x32_bf16 v[104:107], v[152:155], v[168:171], v[104:107]
	v_mfma_f32_16x16x32_bf16 v[92:95], v[138:141], v[176:179], v[92:95]
	v_mfma_f32_16x16x32_bf16 v[88:91], v[152:155], v[176:179], v[88:91]
	v_mfma_f32_16x16x32_bf16 v[76:79], v[138:141], v[200:203], v[76:79]
	v_mfma_f32_16x16x32_bf16 v[72:75], v[152:155], v[200:203], v[72:75]
	v_mfma_f32_16x16x32_bf16 v[124:127], v[148:151], v[164:167], v[124:127]
	v_mfma_f32_16x16x32_bf16 v[120:123], v[156:159], v[164:167], v[120:123]
	v_mfma_f32_16x16x32_bf16 v[108:111], v[148:151], v[172:175], v[108:111]
	v_mfma_f32_16x16x32_bf16 v[104:107], v[156:159], v[172:175], v[104:107]
	v_mfma_f32_16x16x32_bf16 v[92:95], v[148:151], v[196:199], v[92:95]
	v_mfma_f32_16x16x32_bf16 v[88:91], v[156:159], v[196:199], v[88:91]
	v_mfma_f32_16x16x32_bf16 v[76:79], v[148:151], v[204:207], v[76:79]
	v_mfma_f32_16x16x32_bf16 v[72:75], v[156:159], v[204:207], v[72:75]
	s_barrier
	s_add_i32 s28, 0, 0x1c000
	s_add_i32 s29, s51, s38
	s_mov_b32 m0, s29
	ds_read_b128 v[208:211], v227
	ds_read_b128 v[212:215], v227 offset:1024
	ds_read_b128 v[216:219], v227 offset:2048
	ds_read_b128 v[220:223], v227 offset:3072
	global_load_lds_dwordx4 v144, vcc
	s_add_i32 m0, s29, 0x2000
	s_nop 0
	global_load_lds_dwordx4 v132, vcc
	s_barrier
	s_waitcnt lgkmcnt(0)
	v_mfma_f32_16x16x32_bf16 v[116:119], v[208:211], v[160:163], v[116:119]
	v_mfma_f32_16x16x32_bf16 v[112:115], v[216:219], v[160:163], v[112:115]
	v_mfma_f32_16x16x32_bf16 v[100:103], v[208:211], v[168:171], v[100:103]
	v_mfma_f32_16x16x32_bf16 v[96:99], v[216:219], v[168:171], v[96:99]
	v_mfma_f32_16x16x32_bf16 v[84:87], v[208:211], v[176:179], v[84:87]
	v_mfma_f32_16x16x32_bf16 v[80:83], v[216:219], v[176:179], v[80:83]
	v_mfma_f32_16x16x32_bf16 v[68:71], v[208:211], v[200:203], v[68:71]
	v_mfma_f32_16x16x32_bf16 v[64:67], v[216:219], v[200:203], v[64:67]
	v_mfma_f32_16x16x32_bf16 v[116:119], v[212:215], v[164:167], v[116:119]
	v_mfma_f32_16x16x32_bf16 v[112:115], v[220:223], v[164:167], v[112:115]
	v_mfma_f32_16x16x32_bf16 v[100:103], v[212:215], v[172:175], v[100:103]
	v_mfma_f32_16x16x32_bf16 v[96:99], v[220:223], v[172:175], v[96:99]
	v_mfma_f32_16x16x32_bf16 v[84:87], v[212:215], v[196:199], v[84:87]
	v_mfma_f32_16x16x32_bf16 v[80:83], v[220:223], v[196:199], v[80:83]
	v_mfma_f32_16x16x32_bf16 v[68:71], v[212:215], v[204:207], v[68:71]
	v_mfma_f32_16x16x32_bf16 v[64:67], v[220:223], v[204:207], v[64:67]
	s_mov_b32 m0, s46
	s_barrier
	ds_read_b128 v[160:163], v147 offset:49152
	ds_read_b128 v[164:167], v147 offset:50176
	ds_read_b128 v[168:171], v147 offset:51200
	ds_read_b128 v[172:175], v147 offset:52224
	ds_read_b128 v[176:179], v147 offset:53248
	ds_read_b128 v[196:199], v147 offset:54272
	ds_read_b128 v[200:203], v147 offset:55296
	ds_read_b128 v[204:207], v147 offset:56320
	global_load_lds_dwordx4 v128, s[100:101]
	s_mov_b32 m0, s47
	s_nop 0
	global_load_lds_dwordx4 v130, s[100:101]
	s_barrier
; DI float bf2f(unsigned v) { return __uint_as_float(v << 16); }
; template <class Epi, class Sched>
; DI void gemm_phase(LAS unsigned char* lds, const Gemm g, const Sched& S, const Epi& E) {
;     ...
;       PG8_BAR; PG8_WAIT_L(0); PG8_MMA(1, 0, At, B0); PG8_BAR; PG8_SCHED;
;       PG8_STAGE(PG8_SB(1, 1), b3 + hstep, voffB);
;       PG8_WAIT_V(6); PG8_BAR; PG8_MMA(1, 1, At, B1); PG8_BAR;
;     }
;   DI void operator()(const f32x4 (&acc)[2][2][4][2], const pg8::Unit& u, int wr, int wc, int fr_, int fq_) const {
;     ...
;               if (n == 0) {
;                 const int f8 = u.pn * 256 + bj * 128 + wc * 32 + 8 * fq;
;                 const f32x4 v1 = acc[ai][bj][m][1];
;                 f32x4 r0, r1;
;                 if (rsrc) {
;                   r0 = *(const f32x4*)(rsrc + (size_t)token * 1024 + f8); r1 = *(const f32x4*)(rsrc + (size_t)token * 1024 + f8 + 4);
;                 } else {
;                   const u32x4 xu = *(const u32x4*)(xr + (size_t)token * 1024 + f8);
;                   r0 = (f32x4){bf2f(xu.x & 0xffffu), bf2f(xu.x >> 16), bf2f(xu.y & 0xffffu), bf2f(xu.y >> 16)};
;                   r1 = (f32x4){bf2f(xu.z & 0xffffu), bf2f(xu.z >> 16), bf2f(xu.w & 0xffffu), bf2f(xu.w >> 16)};
;                 }
;                 r0 += v; r1 += v1;
;                 st_bf8(xr + (size_t)token * 1024 + f8, r0, r1, 1.f);
;                 ssq += r0[0] * r0[0] + r0[1] * r0[1] + r0[2] * r0[2] + r0[3] * r0[3] + r1[0] * r1[0] + r1[1] * r1[1] + r1[2] * r1[2] + r1[3] * r1[3];
;               }
;             } else {
;               if (n == 0) {
;                 const f32x4 v1 = acc[ai][bj][m][1];
;                 u32x4 o4;
;                 { const float t0 = fmaxf(v[0], 0.f) * rinv, t1 = fmaxf(v[1], 0.f) * rinv, t2 = fmaxf(v[2], 0.f) * rinv, t3 = fmaxf(v[3], 0.f) * rinv;
;                   o4.x = pack2(t0 * t0, t1 * t1); o4.y = pack2(t2 * t2, t3 * t3); }
;                 { const float t0 = fmaxf(v1[0], 0.f) * rinv, t1 = fmaxf(v1[1], 0.f) * rinv, t2 = fmaxf(v1[2], 0.f) * rinv, t3 = fmaxf(v1[3], 0.f) * rinv;
;                   o4.z = pack2(t0 * t0, t1 * t1); o4.w = pack2(t2 * t2, t3 * t3); }
;                 *(u32x4*)((u16*)big + (size_t)token * 4096 + u.pn * 256 + bj * 128 + wc * 32 + 8 * fq) = o4;
;               }
;             }
;           }
;         if (EPI == EPI_RESID) {
;           ssq += shx(ssq, 16, t_ & 63);
;           ssq += shx(ssq, 32, t_ & 63);
	s_waitcnt lgkmcnt(0)
	v_mfma_f32_16x16x32_bf16 v[60:63], v[138:141], v[160:163], v[60:63]
	v_mfma_f32_16x16x32_bf16 v[56:59], v[152:155], v[160:163], v[56:59]
	v_mfma_f32_16x16x32_bf16 v[44:47], v[138:141], v[168:171], v[44:47]
	v_mfma_f32_16x16x32_bf16 v[40:43], v[152:155], v[168:171], v[40:43]
	v_mfma_f32_16x16x32_bf16 v[28:31], v[138:141], v[176:179], v[28:31]
	v_mfma_f32_16x16x32_bf16 v[24:27], v[152:155], v[176:179], v[24:27]
	v_mfma_f32_16x16x32_bf16 v[12:15], v[138:141], v[200:203], v[12:15]
	v_mfma_f32_16x16x32_bf16 v[8:11], v[152:155], v[200:203], v[8:11]
	v_mfma_f32_16x16x32_bf16 v[60:63], v[148:151], v[164:167], v[60:63]
	v_mfma_f32_16x16x32_bf16 v[56:59], v[156:159], v[164:167], v[56:59]
	v_mfma_f32_16x16x32_bf16 v[44:47], v[148:151], v[172:175], v[44:47]
	v_mfma_f32_16x16x32_bf16 v[40:43], v[156:159], v[172:175], v[40:43]
	v_mfma_f32_16x16x32_bf16 v[28:31], v[148:151], v[196:199], v[28:31]
	v_mfma_f32_16x16x32_bf16 v[24:27], v[156:159], v[196:199], v[24:27]
	v_mfma_f32_16x16x32_bf16 v[12:15], v[148:151], v[204:207], v[12:15]
	v_mfma_f32_16x16x32_bf16 v[8:11], v[156:159], v[204:207], v[8:11]
	s_barrier
	s_add_u32 s22, s22, 0x100080
	s_addc_u32 s23, s23, 0
	s_add_i32 s28, s28, s38
	s_mov_b32 m0, s28
	s_nop 0
	global_load_lds_dwordx4 v144, s[22:23]
	s_add_i32 m0, s28, 0x2000
	s_nop 0
	global_load_lds_dwordx4 v132, s[22:23]
	s_waitcnt vmcnt(6)
	s_barrier
	v_mfma_f32_16x16x32_bf16 v[52:55], v[208:211], v[160:163], v[52:55]
	v_mfma_f32_16x16x32_bf16 v[48:51], v[216:219], v[160:163], v[48:51]
	v_mfma_f32_16x16x32_bf16 v[36:39], v[208:211], v[168:171], v[36:39]
	v_mfma_f32_16x16x32_bf16 v[32:35], v[216:219], v[168:171], v[32:35]
	v_mfma_f32_16x16x32_bf16 v[20:23], v[208:211], v[176:179], v[20:23]
	v_mfma_f32_16x16x32_bf16 v[16:19], v[216:219], v[176:179], v[16:19]
	v_mfma_f32_16x16x32_bf16 v[4:7], v[208:211], v[200:203], v[4:7]
	v_mfma_f32_16x16x32_bf16 v[0:3], v[216:219], v[200:203], v[0:3]
	v_mfma_f32_16x16x32_bf16 v[52:55], v[212:215], v[164:167], v[52:55]
	v_mfma_f32_16x16x32_bf16 v[48:51], v[220:223], v[164:167], v[48:51]
	v_mfma_f32_16x16x32_bf16 v[36:39], v[212:215], v[172:175], v[36:39]
	v_mfma_f32_16x16x32_bf16 v[32:35], v[220:223], v[172:175], v[32:35]
	v_mfma_f32_16x16x32_bf16 v[20:23], v[212:215], v[196:199], v[20:23]
	v_mfma_f32_16x16x32_bf16 v[16:19], v[220:223], v[196:199], v[16:19]
	v_mfma_f32_16x16x32_bf16 v[4:7], v[212:215], v[204:207], v[4:7]
	v_mfma_f32_16x16x32_bf16 v[0:3], v[220:223], v[204:207], v[0:3]
	s_add_i32 s50, s50, 2
	s_add_u32 s20, s20, 0x100
	s_addc_u32 s21, s21, 0
	s_add_u32 s24, s24, 0x100
	s_addc_u32 s49, s49, 0
	s_cmp_gt_u32 s50, 61
	s_barrier
	s_cbranch_scc0 .LBB0_1905
	s_lshl_b32 s7, s18, 8
	v_mov_b32_e32 v139, v182
	s_add_i32 s7, s7, s44
	s_nop 0
	v_and_or_b32 v140, v139, 15, s7
	s_lshl_b32 s7, s16, 8
	v_bfe_u32 v141, v139, 4, 2
	s_or_b32 s7, s7, s45
	v_lshl_or_b32 v138, v141, 3, s7
	v_cmp_eq_u32_e32 vcc, 0, v141
	v_ashrrev_i32_e32 v141, 31, v140
	v_lshlrev_b32_e32 v139, 2, v139
	s_movk_i32 s7, 0x80
	v_lshlrev_b64 v[142:143], 11, v[140:141]
	v_bitop3_b32 v149, v139, 64, v190 bitop3:0x6c
	v_bitop3_b32 v148, v139, s7, v190 bitop3:0x6c
	v_ashrrev_i32_e32 v139, 31, v138
	v_lshl_add_u64 v[142:143], s[4:5], 0, v[142:143]
	v_lshl_add_u64 v[142:143], v[138:139], 1, v[142:143]
	global_load_dwordx4 v[150:153], v[142:143], off
	s_lshl_b32 s16, s16, 2
	s_ashr_i32 s17, s16, 31
	s_waitcnt vmcnt(0)
	v_lshlrev_b32_e32 v154, 16, v150
	v_and_b32_e32 v155, 0xffff0000, v150
	v_lshlrev_b32_e32 v150, 16, v151
	v_and_b32_e32 v151, 0xffff0000, v151
	v_lshlrev_b32_e32 v156, 16, v152
	v_and_b32_e32 v157, 0xffff0000, v152
	v_lshlrev_b32_e32 v152, 16, v153
	v_and_b32_e32 v153, 0xffff0000, v153
	v_pk_add_f32 v[126:127], v[126:127], v[150:151]
	v_pk_add_f32 v[124:125], v[124:125], v[154:155]
	v_pk_add_f32 v[150:151], v[122:123], v[152:153]
	v_pk_add_f32 v[152:153], v[120:121], v[156:157]
	v_cvt_pk_bf16_f32 v120, v124, v125
	v_cvt_pk_bf16_f32 v121, v126, v127
	v_cvt_pk_bf16_f32 v122, v152, v153
	v_cvt_pk_bf16_f32 v123, v150, v151
	global_store_dwordx4 v[142:143], v[120:123], off
	global_load_dwordx4 v[120:123], v[142:143], off offset:256
	v_mul_f32_e32 v154, v125, v125
	v_fmac_f32_e32 v154, v124, v124
	v_fmac_f32_e32 v154, v126, v126
	v_fmac_f32_e32 v154, v127, v127
	v_fmac_f32_e32 v154, v152, v152
	v_fmac_f32_e32 v154, v153, v153
	v_fmac_f32_e32 v154, v150, v150
	v_fmac_f32_e32 v154, v151, v151
	s_waitcnt vmcnt(0)
	v_lshlrev_b32_e32 v124, 16, v120
	v_and_b32_e32 v125, 0xffff0000, v120
	v_lshlrev_b32_e32 v120, 16, v121
	v_and_b32_e32 v121, 0xffff0000, v121
	v_lshlrev_b32_e32 v126, 16, v122
	v_and_b32_e32 v127, 0xffff0000, v122
	v_lshlrev_b32_e32 v122, 16, v123
	v_and_b32_e32 v123, 0xffff0000, v123
	v_pk_add_f32 v[118:119], v[118:119], v[120:121]
	v_pk_add_f32 v[116:117], v[116:117], v[124:125]
	v_pk_add_f32 v[120:121], v[114:115], v[122:123]
	v_pk_add_f32 v[122:123], v[112:113], v[126:127]
	v_cvt_pk_bf16_f32 v112, v116, v117
	v_cvt_pk_bf16_f32 v113, v118, v119
	v_cvt_pk_bf16_f32 v114, v122, v123
	v_cvt_pk_bf16_f32 v115, v120, v121
	global_store_dwordx4 v[142:143], v[112:115], off offset:256
	s_nop 1
	v_mul_f32_e32 v112, v117, v117
	v_fmac_f32_e32 v112, v116, v116
	v_fmac_f32_e32 v112, v118, v118
	v_fmac_f32_e32 v112, v119, v119
	v_fmac_f32_e32 v112, v122, v122
	v_fmac_f32_e32 v112, v123, v123
	v_fmac_f32_e32 v112, v120, v120
	v_fmac_f32_e32 v112, v121, v121
	v_add_f32_e32 v112, v154, v112
	ds_bpermute_b32 v113, v149, v112
	s_waitcnt lgkmcnt(0)
	v_add_f32_e32 v112, v112, v113
	ds_bpermute_b32 v113, v148, v112
	s_and_saveexec_b64 s[18:19], vcc
	s_cbranch_execz .LBB0_1908
	s_waitcnt lgkmcnt(0)
	v_add_f32_e32 v114, v112, v113
	v_lshlrev_b64 v[112:113], 6, v[140:141]
	v_lshl_add_u64 v[112:113], s[2:3], 0, v[112:113]
	v_lshl_add_u64 v[112:113], s[16:17], 2, v[112:113]
	s_lshl_b32 s24, s43, 2
	v_lshl_add_u64 v[112:113], v[112:113], 0, s[24:25]
	global_store_dword v[112:113], v114, off
